# v079: v078 + 41 more epilogue row reductions (k-norm / q-norm / per-head norms) via v_permlane16/32_swap instead of LDS round trips
# baseline (speedup 1.0000x reference)
.LBB0_342:
	s_lshl_b32 s38, s38, 6
	s_andn2_b64 vcc, exec, s[6:7]
	s_ashr_i32 s39, s38, 31
	s_cbranch_vccnz .LBB0_344
	v_mov_b32_e32 v152, v127
	v_mov_b32_e32 v153, v119
	v_mov_b32_e32 v150, v126
	v_mov_b32_e32 v151, v118
	v_pk_mul_f32 v[152:153], v[152:153], v[152:153]
	v_mov_b32_e32 v154, v129
	v_mov_b32_e32 v155, v121
	v_pk_fma_f32 v[150:151], v[150:151], v[150:151], v[152:153]
	v_mov_b32_e32 v152, v128
	v_mov_b32_e32 v153, v120
	v_pk_mul_f32 v[154:155], v[154:155], v[154:155]
	v_mov_b32_e32 v156, v125
	v_pk_fma_f32 v[152:153], v[152:153], v[152:153], v[154:155]
	v_mov_b32_e32 v154, v123
	v_mov_b32_e32 v155, v115
	v_pk_add_f32 v[150:151], v[150:151], v[152:153]
	v_mov_b32_e32 v152, v122
	v_mov_b32_e32 v153, v114
	v_pk_mul_f32 v[154:155], v[154:155], v[154:155]
	v_mov_b32_e32 v157, v117
	v_pk_fma_f32 v[152:153], v[152:153], v[152:153], v[154:155]
	v_mov_b32_e32 v154, v124
	v_mov_b32_e32 v155, v116
	v_pk_mul_f32 v[156:157], v[156:157], v[156:157]
	v_and_b32_e32 v141, 64, v148
	v_pk_fma_f32 v[154:155], v[154:155], v[154:155], v[156:157]
	v_add_u32_e32 v141, 64, v141
	v_pk_add_f32 v[152:153], v[152:153], v[154:155]
	s_lshl_b64 s[6:7], s[38:39], 2
	v_pk_add_f32 v[150:151], v[150:151], v[152:153]
	s_add_u32 s6, s12, s6
	v_add_f32_e32 v137, v150, v151
	v_mov_b32_e32 v139, v137
	s_nop 1
	v_permlane16_swap_b32 v139, v137
	s_addc_u32 s7, s13, s7
	s_mov_b64 s[42:43], 0x1a923c00
	s_waitcnt lgkmcnt(0)
	v_add_f32_e32 v137, v137, v139
	v_xor_b32_e32 v139, 32, v148
	v_cmp_lt_i32_e32 vcc, v139, v141
	s_nop 1
	v_cndmask_b32_e32 v139, v148, v139, vcc
	v_lshlrev_b32_e32 v139, 2, v139
	v_mov_b32_e32 v139, v137
	s_nop 1
	v_permlane32_swap_b32 v139, v137
	s_waitcnt lgkmcnt(0)
	v_add_f32_e32 v137, v137, v139
	v_fmamk_f32 v137, v137, 0x3c800000, v147
	v_cmp_gt_f32_e32 vcc, s64, v137
	v_mul_f32_e32 v139, 0x4b800000, v137
	s_nop 0
	v_cndmask_b32_e32 v137, v137, v139, vcc
	v_rsq_f32_e32 v137, v137
	s_nop 0
	v_mul_f32_e32 v139, 0x45800000, v137
	v_cndmask_b32_e32 v154, v137, v139, vcc
	v_pk_mul_f32 v[156:157], v[126:127], v[154:155] op_sel_hi:[1,0]
	v_pk_mul_f32 v[158:159], v[128:129], v[154:155] op_sel_hi:[1,0]
	global_load_dwordx4 v[126:129], v134, s[6:7] offset:16
	global_load_dwordx4 v[150:153], v134, s[6:7]
	v_pk_mul_f32 v[122:123], v[122:123], v[154:155] op_sel_hi:[1,0]
	v_pk_mul_f32 v[124:125], v[124:125], v[154:155] op_sel_hi:[1,0]
	v_mov_b32_e32 v139, v135
	v_pk_mul_f32 v[116:117], v[116:117], v[154:155] op_sel_hi:[1,0]
	v_pk_mul_f32 v[114:115], v[114:115], v[154:155] op_sel_hi:[1,0]
	v_mov_b32_e32 v137, v135
	s_waitcnt vmcnt(0)
	v_pk_mul_f32 v[122:123], v[126:127], v[122:123]
	v_lshl_add_u64 v[126:127], v[142:143], 2, s[14:15]
	v_pk_mul_f32 v[152:153], v[152:153], v[158:159]
	v_pk_mul_f32 v[150:151], v[150:151], v[156:157]
	v_pk_mul_f32 v[124:125], v[128:129], v[124:125]
	v_lshl_add_u64 v[156:157], v[126:127], 0, v[134:135]
	v_lshl_add_u64 v[126:127], v[142:143], 1, s[18:19]
	v_lshl_add_u64 v[158:159], v[126:127], 0, v[138:139]
	v_cvt_pk_bf16_f32 v126, v150, v151
	v_cvt_pk_bf16_f32 v127, v152, v153
	v_cvt_pk_bf16_f32 v128, v122, v123
	v_cvt_pk_bf16_f32 v129, v124, v125
	global_store_dwordx4 v[156:157], v[150:153], off
	global_store_dwordx4 v[156:157], v[122:125], off offset:16
	global_store_dwordx4 v[158:159], v[126:129], off
	s_nop 1
	v_pk_mul_f32 v[126:127], v[120:121], v[154:155] op_sel_hi:[1,0]
	v_pk_mul_f32 v[128:129], v[118:119], v[154:155] op_sel_hi:[1,0]
	global_load_dwordx4 v[122:125], v134, s[6:7] offset:144
	global_load_dwordx4 v[118:121], v134, s[6:7] offset:128
	s_mov_b64 s[6:7], 0x56cc000
	s_waitcnt vmcnt(1)
	v_pk_mul_f32 v[114:115], v[122:123], v[114:115]
	s_waitcnt vmcnt(0)
	v_pk_mul_f32 v[118:119], v[118:119], v[128:129]
	v_pk_mul_f32 v[120:121], v[120:121], v[126:127]
	v_pk_mul_f32 v[116:117], v[124:125], v[116:117]
	global_store_dwordx4 v[156:157], v[118:121], off offset:128
	s_branch .LBB0_345

.LBB0_516:
	s_andn2_b64 vcc, exec, s[18:19]
	s_cbranch_vccnz .LBB0_518
	v_lshlrev_b64 v[132:133], 9, v[142:143]
	v_lshl_add_u64 v[132:133], s[30:31], 0, v[132:133]
	v_pk_mul_f32 v[162:163], v[130:131], v[146:147] op_sel_hi:[1,0]
	v_pk_mul_f32 v[164:165], v[128:129], v[146:147] op_sel_hi:[1,0]
	v_lshl_add_u64 v[166:167], s[68:69], 1, v[132:133]
	v_pk_mul_f32 v[132:133], v[162:163], v[162:163]
	v_pk_mul_f32 v[134:135], v[164:165], v[164:165]
	v_pk_mul_f32 v[158:159], v[126:127], v[146:147] op_sel_hi:[1,0]
	v_pk_mov_b32 v[148:149], v[134:135], v[132:133] op_sel:[1,0]
	v_mov_b32_e32 v135, v133
	v_pk_add_f32 v[132:133], v[148:149], v[134:135]
	v_pk_mul_f32 v[160:161], v[124:125], v[146:147] op_sel_hi:[1,0]
	v_pk_add_f32 v[132:133], v[132:133], v[132:133] op_sel_hi:[0,1]
	v_pk_mul_f32 v[134:135], v[158:159], v[158:159]
	v_pk_mul_f32 v[148:149], v[160:161], v[160:161]
	v_pk_mul_f32 v[154:155], v[120:121], v[146:147] op_sel_hi:[1,0]
	v_pk_mov_b32 v[150:151], v[148:149], v[134:135] op_sel:[1,0]
	v_mov_b32_e32 v149, v135
	v_pk_mul_f32 v[152:153], v[122:123], v[146:147] op_sel_hi:[1,0]
	v_mul_f32_e32 v132, v154, v154
	v_pk_add_f32 v[134:135], v[150:151], v[148:149]
	v_pk_fma_f32 v[174:175], v[154:155], v[154:155], v[132:133] op_sel_hi:[1,1,0]
	v_mul_f32_e32 v132, v152, v152
	v_pk_add_f32 v[134:135], v[134:135], v[134:135] op_sel_hi:[0,1]
	v_pk_fma_f32 v[176:177], v[152:153], v[152:153], v[132:133] op_sel_hi:[1,1,0]
	v_pk_mul_f32 v[148:149], v[118:119], v[146:147] op_sel_hi:[1,0]
	v_pk_mul_f32 v[150:151], v[116:117], v[146:147] op_sel_hi:[1,0]
	v_mul_f32_e32 v132, v148, v148
	v_mul_f32_e32 v174, v150, v150
	v_mul_f32_e32 v176, v151, v151
	v_mul_f32_e32 v134, v149, v149
	v_pk_add_f32 v[174:175], v[174:175], v[176:177]
	v_pk_add_f32 v[132:133], v[132:133], v[134:135]
	v_and_b32_e32 v134, 64, v236
	v_pk_add_f32 v[132:133], v[174:175], v[132:133]
	v_add_u32_e32 v134, 64, v134
	v_add_f32_e32 v132, v132, v133
	v_mov_b32_e32 v133, v132
	s_nop 1
	v_permlane16_swap_b32 v133, v132
	v_lshlrev_b32_e32 v145, 2, v157
	v_lshlrev_b32_e32 v178, 1, v157
	v_mov_b32_e32 v179, v2
	v_lshl_add_u64 v[166:167], v[166:167], 0, v[178:179]
	s_waitcnt lgkmcnt(0)
	v_add_f32_e32 v132, v132, v133
	v_xor_b32_e32 v133, 32, v236
	v_cmp_lt_i32_e32 vcc, v133, v134
	s_nop 1
	v_cndmask_b32_e32 v133, v236, v133, vcc
	v_lshlrev_b32_e32 v133, 2, v133
	v_mov_b32_e32 v133, v132
	s_nop 1
	v_permlane32_swap_b32 v133, v132
	s_waitcnt lgkmcnt(0)
	v_add_f32_e32 v132, v132, v133
	v_fmamk_f32 v132, v132, 0x3c800000, v231
	v_cmp_gt_f32_e32 vcc, s11, v132
	v_mul_f32_e32 v133, 0x4b800000, v132
	s_nop 0
	v_cndmask_b32_e32 v132, v132, v133, vcc
	v_rsq_f32_e32 v132, v132
	s_nop 0
	v_mul_f32_e32 v133, 0x45800000, v132
	v_cndmask_b32_e32 v132, v132, v133, vcc
	v_mul_f32_e32 v156, 0x3e38aa3b, v132
	global_load_dwordx4 v[132:135], v145, s[36:37] offset:16
	global_load_dwordx4 v[174:177], v145, s[36:37]
	v_pk_mul_f32 v[164:165], v[164:165], v[156:157] op_sel_hi:[1,0]
	v_pk_mul_f32 v[162:163], v[162:163], v[156:157] op_sel_hi:[1,0]
	v_pk_mul_f32 v[160:161], v[160:161], v[156:157] op_sel_hi:[1,0]
	v_pk_mul_f32 v[158:159], v[158:159], v[156:157] op_sel_hi:[1,0]
	v_pk_mul_f32 v[154:155], v[154:155], v[156:157] op_sel_hi:[1,0]
	v_pk_mul_f32 v[152:153], v[152:153], v[156:157] op_sel_hi:[1,0]
	v_pk_mul_f32 v[150:151], v[150:151], v[156:157] op_sel_hi:[1,0]
	v_pk_mul_f32 v[148:149], v[148:149], v[156:157] op_sel_hi:[1,0]
	s_waitcnt vmcnt(1)
	v_pk_mul_f32 v[158:159], v[134:135], v[158:159]
	s_waitcnt vmcnt(0)
	v_pk_mul_f32 v[162:163], v[176:177], v[162:163]
	v_pk_mul_f32 v[164:165], v[174:175], v[164:165]
	v_pk_mul_f32 v[134:135], v[132:133], v[160:161]
	v_cvt_pk_bf16_f32 v132, v164, v165
	v_cvt_pk_bf16_f32 v133, v162, v163
	v_cvt_pk_bf16_f32 v134, v134, v135
	v_cvt_pk_bf16_f32 v135, v158, v159
	global_store_dwordx4 v[166:167], v[132:135], off offset:-768
	global_load_dwordx4 v[132:135], v145, s[36:37] offset:144
	s_nop 0
	global_load_dwordx4 v[158:161], v145, s[36:37] offset:128
	s_waitcnt vmcnt(1)
	v_pk_mul_f32 v[148:149], v[134:135], v[148:149]
	s_waitcnt vmcnt(0)
	v_pk_mul_f32 v[152:153], v[160:161], v[152:153]
	v_pk_mul_f32 v[154:155], v[158:159], v[154:155]
	v_pk_mul_f32 v[134:135], v[132:133], v[150:151]
	v_cvt_pk_bf16_f32 v132, v154, v155
	v_cvt_pk_bf16_f32 v133, v152, v153
	v_cvt_pk_bf16_f32 v134, v134, v135
	v_cvt_pk_bf16_f32 v135, v148, v149
	global_store_dwordx4 v[166:167], v[132:135], off offset:-704

.LBB0_519:
	s_nop 0
	v_or_b32_e32 v132, s68, v157
	s_andn2_b64 vcc, exec, s[18:19]
	v_ashrrev_i32_e32 v133, 31, v132
	s_cbranch_vccnz .LBB0_523
	v_pk_mul_f32 v[130:131], v[130:131], v[146:147] op_sel_hi:[1,0]
	v_pk_mul_f32 v[128:129], v[128:129], v[146:147] op_sel_hi:[1,0]
	v_pk_mul_f32 v[134:135], v[126:127], v[146:147] op_sel_hi:[1,0]
	v_pk_mul_f32 v[126:127], v[124:125], v[146:147] op_sel_hi:[1,0]
	v_mul_f32_e32 v124, v129, v129
	v_mul_f32_e32 v125, v131, v131
	v_fmac_f32_e32 v124, v128, v128
	v_fmac_f32_e32 v125, v130, v130
	v_add_f32_e32 v124, v124, v125
	v_mul_f32_e32 v125, v127, v127
	v_mul_f32_e32 v145, v135, v135
	v_fmac_f32_e32 v125, v126, v126
	v_fmac_f32_e32 v145, v134, v134
	v_add_f32_e32 v125, v125, v145
	v_add_f32_e32 v145, v124, v125
	v_mov_b64_e32 v[124:125], s[26:27]
	s_movk_i32 s18, 0x300
	v_mad_i64_i32 v[124:125], s[18:19], v142, s18, v[124:125]
	v_pk_mul_f32 v[122:123], v[122:123], v[146:147] op_sel_hi:[1,0]
	v_pk_mul_f32 v[120:121], v[120:121], v[146:147] op_sel_hi:[1,0]
	v_lshl_add_u64 v[148:149], v[132:133], 1, v[124:125]
	v_cvt_pk_bf16_f32 v125, v130, v131
	v_pk_mul_f32 v[130:131], v[116:117], v[146:147] op_sel_hi:[1,0]
	v_mul_f32_e32 v116, v121, v121
	v_mul_f32_e32 v117, v123, v123
	v_cvt_pk_bf16_f32 v124, v128, v129
	v_pk_mul_f32 v[128:129], v[118:119], v[146:147] op_sel_hi:[1,0]
	v_fmac_f32_e32 v116, v120, v120
	v_fmac_f32_e32 v117, v122, v122
	v_add_f32_e32 v116, v116, v117
	v_mul_f32_e32 v117, v131, v131
	v_mul_f32_e32 v118, v129, v129
	v_fmac_f32_e32 v117, v130, v130
	v_fmac_f32_e32 v118, v128, v128
	v_add_f32_e32 v117, v117, v118
	v_add_f32_e32 v116, v116, v117
	v_add_f32_e32 v116, v145, v116
	v_mov_b32_e32 v117, v116
	s_nop 1
	v_permlane16_swap_b32 v117, v116
	v_and_b32_e32 v119, 64, v236
	v_add_u32_e32 v119, 64, v119
	v_cvt_pk_bf16_f32 v126, v126, v127
	v_cvt_pk_bf16_f32 v127, v134, v135
	s_waitcnt lgkmcnt(0)
	v_add_f32_e32 v116, v116, v117
	v_xor_b32_e32 v117, 32, v236
	v_cmp_lt_i32_e32 vcc, v117, v119
	v_cvt_pk_bf16_f32 v118, v120, v121
	v_cvt_pk_bf16_f32 v119, v122, v123
	v_cndmask_b32_e32 v117, v236, v117, vcc
	v_lshlrev_b32_e32 v117, 2, v117
	v_mov_b32_e32 v117, v116
	s_nop 1
	v_permlane32_swap_b32 v117, v116
	v_cvt_pk_bf16_f32 v120, v130, v131
	v_cvt_pk_bf16_f32 v121, v128, v129
	global_store_dwordx4 v[148:149], v[124:127], off
	global_store_dwordx4 v[148:149], v[118:121], off offset:64
	s_and_saveexec_b64 s[18:19], s[16:17]
	s_cbranch_execz .LBB0_522
	s_waitcnt lgkmcnt(0)
	v_add_f32_e32 v118, v116, v117
	v_lshl_add_u64 v[116:117], v[142:143], 2, s[28:29]
	global_atomic_add_f32 v[116:117], v118, off

.LBB0_533:
	s_andn2_b64 vcc, exec, s[0:1]
	s_cbranch_vccnz .LBB0_535
	v_lshlrev_b64 v[116:117], 9, v[122:123]
	v_lshl_add_u64 v[116:117], s[30:31], 0, v[116:117]
	v_pk_mul_f32 v[150:151], v[114:115], v[120:121] op_sel_hi:[1,0]
	v_pk_mul_f32 v[152:153], v[112:113], v[120:121] op_sel_hi:[1,0]
	v_lshl_add_u64 v[154:155], s[68:69], 1, v[116:117]
	v_pk_mul_f32 v[116:117], v[150:151], v[150:151]
	v_pk_mul_f32 v[118:119], v[152:153], v[152:153]
	v_pk_mul_f32 v[146:147], v[110:111], v[120:121] op_sel_hi:[1,0]
	v_pk_mov_b32 v[124:125], v[118:119], v[116:117] op_sel:[1,0]
	v_mov_b32_e32 v119, v117
	v_pk_add_f32 v[116:117], v[124:125], v[118:119]
	v_pk_mul_f32 v[148:149], v[108:109], v[120:121] op_sel_hi:[1,0]
	v_pk_add_f32 v[116:117], v[116:117], v[116:117] op_sel_hi:[0,1]
	v_pk_mul_f32 v[118:119], v[146:147], v[146:147]
	v_pk_mul_f32 v[124:125], v[148:149], v[148:149]
	v_pk_mul_f32 v[130:131], v[104:105], v[120:121] op_sel_hi:[1,0]
	v_pk_mov_b32 v[126:127], v[124:125], v[118:119] op_sel:[1,0]
	v_mov_b32_e32 v125, v119
	v_pk_mul_f32 v[128:129], v[106:107], v[120:121] op_sel_hi:[1,0]
	v_mul_f32_e32 v116, v130, v130
	v_pk_add_f32 v[118:119], v[126:127], v[124:125]
	v_pk_fma_f32 v[134:135], v[130:131], v[130:131], v[116:117] op_sel_hi:[1,1,0]
	v_mul_f32_e32 v116, v128, v128
	v_pk_add_f32 v[118:119], v[118:119], v[118:119] op_sel_hi:[0,1]
	v_pk_fma_f32 v[158:159], v[128:129], v[128:129], v[116:117] op_sel_hi:[1,1,0]
	v_pk_mul_f32 v[124:125], v[102:103], v[120:121] op_sel_hi:[1,0]
	v_pk_mul_f32 v[126:127], v[100:101], v[120:121] op_sel_hi:[1,0]
	v_mul_f32_e32 v116, v124, v124
	v_mul_f32_e32 v134, v126, v126
	v_mul_f32_e32 v158, v127, v127
	v_mul_f32_e32 v118, v125, v125
	v_pk_add_f32 v[134:135], v[134:135], v[158:159]
	v_pk_add_f32 v[116:117], v[116:117], v[118:119]
	v_and_b32_e32 v118, 64, v236
	v_pk_add_f32 v[116:117], v[134:135], v[116:117]
	v_add_u32_e32 v118, 64, v118
	v_add_f32_e32 v116, v116, v117
	v_mov_b32_e32 v117, v116
	s_nop 1
	v_permlane16_swap_b32 v117, v116
	v_lshlrev_b32_e32 v121, 2, v157
	v_lshlrev_b32_e32 v162, 1, v157
	v_mov_b32_e32 v163, v2
	v_lshl_add_u64 v[154:155], v[154:155], 0, v[162:163]
	s_waitcnt lgkmcnt(0)
	v_add_f32_e32 v116, v116, v117
	v_xor_b32_e32 v117, 32, v236
	v_cmp_lt_i32_e32 vcc, v117, v118
	s_nop 1
	v_cndmask_b32_e32 v117, v236, v117, vcc
	v_lshlrev_b32_e32 v117, 2, v117
	v_mov_b32_e32 v117, v116
	s_nop 1
	v_permlane32_swap_b32 v117, v116
	s_waitcnt lgkmcnt(0)
	v_add_f32_e32 v116, v116, v117
	v_fmamk_f32 v116, v116, 0x3c800000, v231
	v_cmp_gt_f32_e32 vcc, s11, v116
	v_mul_f32_e32 v117, 0x4b800000, v116
	s_nop 0
	v_cndmask_b32_e32 v116, v116, v117, vcc
	v_rsq_f32_e32 v116, v116
	s_nop 0
	v_mul_f32_e32 v117, 0x45800000, v116
	v_cndmask_b32_e32 v116, v116, v117, vcc
	v_mul_f32_e32 v134, 0x3e38aa3b, v116
	global_load_dwordx4 v[116:119], v121, s[36:37] offset:16
	global_load_dwordx4 v[158:161], v121, s[36:37]
	v_pk_mul_f32 v[152:153], v[152:153], v[134:135] op_sel_hi:[1,0]
	v_pk_mul_f32 v[150:151], v[150:151], v[134:135] op_sel_hi:[1,0]
	v_pk_mul_f32 v[148:149], v[148:149], v[134:135] op_sel_hi:[1,0]
	v_pk_mul_f32 v[146:147], v[146:147], v[134:135] op_sel_hi:[1,0]
	v_pk_mul_f32 v[130:131], v[130:131], v[134:135] op_sel_hi:[1,0]
	v_pk_mul_f32 v[128:129], v[128:129], v[134:135] op_sel_hi:[1,0]
	v_pk_mul_f32 v[126:127], v[126:127], v[134:135] op_sel_hi:[1,0]
	v_pk_mul_f32 v[124:125], v[124:125], v[134:135] op_sel_hi:[1,0]
	s_waitcnt vmcnt(1)
	v_pk_mul_f32 v[146:147], v[118:119], v[146:147]
	s_waitcnt vmcnt(0)
	v_pk_mul_f32 v[150:151], v[160:161], v[150:151]
	v_pk_mul_f32 v[152:153], v[158:159], v[152:153]
	v_pk_mul_f32 v[118:119], v[116:117], v[148:149]
	v_cvt_pk_bf16_f32 v116, v152, v153
	v_cvt_pk_bf16_f32 v117, v150, v151
	v_cvt_pk_bf16_f32 v118, v118, v119
	v_cvt_pk_bf16_f32 v119, v146, v147
	global_store_dwordx4 v[154:155], v[116:119], off offset:-768
	global_load_dwordx4 v[116:119], v121, s[36:37] offset:144
	s_nop 0
	global_load_dwordx4 v[146:149], v121, s[36:37] offset:128
	s_waitcnt vmcnt(1)
	v_pk_mul_f32 v[124:125], v[118:119], v[124:125]
	s_waitcnt vmcnt(0)
	v_pk_mul_f32 v[128:129], v[148:149], v[128:129]
	v_pk_mul_f32 v[130:131], v[146:147], v[130:131]
	v_pk_mul_f32 v[118:119], v[116:117], v[126:127]
	v_cvt_pk_bf16_f32 v116, v130, v131
	v_cvt_pk_bf16_f32 v117, v128, v129
	v_cvt_pk_bf16_f32 v118, v118, v119
	v_cvt_pk_bf16_f32 v119, v124, v125
	global_store_dwordx4 v[154:155], v[116:119], off offset:-704

.LBB0_536:
	s_andn2_b64 vcc, exec, s[52:53]
	s_cbranch_vccnz .LBB0_540
	v_pk_mul_f32 v[114:115], v[114:115], v[120:121] op_sel_hi:[1,0]
	v_pk_mul_f32 v[112:113], v[112:113], v[120:121] op_sel_hi:[1,0]
	v_pk_mul_f32 v[116:117], v[110:111], v[120:121] op_sel_hi:[1,0]
	v_pk_mul_f32 v[110:111], v[108:109], v[120:121] op_sel_hi:[1,0]
	v_mul_f32_e32 v108, v113, v113
	v_mul_f32_e32 v109, v115, v115
	v_fmac_f32_e32 v108, v112, v112
	v_fmac_f32_e32 v109, v114, v114
	v_add_f32_e32 v108, v108, v109
	v_mul_f32_e32 v109, v111, v111
	v_mul_f32_e32 v118, v117, v117
	v_fmac_f32_e32 v109, v110, v110
	v_fmac_f32_e32 v118, v116, v116
	v_add_f32_e32 v109, v109, v118
	v_add_f32_e32 v121, v108, v109
	v_mov_b64_e32 v[108:109], s[26:27]
	s_movk_i32 s0, 0x300
	v_mad_i64_i32 v[108:109], s[0:1], v122, s0, v[108:109]
	v_pk_mul_f32 v[106:107], v[106:107], v[120:121] op_sel_hi:[1,0]
	v_pk_mul_f32 v[104:105], v[104:105], v[120:121] op_sel_hi:[1,0]
	v_lshl_add_u64 v[118:119], v[132:133], 1, v[108:109]
	v_cvt_pk_bf16_f32 v109, v114, v115
	v_pk_mul_f32 v[114:115], v[100:101], v[120:121] op_sel_hi:[1,0]
	v_mul_f32_e32 v100, v105, v105
	v_mul_f32_e32 v101, v107, v107
	v_cvt_pk_bf16_f32 v108, v112, v113
	v_pk_mul_f32 v[112:113], v[102:103], v[120:121] op_sel_hi:[1,0]
	v_fmac_f32_e32 v100, v104, v104
	v_fmac_f32_e32 v101, v106, v106
	v_add_f32_e32 v100, v100, v101
	v_mul_f32_e32 v101, v115, v115
	v_mul_f32_e32 v102, v113, v113
	v_fmac_f32_e32 v101, v114, v114
	v_fmac_f32_e32 v102, v112, v112
	v_add_f32_e32 v101, v101, v102
	v_add_f32_e32 v100, v100, v101
	v_add_f32_e32 v100, v121, v100
	v_mov_b32_e32 v101, v100
	s_nop 1
	v_permlane16_swap_b32 v101, v100
	v_and_b32_e32 v103, 64, v236
	v_add_u32_e32 v103, 64, v103
	v_cvt_pk_bf16_f32 v110, v110, v111
	v_cvt_pk_bf16_f32 v111, v116, v117
	s_waitcnt lgkmcnt(0)
	v_add_f32_e32 v100, v100, v101
	v_xor_b32_e32 v101, 32, v236
	v_cmp_lt_i32_e32 vcc, v101, v103
	v_cvt_pk_bf16_f32 v102, v104, v105
	v_cvt_pk_bf16_f32 v103, v106, v107
	v_cndmask_b32_e32 v101, v236, v101, vcc
	v_lshlrev_b32_e32 v101, 2, v101
	v_mov_b32_e32 v101, v100
	s_nop 1
	v_permlane32_swap_b32 v101, v100
	v_cvt_pk_bf16_f32 v104, v114, v115
	v_cvt_pk_bf16_f32 v105, v112, v113
	global_store_dwordx4 v[118:119], v[108:111], off
	global_store_dwordx4 v[118:119], v[102:105], off offset:64
	s_and_saveexec_b64 s[0:1], s[16:17]
	s_cbranch_execz .LBB0_539
	s_waitcnt lgkmcnt(0)
	v_add_f32_e32 v102, v100, v101
	v_lshl_add_u64 v[100:101], v[142:143], 2, s[28:29]
	global_atomic_add_f32 v[100:101], v102, off offset:64

.LBB0_550:
	s_andn2_b64 vcc, exec, s[0:1]
	s_cbranch_vccnz .LBB0_552
	v_lshlrev_b64 v[100:101], 9, v[106:107]
	v_lshl_add_u64 v[100:101], s[30:31], 0, v[100:101]
	v_pk_mul_f32 v[122:123], v[98:99], v[104:105] op_sel_hi:[1,0]
	v_pk_mul_f32 v[124:125], v[96:97], v[104:105] op_sel_hi:[1,0]
	v_lshl_add_u64 v[126:127], s[68:69], 1, v[100:101]
	v_pk_mul_f32 v[100:101], v[122:123], v[122:123]
	v_pk_mul_f32 v[102:103], v[124:125], v[124:125]
	v_pk_mul_f32 v[118:119], v[94:95], v[104:105] op_sel_hi:[1,0]
	v_pk_mov_b32 v[108:109], v[102:103], v[100:101] op_sel:[1,0]
	v_mov_b32_e32 v103, v101
	v_pk_add_f32 v[100:101], v[108:109], v[102:103]
	v_pk_mul_f32 v[120:121], v[92:93], v[104:105] op_sel_hi:[1,0]
	v_pk_add_f32 v[100:101], v[100:101], v[100:101] op_sel_hi:[0,1]
	v_pk_mul_f32 v[102:103], v[118:119], v[118:119]
	v_pk_mul_f32 v[108:109], v[120:121], v[120:121]
	v_pk_mul_f32 v[114:115], v[88:89], v[104:105] op_sel_hi:[1,0]
	v_pk_mov_b32 v[110:111], v[108:109], v[102:103] op_sel:[1,0]
	v_mov_b32_e32 v109, v103
	v_pk_mul_f32 v[112:113], v[90:91], v[104:105] op_sel_hi:[1,0]
	v_mul_f32_e32 v100, v114, v114
	v_pk_add_f32 v[102:103], v[110:111], v[108:109]
	v_pk_fma_f32 v[116:117], v[114:115], v[114:115], v[100:101] op_sel_hi:[1,1,0]
	v_mul_f32_e32 v100, v112, v112
	v_pk_add_f32 v[102:103], v[102:103], v[102:103] op_sel_hi:[0,1]
	v_pk_fma_f32 v[128:129], v[112:113], v[112:113], v[100:101] op_sel_hi:[1,1,0]
	v_pk_mul_f32 v[108:109], v[86:87], v[104:105] op_sel_hi:[1,0]
	v_pk_mul_f32 v[110:111], v[84:85], v[104:105] op_sel_hi:[1,0]
	v_mul_f32_e32 v100, v108, v108
	v_mul_f32_e32 v116, v110, v110
	v_mul_f32_e32 v128, v111, v111
	v_mul_f32_e32 v102, v109, v109
	v_pk_add_f32 v[116:117], v[116:117], v[128:129]
	v_pk_add_f32 v[100:101], v[100:101], v[102:103]
	v_and_b32_e32 v102, 64, v236
	v_pk_add_f32 v[100:101], v[116:117], v[100:101]
	v_add_u32_e32 v102, 64, v102
	v_add_f32_e32 v100, v100, v101
	v_mov_b32_e32 v101, v100
	s_nop 1
	v_permlane16_swap_b32 v101, v100
	v_lshlrev_b32_e32 v105, 2, v157
	v_lshlrev_b32_e32 v134, 1, v157
	v_mov_b32_e32 v135, v2
	v_lshl_add_u64 v[126:127], v[126:127], 0, v[134:135]
	s_waitcnt lgkmcnt(0)
	v_add_f32_e32 v100, v100, v101
	v_xor_b32_e32 v101, 32, v236
	v_cmp_lt_i32_e32 vcc, v101, v102
	s_nop 1
	v_cndmask_b32_e32 v101, v236, v101, vcc
	v_lshlrev_b32_e32 v101, 2, v101
	v_mov_b32_e32 v101, v100
	s_nop 1
	v_permlane32_swap_b32 v101, v100
	s_waitcnt lgkmcnt(0)
	v_add_f32_e32 v100, v100, v101
	v_fmamk_f32 v100, v100, 0x3c800000, v231
	v_cmp_gt_f32_e32 vcc, s11, v100
	v_mul_f32_e32 v101, 0x4b800000, v100
	s_nop 0
	v_cndmask_b32_e32 v100, v100, v101, vcc
	v_rsq_f32_e32 v100, v100
	s_nop 0
	v_mul_f32_e32 v101, 0x45800000, v100
	v_cndmask_b32_e32 v100, v100, v101, vcc
	v_mul_f32_e32 v116, 0x3e38aa3b, v100
	global_load_dwordx4 v[100:103], v105, s[36:37] offset:16
	global_load_dwordx4 v[128:131], v105, s[36:37]
	v_pk_mul_f32 v[124:125], v[124:125], v[116:117] op_sel_hi:[1,0]
	v_pk_mul_f32 v[122:123], v[122:123], v[116:117] op_sel_hi:[1,0]
	v_pk_mul_f32 v[120:121], v[120:121], v[116:117] op_sel_hi:[1,0]
	v_pk_mul_f32 v[118:119], v[118:119], v[116:117] op_sel_hi:[1,0]
	v_pk_mul_f32 v[114:115], v[114:115], v[116:117] op_sel_hi:[1,0]
	v_pk_mul_f32 v[112:113], v[112:113], v[116:117] op_sel_hi:[1,0]
	v_pk_mul_f32 v[110:111], v[110:111], v[116:117] op_sel_hi:[1,0]
	v_pk_mul_f32 v[108:109], v[108:109], v[116:117] op_sel_hi:[1,0]
	s_waitcnt vmcnt(1)
	v_pk_mul_f32 v[118:119], v[102:103], v[118:119]
	s_waitcnt vmcnt(0)
	v_pk_mul_f32 v[122:123], v[130:131], v[122:123]
	v_pk_mul_f32 v[124:125], v[128:129], v[124:125]
	v_pk_mul_f32 v[102:103], v[100:101], v[120:121]
	v_cvt_pk_bf16_f32 v100, v124, v125
	v_cvt_pk_bf16_f32 v101, v122, v123
	v_cvt_pk_bf16_f32 v102, v102, v103
	v_cvt_pk_bf16_f32 v103, v118, v119
	global_store_dwordx4 v[126:127], v[100:103], off offset:-768
	global_load_dwordx4 v[100:103], v105, s[36:37] offset:144
	s_nop 0
	global_load_dwordx4 v[118:121], v105, s[36:37] offset:128
	s_waitcnt vmcnt(1)
	v_pk_mul_f32 v[108:109], v[102:103], v[108:109]
	s_waitcnt vmcnt(0)
	v_pk_mul_f32 v[112:113], v[120:121], v[112:113]
	v_pk_mul_f32 v[114:115], v[118:119], v[114:115]
	v_pk_mul_f32 v[102:103], v[100:101], v[110:111]
	v_cvt_pk_bf16_f32 v100, v114, v115
	v_cvt_pk_bf16_f32 v101, v112, v113
	v_cvt_pk_bf16_f32 v102, v102, v103
	v_cvt_pk_bf16_f32 v103, v108, v109
	global_store_dwordx4 v[126:127], v[100:103], off offset:-704

.LBB0_553:
	s_andn2_b64 vcc, exec, s[0:1]
	s_cbranch_vccnz .LBB0_557
	v_pk_mul_f32 v[98:99], v[98:99], v[104:105] op_sel_hi:[1,0]
	v_pk_mul_f32 v[96:97], v[96:97], v[104:105] op_sel_hi:[1,0]
	v_pk_mul_f32 v[100:101], v[94:95], v[104:105] op_sel_hi:[1,0]
	v_pk_mul_f32 v[94:95], v[92:93], v[104:105] op_sel_hi:[1,0]
	v_mul_f32_e32 v92, v97, v97
	v_mul_f32_e32 v93, v99, v99
	v_fmac_f32_e32 v92, v96, v96
	v_fmac_f32_e32 v93, v98, v98
	v_add_f32_e32 v92, v92, v93
	v_mul_f32_e32 v93, v95, v95
	v_mul_f32_e32 v102, v101, v101
	v_fmac_f32_e32 v93, v94, v94
	v_fmac_f32_e32 v102, v100, v100
	v_add_f32_e32 v93, v93, v102
	v_add_f32_e32 v105, v92, v93
	v_mov_b64_e32 v[92:93], s[26:27]
	s_movk_i32 s0, 0x300
	v_mad_i64_i32 v[92:93], s[0:1], v106, s0, v[92:93]
	v_pk_mul_f32 v[90:91], v[90:91], v[104:105] op_sel_hi:[1,0]
	v_pk_mul_f32 v[88:89], v[88:89], v[104:105] op_sel_hi:[1,0]
	v_lshl_add_u64 v[102:103], v[132:133], 1, v[92:93]
	v_cvt_pk_bf16_f32 v93, v98, v99
	v_pk_mul_f32 v[98:99], v[84:85], v[104:105] op_sel_hi:[1,0]
	v_mul_f32_e32 v84, v89, v89
	v_mul_f32_e32 v85, v91, v91
	v_cvt_pk_bf16_f32 v92, v96, v97
	v_pk_mul_f32 v[96:97], v[86:87], v[104:105] op_sel_hi:[1,0]
	v_fmac_f32_e32 v84, v88, v88
	v_fmac_f32_e32 v85, v90, v90
	v_add_f32_e32 v84, v84, v85
	v_mul_f32_e32 v85, v99, v99
	v_mul_f32_e32 v86, v97, v97
	v_fmac_f32_e32 v85, v98, v98
	v_fmac_f32_e32 v86, v96, v96
	v_add_f32_e32 v85, v85, v86
	v_add_f32_e32 v84, v84, v85
	v_add_f32_e32 v84, v105, v84
	v_mov_b32_e32 v85, v84
	s_nop 1
	v_permlane16_swap_b32 v85, v84
	v_and_b32_e32 v87, 64, v236
	v_add_u32_e32 v87, 64, v87
	v_cvt_pk_bf16_f32 v94, v94, v95
	v_cvt_pk_bf16_f32 v95, v100, v101
	s_waitcnt lgkmcnt(0)
	v_add_f32_e32 v84, v84, v85
	v_xor_b32_e32 v85, 32, v236
	v_cmp_lt_i32_e32 vcc, v85, v87
	v_cvt_pk_bf16_f32 v86, v88, v89
	v_cvt_pk_bf16_f32 v87, v90, v91
	v_cndmask_b32_e32 v85, v236, v85, vcc
	v_lshlrev_b32_e32 v85, 2, v85
	v_mov_b32_e32 v85, v84
	s_nop 1
	v_permlane32_swap_b32 v85, v84
	v_cvt_pk_bf16_f32 v88, v98, v99
	v_cvt_pk_bf16_f32 v89, v96, v97
	global_store_dwordx4 v[102:103], v[92:95], off
	global_store_dwordx4 v[102:103], v[86:89], off offset:64
	s_and_saveexec_b64 s[0:1], s[16:17]
	s_cbranch_execz .LBB0_556
	s_waitcnt lgkmcnt(0)
	v_add_f32_e32 v86, v84, v85
	v_lshl_add_u64 v[84:85], v[142:143], 2, s[28:29]
	global_atomic_add_f32 v[84:85], v86, off offset:128

.LBB0_567:
	s_andn2_b64 vcc, exec, s[0:1]
	s_cbranch_vccnz .LBB0_569
	v_lshlrev_b64 v[84:85], 9, v[90:91]
	v_lshl_add_u64 v[84:85], s[30:31], 0, v[84:85]
	v_pk_mul_f32 v[106:107], v[82:83], v[88:89] op_sel_hi:[1,0]
	v_pk_mul_f32 v[108:109], v[80:81], v[88:89] op_sel_hi:[1,0]
	v_lshl_add_u64 v[110:111], s[68:69], 1, v[84:85]
	v_pk_mul_f32 v[84:85], v[106:107], v[106:107]
	v_pk_mul_f32 v[86:87], v[108:109], v[108:109]
	v_pk_mul_f32 v[102:103], v[78:79], v[88:89] op_sel_hi:[1,0]
	v_pk_mov_b32 v[92:93], v[86:87], v[84:85] op_sel:[1,0]
	v_mov_b32_e32 v87, v85
	v_pk_add_f32 v[84:85], v[92:93], v[86:87]
	v_pk_mul_f32 v[104:105], v[76:77], v[88:89] op_sel_hi:[1,0]
	v_pk_add_f32 v[84:85], v[84:85], v[84:85] op_sel_hi:[0,1]
	v_pk_mul_f32 v[86:87], v[102:103], v[102:103]
	v_pk_mul_f32 v[92:93], v[104:105], v[104:105]
	v_pk_mul_f32 v[98:99], v[72:73], v[88:89] op_sel_hi:[1,0]
	v_pk_mov_b32 v[94:95], v[92:93], v[86:87] op_sel:[1,0]
	v_mov_b32_e32 v93, v87
	v_pk_mul_f32 v[96:97], v[74:75], v[88:89] op_sel_hi:[1,0]
	v_mul_f32_e32 v84, v98, v98
	v_pk_add_f32 v[86:87], v[94:95], v[92:93]
	v_pk_fma_f32 v[100:101], v[98:99], v[98:99], v[84:85] op_sel_hi:[1,1,0]
	v_mul_f32_e32 v84, v96, v96
	v_pk_add_f32 v[86:87], v[86:87], v[86:87] op_sel_hi:[0,1]
	v_pk_fma_f32 v[112:113], v[96:97], v[96:97], v[84:85] op_sel_hi:[1,1,0]
	v_pk_mul_f32 v[92:93], v[70:71], v[88:89] op_sel_hi:[1,0]
	v_pk_mul_f32 v[94:95], v[68:69], v[88:89] op_sel_hi:[1,0]
	v_mul_f32_e32 v84, v92, v92
	v_mul_f32_e32 v100, v94, v94
	v_mul_f32_e32 v112, v95, v95
	v_mul_f32_e32 v86, v93, v93
	v_pk_add_f32 v[100:101], v[100:101], v[112:113]
	v_pk_add_f32 v[84:85], v[84:85], v[86:87]
	v_and_b32_e32 v86, 64, v236
	v_pk_add_f32 v[84:85], v[100:101], v[84:85]
	v_add_u32_e32 v86, 64, v86
	v_add_f32_e32 v84, v84, v85
	v_mov_b32_e32 v85, v84
	s_nop 1
	v_permlane16_swap_b32 v85, v84
	v_lshlrev_b32_e32 v89, 2, v157
	v_lshlrev_b32_e32 v116, 1, v157
	v_mov_b32_e32 v117, v2
	v_lshl_add_u64 v[110:111], v[110:111], 0, v[116:117]
	s_waitcnt lgkmcnt(0)
	v_add_f32_e32 v84, v84, v85
	v_xor_b32_e32 v85, 32, v236
	v_cmp_lt_i32_e32 vcc, v85, v86
	s_nop 1
	v_cndmask_b32_e32 v85, v236, v85, vcc
	v_lshlrev_b32_e32 v85, 2, v85
	v_mov_b32_e32 v85, v84
	s_nop 1
	v_permlane32_swap_b32 v85, v84
	s_waitcnt lgkmcnt(0)
	v_add_f32_e32 v84, v84, v85
	v_fmamk_f32 v84, v84, 0x3c800000, v231
	v_cmp_gt_f32_e32 vcc, s11, v84
	v_mul_f32_e32 v85, 0x4b800000, v84
	s_nop 0
	v_cndmask_b32_e32 v84, v84, v85, vcc
	v_rsq_f32_e32 v84, v84
	s_nop 0
	v_mul_f32_e32 v85, 0x45800000, v84
	v_cndmask_b32_e32 v84, v84, v85, vcc
	v_mul_f32_e32 v100, 0x3e38aa3b, v84
	global_load_dwordx4 v[84:87], v89, s[36:37] offset:16
	global_load_dwordx4 v[112:115], v89, s[36:37]
	v_pk_mul_f32 v[108:109], v[108:109], v[100:101] op_sel_hi:[1,0]
	v_pk_mul_f32 v[106:107], v[106:107], v[100:101] op_sel_hi:[1,0]
	v_pk_mul_f32 v[104:105], v[104:105], v[100:101] op_sel_hi:[1,0]
	v_pk_mul_f32 v[102:103], v[102:103], v[100:101] op_sel_hi:[1,0]
	v_pk_mul_f32 v[98:99], v[98:99], v[100:101] op_sel_hi:[1,0]
	v_pk_mul_f32 v[96:97], v[96:97], v[100:101] op_sel_hi:[1,0]
	v_pk_mul_f32 v[94:95], v[94:95], v[100:101] op_sel_hi:[1,0]
	v_pk_mul_f32 v[92:93], v[92:93], v[100:101] op_sel_hi:[1,0]
	s_waitcnt vmcnt(1)
	v_pk_mul_f32 v[102:103], v[86:87], v[102:103]
	s_waitcnt vmcnt(0)
	v_pk_mul_f32 v[106:107], v[114:115], v[106:107]
	v_pk_mul_f32 v[108:109], v[112:113], v[108:109]
	v_pk_mul_f32 v[86:87], v[84:85], v[104:105]
	v_cvt_pk_bf16_f32 v84, v108, v109
	v_cvt_pk_bf16_f32 v85, v106, v107
	v_cvt_pk_bf16_f32 v86, v86, v87
	v_cvt_pk_bf16_f32 v87, v102, v103
	global_store_dwordx4 v[110:111], v[84:87], off offset:-768
	global_load_dwordx4 v[84:87], v89, s[36:37] offset:144
	s_nop 0
	global_load_dwordx4 v[102:105], v89, s[36:37] offset:128
	s_waitcnt vmcnt(1)
	v_pk_mul_f32 v[92:93], v[86:87], v[92:93]
	s_waitcnt vmcnt(0)
	v_pk_mul_f32 v[96:97], v[104:105], v[96:97]
	v_pk_mul_f32 v[98:99], v[102:103], v[98:99]
	v_pk_mul_f32 v[86:87], v[84:85], v[94:95]
	v_cvt_pk_bf16_f32 v84, v98, v99
	v_cvt_pk_bf16_f32 v85, v96, v97
	v_cvt_pk_bf16_f32 v86, v86, v87
	v_cvt_pk_bf16_f32 v87, v92, v93
	global_store_dwordx4 v[110:111], v[84:87], off offset:-704

.LBB0_570:
	s_andn2_b64 vcc, exec, s[0:1]
	s_cbranch_vccnz .LBB0_574
	v_pk_mul_f32 v[82:83], v[82:83], v[88:89] op_sel_hi:[1,0]
	v_pk_mul_f32 v[80:81], v[80:81], v[88:89] op_sel_hi:[1,0]
	v_pk_mul_f32 v[84:85], v[78:79], v[88:89] op_sel_hi:[1,0]
	v_pk_mul_f32 v[78:79], v[76:77], v[88:89] op_sel_hi:[1,0]
	v_mul_f32_e32 v76, v81, v81
	v_mul_f32_e32 v77, v83, v83
	v_fmac_f32_e32 v76, v80, v80
	v_fmac_f32_e32 v77, v82, v82
	v_add_f32_e32 v76, v76, v77
	v_mul_f32_e32 v77, v79, v79
	v_mul_f32_e32 v86, v85, v85
	v_fmac_f32_e32 v77, v78, v78
	v_fmac_f32_e32 v86, v84, v84
	v_add_f32_e32 v77, v77, v86
	v_add_f32_e32 v89, v76, v77
	v_mov_b64_e32 v[76:77], s[26:27]
	s_movk_i32 s0, 0x300
	v_mad_i64_i32 v[76:77], s[0:1], v90, s0, v[76:77]
	v_pk_mul_f32 v[74:75], v[74:75], v[88:89] op_sel_hi:[1,0]
	v_pk_mul_f32 v[72:73], v[72:73], v[88:89] op_sel_hi:[1,0]
	v_lshl_add_u64 v[86:87], v[132:133], 1, v[76:77]
	v_cvt_pk_bf16_f32 v77, v82, v83
	v_pk_mul_f32 v[82:83], v[68:69], v[88:89] op_sel_hi:[1,0]
	v_mul_f32_e32 v68, v73, v73
	v_mul_f32_e32 v69, v75, v75
	v_cvt_pk_bf16_f32 v76, v80, v81
	v_pk_mul_f32 v[80:81], v[70:71], v[88:89] op_sel_hi:[1,0]
	v_fmac_f32_e32 v68, v72, v72
	v_fmac_f32_e32 v69, v74, v74
	v_add_f32_e32 v68, v68, v69
	v_mul_f32_e32 v69, v83, v83
	v_mul_f32_e32 v70, v81, v81
	v_fmac_f32_e32 v69, v82, v82
	v_fmac_f32_e32 v70, v80, v80
	v_add_f32_e32 v69, v69, v70
	v_add_f32_e32 v68, v68, v69
	v_add_f32_e32 v68, v89, v68
	v_mov_b32_e32 v69, v68
	s_nop 1
	v_permlane16_swap_b32 v69, v68
	v_and_b32_e32 v71, 64, v236
	v_add_u32_e32 v71, 64, v71
	v_cvt_pk_bf16_f32 v78, v78, v79
	v_cvt_pk_bf16_f32 v79, v84, v85
	s_waitcnt lgkmcnt(0)
	v_add_f32_e32 v68, v68, v69
	v_xor_b32_e32 v69, 32, v236
	v_cmp_lt_i32_e32 vcc, v69, v71
	v_cvt_pk_bf16_f32 v70, v72, v73
	v_cvt_pk_bf16_f32 v71, v74, v75
	v_cndmask_b32_e32 v69, v236, v69, vcc
	v_lshlrev_b32_e32 v69, 2, v69
	v_mov_b32_e32 v69, v68
	s_nop 1
	v_permlane32_swap_b32 v69, v68
	v_cvt_pk_bf16_f32 v72, v82, v83
	v_cvt_pk_bf16_f32 v73, v80, v81
	global_store_dwordx4 v[86:87], v[76:79], off
	global_store_dwordx4 v[86:87], v[70:73], off offset:64
	s_and_saveexec_b64 s[0:1], s[16:17]
	s_cbranch_execz .LBB0_573
	s_waitcnt lgkmcnt(0)
	v_add_f32_e32 v70, v68, v69
	v_lshl_add_u64 v[68:69], v[142:143], 2, s[28:29]
	global_atomic_add_f32 v[68:69], v70, off offset:192

.LBB0_584:
	s_andn2_b64 vcc, exec, s[0:1]
	s_cbranch_vccnz .LBB0_586
	v_lshlrev_b64 v[68:69], 9, v[74:75]
	v_lshl_add_u64 v[68:69], s[30:31], 0, v[68:69]
	v_pk_mul_f32 v[90:91], v[66:67], v[72:73] op_sel_hi:[1,0]
	v_pk_mul_f32 v[92:93], v[64:65], v[72:73] op_sel_hi:[1,0]
	v_lshl_add_u64 v[94:95], s[68:69], 1, v[68:69]
	v_pk_mul_f32 v[68:69], v[90:91], v[90:91]
	v_pk_mul_f32 v[70:71], v[92:93], v[92:93]
	v_pk_mul_f32 v[86:87], v[62:63], v[72:73] op_sel_hi:[1,0]
	v_pk_mov_b32 v[76:77], v[70:71], v[68:69] op_sel:[1,0]
	v_mov_b32_e32 v71, v69
	v_pk_add_f32 v[68:69], v[76:77], v[70:71]
	v_pk_mul_f32 v[88:89], v[60:61], v[72:73] op_sel_hi:[1,0]
	v_pk_add_f32 v[68:69], v[68:69], v[68:69] op_sel_hi:[0,1]
	v_pk_mul_f32 v[70:71], v[86:87], v[86:87]
	v_pk_mul_f32 v[76:77], v[88:89], v[88:89]
	v_pk_mul_f32 v[82:83], v[56:57], v[72:73] op_sel_hi:[1,0]
	v_pk_mov_b32 v[78:79], v[76:77], v[70:71] op_sel:[1,0]
	v_mov_b32_e32 v77, v71
	v_pk_mul_f32 v[80:81], v[58:59], v[72:73] op_sel_hi:[1,0]
	v_mul_f32_e32 v68, v82, v82
	v_pk_add_f32 v[70:71], v[78:79], v[76:77]
	v_pk_fma_f32 v[84:85], v[82:83], v[82:83], v[68:69] op_sel_hi:[1,1,0]
	v_mul_f32_e32 v68, v80, v80
	v_pk_add_f32 v[70:71], v[70:71], v[70:71] op_sel_hi:[0,1]
	v_pk_fma_f32 v[96:97], v[80:81], v[80:81], v[68:69] op_sel_hi:[1,1,0]
	v_pk_mul_f32 v[76:77], v[54:55], v[72:73] op_sel_hi:[1,0]
	v_pk_mul_f32 v[78:79], v[52:53], v[72:73] op_sel_hi:[1,0]
	v_mul_f32_e32 v68, v76, v76
	v_mul_f32_e32 v84, v78, v78
	v_mul_f32_e32 v96, v79, v79
	v_mul_f32_e32 v70, v77, v77
	v_pk_add_f32 v[84:85], v[84:85], v[96:97]
	v_pk_add_f32 v[68:69], v[68:69], v[70:71]
	v_and_b32_e32 v70, 64, v236
	v_pk_add_f32 v[68:69], v[84:85], v[68:69]
	v_add_u32_e32 v70, 64, v70
	v_add_f32_e32 v68, v68, v69
	v_mov_b32_e32 v69, v68
	s_nop 1
	v_permlane16_swap_b32 v69, v68
	v_lshlrev_b32_e32 v73, 2, v157
	v_lshlrev_b32_e32 v100, 1, v157
	v_mov_b32_e32 v101, v2
	v_lshl_add_u64 v[94:95], v[94:95], 0, v[100:101]
	s_waitcnt lgkmcnt(0)
	v_add_f32_e32 v68, v68, v69
	v_xor_b32_e32 v69, 32, v236
	v_cmp_lt_i32_e32 vcc, v69, v70
	s_nop 1
	v_cndmask_b32_e32 v69, v236, v69, vcc
	v_lshlrev_b32_e32 v69, 2, v69
	v_mov_b32_e32 v69, v68
	s_nop 1
	v_permlane32_swap_b32 v69, v68
	s_waitcnt lgkmcnt(0)
	v_add_f32_e32 v68, v68, v69
	v_fmamk_f32 v68, v68, 0x3c800000, v231
	v_cmp_gt_f32_e32 vcc, s11, v68
	v_mul_f32_e32 v69, 0x4b800000, v68
	s_nop 0
	v_cndmask_b32_e32 v68, v68, v69, vcc
	v_rsq_f32_e32 v68, v68
	s_nop 0
	v_mul_f32_e32 v69, 0x45800000, v68
	v_cndmask_b32_e32 v68, v68, v69, vcc
	v_mul_f32_e32 v84, 0x3e38aa3b, v68
	global_load_dwordx4 v[68:71], v73, s[36:37] offset:16
	global_load_dwordx4 v[96:99], v73, s[36:37]
	v_pk_mul_f32 v[92:93], v[92:93], v[84:85] op_sel_hi:[1,0]
	v_pk_mul_f32 v[90:91], v[90:91], v[84:85] op_sel_hi:[1,0]
	v_pk_mul_f32 v[88:89], v[88:89], v[84:85] op_sel_hi:[1,0]
	v_pk_mul_f32 v[86:87], v[86:87], v[84:85] op_sel_hi:[1,0]
	v_pk_mul_f32 v[82:83], v[82:83], v[84:85] op_sel_hi:[1,0]
	v_pk_mul_f32 v[80:81], v[80:81], v[84:85] op_sel_hi:[1,0]
	v_pk_mul_f32 v[78:79], v[78:79], v[84:85] op_sel_hi:[1,0]
	v_pk_mul_f32 v[76:77], v[76:77], v[84:85] op_sel_hi:[1,0]
	s_waitcnt vmcnt(1)
	v_pk_mul_f32 v[86:87], v[70:71], v[86:87]
	s_waitcnt vmcnt(0)
	v_pk_mul_f32 v[90:91], v[98:99], v[90:91]
	v_pk_mul_f32 v[92:93], v[96:97], v[92:93]
	v_pk_mul_f32 v[70:71], v[68:69], v[88:89]
	v_cvt_pk_bf16_f32 v68, v92, v93
	v_cvt_pk_bf16_f32 v69, v90, v91
	v_cvt_pk_bf16_f32 v70, v70, v71
	v_cvt_pk_bf16_f32 v71, v86, v87
	global_store_dwordx4 v[94:95], v[68:71], off offset:-768
	global_load_dwordx4 v[68:71], v73, s[36:37] offset:144
	s_nop 0
	global_load_dwordx4 v[86:89], v73, s[36:37] offset:128
	s_waitcnt vmcnt(1)
	v_pk_mul_f32 v[76:77], v[70:71], v[76:77]
	s_waitcnt vmcnt(0)
	v_pk_mul_f32 v[80:81], v[88:89], v[80:81]
	v_pk_mul_f32 v[82:83], v[86:87], v[82:83]
	v_pk_mul_f32 v[70:71], v[68:69], v[78:79]
	v_cvt_pk_bf16_f32 v68, v82, v83
	v_cvt_pk_bf16_f32 v69, v80, v81
	v_cvt_pk_bf16_f32 v70, v70, v71
	v_cvt_pk_bf16_f32 v71, v76, v77
	global_store_dwordx4 v[94:95], v[68:71], off offset:-704

.LBB0_587:
	s_andn2_b64 vcc, exec, s[0:1]
	s_cbranch_vccnz .LBB0_591
	v_pk_mul_f32 v[66:67], v[66:67], v[72:73] op_sel_hi:[1,0]
	v_pk_mul_f32 v[64:65], v[64:65], v[72:73] op_sel_hi:[1,0]
	v_pk_mul_f32 v[68:69], v[62:63], v[72:73] op_sel_hi:[1,0]
	v_pk_mul_f32 v[62:63], v[60:61], v[72:73] op_sel_hi:[1,0]
	v_mul_f32_e32 v60, v65, v65
	v_mul_f32_e32 v61, v67, v67
	v_fmac_f32_e32 v60, v64, v64
	v_fmac_f32_e32 v61, v66, v66
	v_add_f32_e32 v60, v60, v61
	v_mul_f32_e32 v61, v63, v63
	v_mul_f32_e32 v70, v69, v69
	v_fmac_f32_e32 v61, v62, v62
	v_fmac_f32_e32 v70, v68, v68
	v_add_f32_e32 v61, v61, v70
	v_add_f32_e32 v73, v60, v61
	v_mov_b64_e32 v[60:61], s[26:27]
	s_movk_i32 s0, 0x300
	v_mad_i64_i32 v[60:61], s[0:1], v74, s0, v[60:61]
	v_pk_mul_f32 v[58:59], v[58:59], v[72:73] op_sel_hi:[1,0]
	v_pk_mul_f32 v[56:57], v[56:57], v[72:73] op_sel_hi:[1,0]
	v_lshl_add_u64 v[70:71], v[132:133], 1, v[60:61]
	v_cvt_pk_bf16_f32 v61, v66, v67
	v_pk_mul_f32 v[66:67], v[52:53], v[72:73] op_sel_hi:[1,0]
	v_mul_f32_e32 v52, v57, v57
	v_mul_f32_e32 v53, v59, v59
	v_cvt_pk_bf16_f32 v60, v64, v65
	v_pk_mul_f32 v[64:65], v[54:55], v[72:73] op_sel_hi:[1,0]
	v_fmac_f32_e32 v52, v56, v56
	v_fmac_f32_e32 v53, v58, v58
	v_add_f32_e32 v52, v52, v53
	v_mul_f32_e32 v53, v67, v67
	v_mul_f32_e32 v54, v65, v65
	v_fmac_f32_e32 v53, v66, v66
	v_fmac_f32_e32 v54, v64, v64
	v_add_f32_e32 v53, v53, v54
	v_add_f32_e32 v52, v52, v53
	v_add_f32_e32 v52, v73, v52
	v_mov_b32_e32 v53, v52
	s_nop 1
	v_permlane16_swap_b32 v53, v52
	v_and_b32_e32 v55, 64, v236
	v_add_u32_e32 v55, 64, v55
	v_cvt_pk_bf16_f32 v62, v62, v63
	v_cvt_pk_bf16_f32 v63, v68, v69
	s_waitcnt lgkmcnt(0)
	v_add_f32_e32 v52, v52, v53
	v_xor_b32_e32 v53, 32, v236
	v_cmp_lt_i32_e32 vcc, v53, v55
	v_cvt_pk_bf16_f32 v54, v56, v57
	v_cvt_pk_bf16_f32 v55, v58, v59
	v_cndmask_b32_e32 v53, v236, v53, vcc
	v_lshlrev_b32_e32 v53, 2, v53
	v_mov_b32_e32 v53, v52
	s_nop 1
	v_permlane32_swap_b32 v53, v52
	v_cvt_pk_bf16_f32 v56, v66, v67
	v_cvt_pk_bf16_f32 v57, v64, v65
	global_store_dwordx4 v[70:71], v[60:63], off
	global_store_dwordx4 v[70:71], v[54:57], off offset:64
	s_and_saveexec_b64 s[0:1], s[16:17]
	s_cbranch_execz .LBB0_590
	s_waitcnt lgkmcnt(0)
	v_add_f32_e32 v54, v52, v53
	v_lshl_add_u64 v[52:53], v[142:143], 2, s[28:29]
	global_atomic_add_f32 v[52:53], v54, off offset:512

.LBB0_601:
	s_andn2_b64 vcc, exec, s[0:1]
	s_cbranch_vccnz .LBB0_603
	v_lshlrev_b64 v[52:53], 9, v[58:59]
	v_lshl_add_u64 v[52:53], s[30:31], 0, v[52:53]
	v_pk_mul_f32 v[74:75], v[50:51], v[56:57] op_sel_hi:[1,0]
	v_pk_mul_f32 v[76:77], v[48:49], v[56:57] op_sel_hi:[1,0]
	v_lshl_add_u64 v[78:79], s[68:69], 1, v[52:53]
	v_pk_mul_f32 v[52:53], v[74:75], v[74:75]
	v_pk_mul_f32 v[54:55], v[76:77], v[76:77]
	v_pk_mul_f32 v[70:71], v[46:47], v[56:57] op_sel_hi:[1,0]
	v_pk_mov_b32 v[60:61], v[54:55], v[52:53] op_sel:[1,0]
	v_mov_b32_e32 v55, v53
	v_pk_add_f32 v[52:53], v[60:61], v[54:55]
	v_pk_mul_f32 v[72:73], v[44:45], v[56:57] op_sel_hi:[1,0]
	v_pk_add_f32 v[52:53], v[52:53], v[52:53] op_sel_hi:[0,1]
	v_pk_mul_f32 v[54:55], v[70:71], v[70:71]
	v_pk_mul_f32 v[60:61], v[72:73], v[72:73]
	v_pk_mul_f32 v[66:67], v[40:41], v[56:57] op_sel_hi:[1,0]
	v_pk_mov_b32 v[62:63], v[60:61], v[54:55] op_sel:[1,0]
	v_mov_b32_e32 v61, v55
	v_pk_mul_f32 v[64:65], v[42:43], v[56:57] op_sel_hi:[1,0]
	v_mul_f32_e32 v52, v66, v66
	v_pk_add_f32 v[54:55], v[62:63], v[60:61]
	v_pk_fma_f32 v[68:69], v[66:67], v[66:67], v[52:53] op_sel_hi:[1,1,0]
	v_mul_f32_e32 v52, v64, v64
	v_pk_add_f32 v[54:55], v[54:55], v[54:55] op_sel_hi:[0,1]
	v_pk_fma_f32 v[80:81], v[64:65], v[64:65], v[52:53] op_sel_hi:[1,1,0]
	v_pk_mul_f32 v[60:61], v[38:39], v[56:57] op_sel_hi:[1,0]
	v_pk_mul_f32 v[62:63], v[36:37], v[56:57] op_sel_hi:[1,0]
	v_mul_f32_e32 v52, v60, v60
	v_mul_f32_e32 v68, v62, v62
	v_mul_f32_e32 v80, v63, v63
	v_mul_f32_e32 v54, v61, v61
	v_pk_add_f32 v[68:69], v[68:69], v[80:81]
	v_pk_add_f32 v[52:53], v[52:53], v[54:55]
	v_and_b32_e32 v54, 64, v236
	v_pk_add_f32 v[52:53], v[68:69], v[52:53]
	v_add_u32_e32 v54, 64, v54
	v_add_f32_e32 v52, v52, v53
	v_mov_b32_e32 v53, v52
	s_nop 1
	v_permlane16_swap_b32 v53, v52
	v_lshlrev_b32_e32 v57, 2, v157
	v_lshlrev_b32_e32 v84, 1, v157
	v_mov_b32_e32 v85, v2
	v_lshl_add_u64 v[78:79], v[78:79], 0, v[84:85]
	s_waitcnt lgkmcnt(0)
	v_add_f32_e32 v52, v52, v53
	v_xor_b32_e32 v53, 32, v236
	v_cmp_lt_i32_e32 vcc, v53, v54
	s_nop 1
	v_cndmask_b32_e32 v53, v236, v53, vcc
	v_lshlrev_b32_e32 v53, 2, v53
	v_mov_b32_e32 v53, v52
	s_nop 1
	v_permlane32_swap_b32 v53, v52
	s_waitcnt lgkmcnt(0)
	v_add_f32_e32 v52, v52, v53
	v_fmamk_f32 v52, v52, 0x3c800000, v231
	v_cmp_gt_f32_e32 vcc, s11, v52
	v_mul_f32_e32 v53, 0x4b800000, v52
	s_nop 0
	v_cndmask_b32_e32 v52, v52, v53, vcc
	v_rsq_f32_e32 v52, v52
	s_nop 0
	v_mul_f32_e32 v53, 0x45800000, v52
	v_cndmask_b32_e32 v52, v52, v53, vcc
	v_mul_f32_e32 v68, 0x3e38aa3b, v52
	global_load_dwordx4 v[52:55], v57, s[36:37] offset:16
	global_load_dwordx4 v[80:83], v57, s[36:37]
	v_pk_mul_f32 v[76:77], v[76:77], v[68:69] op_sel_hi:[1,0]
	v_pk_mul_f32 v[74:75], v[74:75], v[68:69] op_sel_hi:[1,0]
	v_pk_mul_f32 v[72:73], v[72:73], v[68:69] op_sel_hi:[1,0]
	v_pk_mul_f32 v[70:71], v[70:71], v[68:69] op_sel_hi:[1,0]
	v_pk_mul_f32 v[66:67], v[66:67], v[68:69] op_sel_hi:[1,0]
	v_pk_mul_f32 v[64:65], v[64:65], v[68:69] op_sel_hi:[1,0]
	v_pk_mul_f32 v[62:63], v[62:63], v[68:69] op_sel_hi:[1,0]
	v_pk_mul_f32 v[60:61], v[60:61], v[68:69] op_sel_hi:[1,0]
	s_waitcnt vmcnt(1)
	v_pk_mul_f32 v[70:71], v[54:55], v[70:71]
	s_waitcnt vmcnt(0)
	v_pk_mul_f32 v[74:75], v[82:83], v[74:75]
	v_pk_mul_f32 v[76:77], v[80:81], v[76:77]
	v_pk_mul_f32 v[54:55], v[52:53], v[72:73]
	v_cvt_pk_bf16_f32 v52, v76, v77
	v_cvt_pk_bf16_f32 v53, v74, v75
	v_cvt_pk_bf16_f32 v54, v54, v55
	v_cvt_pk_bf16_f32 v55, v70, v71
	global_store_dwordx4 v[78:79], v[52:55], off offset:-768
	global_load_dwordx4 v[52:55], v57, s[36:37] offset:144
	s_nop 0
	global_load_dwordx4 v[70:73], v57, s[36:37] offset:128
	s_waitcnt vmcnt(1)
	v_pk_mul_f32 v[60:61], v[54:55], v[60:61]
	s_waitcnt vmcnt(0)
	v_pk_mul_f32 v[64:65], v[72:73], v[64:65]
	v_pk_mul_f32 v[66:67], v[70:71], v[66:67]
	v_pk_mul_f32 v[54:55], v[52:53], v[62:63]
	v_cvt_pk_bf16_f32 v52, v66, v67
	v_cvt_pk_bf16_f32 v53, v64, v65
	v_cvt_pk_bf16_f32 v54, v54, v55
	v_cvt_pk_bf16_f32 v55, v60, v61
	global_store_dwordx4 v[78:79], v[52:55], off offset:-704

.LBB0_604:
	s_andn2_b64 vcc, exec, s[0:1]
	s_cbranch_vccnz .LBB0_608
	v_pk_mul_f32 v[50:51], v[50:51], v[56:57] op_sel_hi:[1,0]
	v_pk_mul_f32 v[48:49], v[48:49], v[56:57] op_sel_hi:[1,0]
	v_pk_mul_f32 v[52:53], v[46:47], v[56:57] op_sel_hi:[1,0]
	v_pk_mul_f32 v[46:47], v[44:45], v[56:57] op_sel_hi:[1,0]
	v_mul_f32_e32 v44, v49, v49
	v_mul_f32_e32 v45, v51, v51
	v_fmac_f32_e32 v44, v48, v48
	v_fmac_f32_e32 v45, v50, v50
	v_add_f32_e32 v44, v44, v45
	v_mul_f32_e32 v45, v47, v47
	v_mul_f32_e32 v54, v53, v53
	v_fmac_f32_e32 v45, v46, v46
	v_fmac_f32_e32 v54, v52, v52
	v_add_f32_e32 v45, v45, v54
	v_add_f32_e32 v57, v44, v45
	v_mov_b64_e32 v[44:45], s[26:27]
	s_movk_i32 s0, 0x300
	v_mad_i64_i32 v[44:45], s[0:1], v58, s0, v[44:45]
	v_pk_mul_f32 v[42:43], v[42:43], v[56:57] op_sel_hi:[1,0]
	v_pk_mul_f32 v[40:41], v[40:41], v[56:57] op_sel_hi:[1,0]
	v_lshl_add_u64 v[54:55], v[132:133], 1, v[44:45]
	v_cvt_pk_bf16_f32 v45, v50, v51
	v_pk_mul_f32 v[50:51], v[36:37], v[56:57] op_sel_hi:[1,0]
	v_mul_f32_e32 v36, v41, v41
	v_mul_f32_e32 v37, v43, v43
	v_cvt_pk_bf16_f32 v44, v48, v49
	v_pk_mul_f32 v[48:49], v[38:39], v[56:57] op_sel_hi:[1,0]
	v_fmac_f32_e32 v36, v40, v40
	v_fmac_f32_e32 v37, v42, v42
	v_add_f32_e32 v36, v36, v37
	v_mul_f32_e32 v37, v51, v51
	v_mul_f32_e32 v38, v49, v49
	v_fmac_f32_e32 v37, v50, v50
	v_fmac_f32_e32 v38, v48, v48
	v_add_f32_e32 v37, v37, v38
	v_add_f32_e32 v36, v36, v37
	v_add_f32_e32 v36, v57, v36
	v_mov_b32_e32 v37, v36
	s_nop 1
	v_permlane16_swap_b32 v37, v36
	v_and_b32_e32 v39, 64, v236
	v_add_u32_e32 v39, 64, v39
	v_cvt_pk_bf16_f32 v46, v46, v47
	v_cvt_pk_bf16_f32 v47, v52, v53
	s_waitcnt lgkmcnt(0)
	v_add_f32_e32 v36, v36, v37
	v_xor_b32_e32 v37, 32, v236
	v_cmp_lt_i32_e32 vcc, v37, v39
	v_cvt_pk_bf16_f32 v38, v40, v41
	v_cvt_pk_bf16_f32 v39, v42, v43
	v_cndmask_b32_e32 v37, v236, v37, vcc
	v_lshlrev_b32_e32 v37, 2, v37
	v_mov_b32_e32 v37, v36
	s_nop 1
	v_permlane32_swap_b32 v37, v36
	v_cvt_pk_bf16_f32 v40, v50, v51
	v_cvt_pk_bf16_f32 v41, v48, v49
	global_store_dwordx4 v[54:55], v[44:47], off
	global_store_dwordx4 v[54:55], v[38:41], off offset:64
	s_and_saveexec_b64 s[0:1], s[16:17]
	s_cbranch_execz .LBB0_607
	s_waitcnt lgkmcnt(0)
	v_add_f32_e32 v38, v36, v37
	v_lshl_add_u64 v[36:37], v[142:143], 2, s[28:29]
	global_atomic_add_f32 v[36:37], v38, off offset:576

.LBB0_618:
	s_andn2_b64 vcc, exec, s[0:1]
	s_cbranch_vccnz .LBB0_620
	v_lshlrev_b64 v[36:37], 9, v[42:43]
	v_lshl_add_u64 v[36:37], s[30:31], 0, v[36:37]
	v_pk_mul_f32 v[58:59], v[34:35], v[40:41] op_sel_hi:[1,0]
	v_pk_mul_f32 v[60:61], v[32:33], v[40:41] op_sel_hi:[1,0]
	v_lshl_add_u64 v[62:63], s[68:69], 1, v[36:37]
	v_pk_mul_f32 v[36:37], v[58:59], v[58:59]
	v_pk_mul_f32 v[38:39], v[60:61], v[60:61]
	v_pk_mul_f32 v[54:55], v[30:31], v[40:41] op_sel_hi:[1,0]
	v_pk_mov_b32 v[44:45], v[38:39], v[36:37] op_sel:[1,0]
	v_mov_b32_e32 v39, v37
	v_pk_add_f32 v[36:37], v[44:45], v[38:39]
	v_pk_mul_f32 v[56:57], v[28:29], v[40:41] op_sel_hi:[1,0]
	v_pk_add_f32 v[36:37], v[36:37], v[36:37] op_sel_hi:[0,1]
	v_pk_mul_f32 v[38:39], v[54:55], v[54:55]
	v_pk_mul_f32 v[44:45], v[56:57], v[56:57]
	v_pk_mul_f32 v[50:51], v[24:25], v[40:41] op_sel_hi:[1,0]
	v_pk_mov_b32 v[46:47], v[44:45], v[38:39] op_sel:[1,0]
	v_mov_b32_e32 v45, v39
	v_pk_mul_f32 v[48:49], v[26:27], v[40:41] op_sel_hi:[1,0]
	v_mul_f32_e32 v36, v50, v50
	v_pk_add_f32 v[38:39], v[46:47], v[44:45]
	v_pk_fma_f32 v[52:53], v[50:51], v[50:51], v[36:37] op_sel_hi:[1,1,0]
	v_mul_f32_e32 v36, v48, v48
	v_pk_add_f32 v[38:39], v[38:39], v[38:39] op_sel_hi:[0,1]
	v_pk_fma_f32 v[64:65], v[48:49], v[48:49], v[36:37] op_sel_hi:[1,1,0]
	v_pk_mul_f32 v[44:45], v[22:23], v[40:41] op_sel_hi:[1,0]
	v_pk_mul_f32 v[46:47], v[20:21], v[40:41] op_sel_hi:[1,0]
	v_mul_f32_e32 v36, v44, v44
	v_mul_f32_e32 v52, v46, v46
	v_mul_f32_e32 v64, v47, v47
	v_mul_f32_e32 v38, v45, v45
	v_pk_add_f32 v[52:53], v[52:53], v[64:65]
	v_pk_add_f32 v[36:37], v[36:37], v[38:39]
	v_and_b32_e32 v38, 64, v236
	v_pk_add_f32 v[36:37], v[52:53], v[36:37]
	v_add_u32_e32 v38, 64, v38
	v_add_f32_e32 v36, v36, v37
	v_mov_b32_e32 v37, v36
	s_nop 1
	v_permlane16_swap_b32 v37, v36
	v_lshlrev_b32_e32 v41, 2, v157
	v_lshlrev_b32_e32 v68, 1, v157
	v_mov_b32_e32 v69, v2
	v_lshl_add_u64 v[62:63], v[62:63], 0, v[68:69]
	s_waitcnt lgkmcnt(0)
	v_add_f32_e32 v36, v36, v37
	v_xor_b32_e32 v37, 32, v236
	v_cmp_lt_i32_e32 vcc, v37, v38
	s_nop 1
	v_cndmask_b32_e32 v37, v236, v37, vcc
	v_lshlrev_b32_e32 v37, 2, v37
	v_mov_b32_e32 v37, v36
	s_nop 1
	v_permlane32_swap_b32 v37, v36
	s_waitcnt lgkmcnt(0)
	v_add_f32_e32 v36, v36, v37
	v_fmamk_f32 v36, v36, 0x3c800000, v231
	v_cmp_gt_f32_e32 vcc, s11, v36
	v_mul_f32_e32 v37, 0x4b800000, v36
	s_nop 0
	v_cndmask_b32_e32 v36, v36, v37, vcc
	v_rsq_f32_e32 v36, v36
	s_nop 0
	v_mul_f32_e32 v37, 0x45800000, v36
	v_cndmask_b32_e32 v36, v36, v37, vcc
	v_mul_f32_e32 v52, 0x3e38aa3b, v36
	global_load_dwordx4 v[36:39], v41, s[36:37] offset:16
	global_load_dwordx4 v[64:67], v41, s[36:37]
	v_pk_mul_f32 v[60:61], v[60:61], v[52:53] op_sel_hi:[1,0]
	v_pk_mul_f32 v[58:59], v[58:59], v[52:53] op_sel_hi:[1,0]
	v_pk_mul_f32 v[56:57], v[56:57], v[52:53] op_sel_hi:[1,0]
	v_pk_mul_f32 v[54:55], v[54:55], v[52:53] op_sel_hi:[1,0]
	v_pk_mul_f32 v[50:51], v[50:51], v[52:53] op_sel_hi:[1,0]
	v_pk_mul_f32 v[48:49], v[48:49], v[52:53] op_sel_hi:[1,0]
	v_pk_mul_f32 v[46:47], v[46:47], v[52:53] op_sel_hi:[1,0]
	v_pk_mul_f32 v[44:45], v[44:45], v[52:53] op_sel_hi:[1,0]
	s_waitcnt vmcnt(1)
	v_pk_mul_f32 v[54:55], v[38:39], v[54:55]
	s_waitcnt vmcnt(0)
	v_pk_mul_f32 v[58:59], v[66:67], v[58:59]
	v_pk_mul_f32 v[60:61], v[64:65], v[60:61]
	v_pk_mul_f32 v[38:39], v[36:37], v[56:57]
	v_cvt_pk_bf16_f32 v36, v60, v61
	v_cvt_pk_bf16_f32 v37, v58, v59
	v_cvt_pk_bf16_f32 v38, v38, v39
	v_cvt_pk_bf16_f32 v39, v54, v55
	global_store_dwordx4 v[62:63], v[36:39], off offset:-768
	global_load_dwordx4 v[36:39], v41, s[36:37] offset:144
	s_nop 0
	global_load_dwordx4 v[54:57], v41, s[36:37] offset:128
	s_waitcnt vmcnt(1)
	v_pk_mul_f32 v[44:45], v[38:39], v[44:45]
	s_waitcnt vmcnt(0)
	v_pk_mul_f32 v[48:49], v[56:57], v[48:49]
	v_pk_mul_f32 v[50:51], v[54:55], v[50:51]
	v_pk_mul_f32 v[38:39], v[36:37], v[46:47]
	v_cvt_pk_bf16_f32 v36, v50, v51
	v_cvt_pk_bf16_f32 v37, v48, v49
	v_cvt_pk_bf16_f32 v38, v38, v39
	v_cvt_pk_bf16_f32 v39, v44, v45
	global_store_dwordx4 v[62:63], v[36:39], off offset:-704

.LBB0_621:
	s_andn2_b64 vcc, exec, s[0:1]
	s_cbranch_vccnz .LBB0_625
	v_pk_mul_f32 v[34:35], v[34:35], v[40:41] op_sel_hi:[1,0]
	v_pk_mul_f32 v[32:33], v[32:33], v[40:41] op_sel_hi:[1,0]
	v_pk_mul_f32 v[36:37], v[30:31], v[40:41] op_sel_hi:[1,0]
	v_pk_mul_f32 v[30:31], v[28:29], v[40:41] op_sel_hi:[1,0]
	v_mul_f32_e32 v28, v33, v33
	v_mul_f32_e32 v29, v35, v35
	v_fmac_f32_e32 v28, v32, v32
	v_fmac_f32_e32 v29, v34, v34
	v_add_f32_e32 v28, v28, v29
	v_mul_f32_e32 v29, v31, v31
	v_mul_f32_e32 v38, v37, v37
	v_fmac_f32_e32 v29, v30, v30
	v_fmac_f32_e32 v38, v36, v36
	v_add_f32_e32 v29, v29, v38
	v_add_f32_e32 v41, v28, v29
	v_mov_b64_e32 v[28:29], s[26:27]
	s_movk_i32 s0, 0x300
	v_mad_i64_i32 v[28:29], s[0:1], v42, s0, v[28:29]
	v_pk_mul_f32 v[26:27], v[26:27], v[40:41] op_sel_hi:[1,0]
	v_pk_mul_f32 v[24:25], v[24:25], v[40:41] op_sel_hi:[1,0]
	v_lshl_add_u64 v[38:39], v[132:133], 1, v[28:29]
	v_cvt_pk_bf16_f32 v29, v34, v35
	v_pk_mul_f32 v[34:35], v[20:21], v[40:41] op_sel_hi:[1,0]
	v_mul_f32_e32 v20, v25, v25
	v_mul_f32_e32 v21, v27, v27
	v_cvt_pk_bf16_f32 v28, v32, v33
	v_pk_mul_f32 v[32:33], v[22:23], v[40:41] op_sel_hi:[1,0]
	v_fmac_f32_e32 v20, v24, v24
	v_fmac_f32_e32 v21, v26, v26
	v_add_f32_e32 v20, v20, v21
	v_mul_f32_e32 v21, v35, v35
	v_mul_f32_e32 v22, v33, v33
	v_fmac_f32_e32 v21, v34, v34
	v_fmac_f32_e32 v22, v32, v32
	v_add_f32_e32 v21, v21, v22
	v_add_f32_e32 v20, v20, v21
	v_add_f32_e32 v20, v41, v20
	v_mov_b32_e32 v21, v20
	s_nop 1
	v_permlane16_swap_b32 v21, v20
	v_and_b32_e32 v23, 64, v236
	v_add_u32_e32 v23, 64, v23
	v_cvt_pk_bf16_f32 v30, v30, v31
	v_cvt_pk_bf16_f32 v31, v36, v37
	s_waitcnt lgkmcnt(0)
	v_add_f32_e32 v20, v20, v21
	v_xor_b32_e32 v21, 32, v236
	v_cmp_lt_i32_e32 vcc, v21, v23
	v_cvt_pk_bf16_f32 v22, v24, v25
	v_cvt_pk_bf16_f32 v23, v26, v27
	v_cndmask_b32_e32 v21, v236, v21, vcc
	v_lshlrev_b32_e32 v21, 2, v21
	v_mov_b32_e32 v21, v20
	s_nop 1
	v_permlane32_swap_b32 v21, v20
	v_cvt_pk_bf16_f32 v24, v34, v35
	v_cvt_pk_bf16_f32 v25, v32, v33
	global_store_dwordx4 v[38:39], v[28:31], off
	global_store_dwordx4 v[38:39], v[22:25], off offset:64
	s_and_saveexec_b64 s[0:1], s[16:17]
	s_cbranch_execz .LBB0_624
	s_waitcnt lgkmcnt(0)
	v_add_f32_e32 v22, v20, v21
	v_lshl_add_u64 v[20:21], v[142:143], 2, s[28:29]
	global_atomic_add_f32 v[20:21], v22, off offset:640

.LBB0_635:
	s_andn2_b64 vcc, exec, s[0:1]
	s_cbranch_vccnz .LBB0_637
	v_lshlrev_b64 v[20:21], 9, v[26:27]
	v_lshl_add_u64 v[20:21], s[30:31], 0, v[20:21]
	v_pk_mul_f32 v[42:43], v[18:19], v[24:25] op_sel_hi:[1,0]
	v_pk_mul_f32 v[44:45], v[16:17], v[24:25] op_sel_hi:[1,0]
	v_lshl_add_u64 v[46:47], s[68:69], 1, v[20:21]
	v_pk_mul_f32 v[20:21], v[42:43], v[42:43]
	v_pk_mul_f32 v[22:23], v[44:45], v[44:45]
	v_pk_mul_f32 v[38:39], v[14:15], v[24:25] op_sel_hi:[1,0]
	v_pk_mov_b32 v[28:29], v[22:23], v[20:21] op_sel:[1,0]
	v_mov_b32_e32 v23, v21
	v_pk_add_f32 v[20:21], v[28:29], v[22:23]
	v_pk_mul_f32 v[40:41], v[12:13], v[24:25] op_sel_hi:[1,0]
	v_pk_add_f32 v[20:21], v[20:21], v[20:21] op_sel_hi:[0,1]
	v_pk_mul_f32 v[22:23], v[38:39], v[38:39]
	v_pk_mul_f32 v[28:29], v[40:41], v[40:41]
	v_pk_mul_f32 v[34:35], v[8:9], v[24:25] op_sel_hi:[1,0]
	v_pk_mov_b32 v[30:31], v[28:29], v[22:23] op_sel:[1,0]
	v_mov_b32_e32 v29, v23
	v_pk_mul_f32 v[32:33], v[10:11], v[24:25] op_sel_hi:[1,0]
	v_mul_f32_e32 v20, v34, v34
	v_pk_add_f32 v[22:23], v[30:31], v[28:29]
	v_pk_fma_f32 v[36:37], v[34:35], v[34:35], v[20:21] op_sel_hi:[1,1,0]
	v_mul_f32_e32 v20, v32, v32
	v_pk_add_f32 v[22:23], v[22:23], v[22:23] op_sel_hi:[0,1]
	v_pk_fma_f32 v[48:49], v[32:33], v[32:33], v[20:21] op_sel_hi:[1,1,0]
	v_pk_mul_f32 v[28:29], v[6:7], v[24:25] op_sel_hi:[1,0]
	v_pk_mul_f32 v[30:31], v[4:5], v[24:25] op_sel_hi:[1,0]
	v_mul_f32_e32 v20, v28, v28
	v_mul_f32_e32 v36, v30, v30
	v_mul_f32_e32 v48, v31, v31
	v_mul_f32_e32 v22, v29, v29
	v_pk_add_f32 v[36:37], v[36:37], v[48:49]
	v_pk_add_f32 v[20:21], v[20:21], v[22:23]
	v_and_b32_e32 v22, 64, v236
	v_pk_add_f32 v[20:21], v[36:37], v[20:21]
	v_add_u32_e32 v22, 64, v22
	v_add_f32_e32 v20, v20, v21
	v_mov_b32_e32 v21, v20
	s_nop 1
	v_permlane16_swap_b32 v21, v20
	v_lshlrev_b32_e32 v25, 2, v157
	v_lshlrev_b32_e32 v52, 1, v157
	v_mov_b32_e32 v53, v2
	v_lshl_add_u64 v[46:47], v[46:47], 0, v[52:53]
	s_waitcnt lgkmcnt(0)
	v_add_f32_e32 v20, v20, v21
	v_xor_b32_e32 v21, 32, v236
	v_cmp_lt_i32_e32 vcc, v21, v22
	s_nop 1
	v_cndmask_b32_e32 v21, v236, v21, vcc
	v_lshlrev_b32_e32 v21, 2, v21
	v_mov_b32_e32 v21, v20
	s_nop 1
	v_permlane32_swap_b32 v21, v20
	s_waitcnt lgkmcnt(0)
	v_add_f32_e32 v20, v20, v21
	v_fmamk_f32 v20, v20, 0x3c800000, v231
	v_cmp_gt_f32_e32 vcc, s11, v20
	v_mul_f32_e32 v21, 0x4b800000, v20
	s_nop 0
	v_cndmask_b32_e32 v20, v20, v21, vcc
	v_rsq_f32_e32 v20, v20
	s_nop 0
	v_mul_f32_e32 v21, 0x45800000, v20
	v_cndmask_b32_e32 v20, v20, v21, vcc
	v_mul_f32_e32 v36, 0x3e38aa3b, v20
	global_load_dwordx4 v[20:23], v25, s[36:37] offset:16
	global_load_dwordx4 v[48:51], v25, s[36:37]
	v_pk_mul_f32 v[44:45], v[44:45], v[36:37] op_sel_hi:[1,0]
	v_pk_mul_f32 v[42:43], v[42:43], v[36:37] op_sel_hi:[1,0]
	v_pk_mul_f32 v[40:41], v[40:41], v[36:37] op_sel_hi:[1,0]
	v_pk_mul_f32 v[38:39], v[38:39], v[36:37] op_sel_hi:[1,0]
	v_pk_mul_f32 v[34:35], v[34:35], v[36:37] op_sel_hi:[1,0]
	v_pk_mul_f32 v[32:33], v[32:33], v[36:37] op_sel_hi:[1,0]
	v_pk_mul_f32 v[30:31], v[30:31], v[36:37] op_sel_hi:[1,0]
	v_pk_mul_f32 v[28:29], v[28:29], v[36:37] op_sel_hi:[1,0]
	s_waitcnt vmcnt(1)
	v_pk_mul_f32 v[38:39], v[22:23], v[38:39]
	s_waitcnt vmcnt(0)
	v_pk_mul_f32 v[42:43], v[50:51], v[42:43]
	v_pk_mul_f32 v[44:45], v[48:49], v[44:45]
	v_pk_mul_f32 v[22:23], v[20:21], v[40:41]
	v_cvt_pk_bf16_f32 v20, v44, v45
	v_cvt_pk_bf16_f32 v21, v42, v43
	v_cvt_pk_bf16_f32 v22, v22, v23
	v_cvt_pk_bf16_f32 v23, v38, v39
	global_store_dwordx4 v[46:47], v[20:23], off offset:-768
	global_load_dwordx4 v[20:23], v25, s[36:37] offset:144
	s_nop 0
	global_load_dwordx4 v[38:41], v25, s[36:37] offset:128
	s_waitcnt vmcnt(1)
	v_pk_mul_f32 v[28:29], v[22:23], v[28:29]
	s_waitcnt vmcnt(0)
	v_pk_mul_f32 v[32:33], v[40:41], v[32:33]
	v_pk_mul_f32 v[34:35], v[38:39], v[34:35]
	v_pk_mul_f32 v[22:23], v[20:21], v[30:31]
	v_cvt_pk_bf16_f32 v20, v34, v35
	v_cvt_pk_bf16_f32 v21, v32, v33
	v_cvt_pk_bf16_f32 v22, v22, v23
	v_cvt_pk_bf16_f32 v23, v28, v29
	global_store_dwordx4 v[46:47], v[20:23], off offset:-704

.LBB0_638:
	s_andn2_b64 vcc, exec, s[0:1]
	s_cbranch_vccnz .LBB0_497
	v_pk_mul_f32 v[18:19], v[18:19], v[24:25] op_sel_hi:[1,0]
	v_pk_mul_f32 v[16:17], v[16:17], v[24:25] op_sel_hi:[1,0]
	v_pk_mul_f32 v[20:21], v[14:15], v[24:25] op_sel_hi:[1,0]
	v_pk_mul_f32 v[14:15], v[12:13], v[24:25] op_sel_hi:[1,0]
	v_mul_f32_e32 v12, v17, v17
	v_mul_f32_e32 v13, v19, v19
	v_fmac_f32_e32 v12, v16, v16
	v_fmac_f32_e32 v13, v18, v18
	v_add_f32_e32 v12, v12, v13
	v_mul_f32_e32 v13, v15, v15
	v_mul_f32_e32 v22, v21, v21
	v_fmac_f32_e32 v13, v14, v14
	v_fmac_f32_e32 v22, v20, v20
	v_add_f32_e32 v13, v13, v22
	v_add_f32_e32 v25, v12, v13
	v_mov_b64_e32 v[12:13], s[26:27]
	s_movk_i32 s0, 0x300
	v_mad_i64_i32 v[12:13], s[0:1], v26, s0, v[12:13]
	v_pk_mul_f32 v[10:11], v[10:11], v[24:25] op_sel_hi:[1,0]
	v_pk_mul_f32 v[8:9], v[8:9], v[24:25] op_sel_hi:[1,0]
	v_lshl_add_u64 v[22:23], v[132:133], 1, v[12:13]
	v_cvt_pk_bf16_f32 v13, v18, v19
	v_pk_mul_f32 v[18:19], v[4:5], v[24:25] op_sel_hi:[1,0]
	v_mul_f32_e32 v4, v9, v9
	v_mul_f32_e32 v5, v11, v11
	v_cvt_pk_bf16_f32 v12, v16, v17
	v_pk_mul_f32 v[16:17], v[6:7], v[24:25] op_sel_hi:[1,0]
	v_fmac_f32_e32 v4, v8, v8
	v_fmac_f32_e32 v5, v10, v10
	v_add_f32_e32 v4, v4, v5
	v_mul_f32_e32 v5, v19, v19
	v_mul_f32_e32 v6, v17, v17
	v_fmac_f32_e32 v5, v18, v18
	v_fmac_f32_e32 v6, v16, v16
	v_add_f32_e32 v5, v5, v6
	v_add_f32_e32 v4, v4, v5
	v_add_f32_e32 v4, v25, v4
	v_mov_b32_e32 v5, v4
	s_nop 1
	v_permlane16_swap_b32 v5, v4
	v_and_b32_e32 v7, 64, v236
	v_add_u32_e32 v7, 64, v7
	v_cvt_pk_bf16_f32 v14, v14, v15
	v_cvt_pk_bf16_f32 v15, v20, v21
	s_waitcnt lgkmcnt(0)
	v_add_f32_e32 v4, v4, v5
	v_xor_b32_e32 v5, 32, v236
	v_cmp_lt_i32_e32 vcc, v5, v7
	v_cvt_pk_bf16_f32 v6, v8, v9
	v_cvt_pk_bf16_f32 v7, v10, v11
	v_cndmask_b32_e32 v5, v236, v5, vcc
	v_lshlrev_b32_e32 v5, 2, v5
	v_mov_b32_e32 v5, v4
	s_nop 1
	v_permlane32_swap_b32 v5, v4
	v_cvt_pk_bf16_f32 v8, v18, v19
	v_cvt_pk_bf16_f32 v9, v16, v17
	global_store_dwordx4 v[22:23], v[12:15], off
	global_store_dwordx4 v[22:23], v[6:9], off offset:64
	s_and_saveexec_b64 s[0:1], s[16:17]
	s_cbranch_execz .LBB0_496
	s_waitcnt lgkmcnt(0)
	v_add_f32_e32 v6, v4, v5
	v_lshl_add_u64 v[4:5], v[142:143], 2, s[28:29]
	global_atomic_add_f32 v[4:5], v6, off offset:704
	s_branch .LBB0_496

.LBB0_1019:
	s_andn2_b64 vcc, exec, s[36:37]
	s_ashr_i32 s9, s8, 31
	s_cbranch_vccnz .LBB0_1024
	v_pk_mul_f32 v[174:175], v[146:147], v[146:147]
	v_pk_mul_f32 v[176:177], v[144:145], v[144:145]
	s_nop 0
	v_pk_mov_b32 v[180:181], v[176:177], v[174:175] op_sel:[1,0]
	v_mov_b32_e32 v177, v175
	v_pk_add_f32 v[174:175], v[180:181], v[176:177]
	v_pk_mul_f32 v[176:177], v[140:141], v[140:141]
	v_pk_add_f32 v[182:183], v[174:175], v[174:175] op_sel_hi:[0,1]
	v_pk_mul_f32 v[174:175], v[142:143], v[142:143]
	s_nop 0
	v_pk_mov_b32 v[180:181], v[176:177], v[174:175] op_sel:[1,0]
	v_mov_b32_e32 v177, v175
	v_pk_add_f32 v[174:175], v[180:181], v[176:177]
	v_mov_b32_e32 v176, v137
	v_mov_b32_e32 v177, v133
	v_pk_add_f32 v[184:185], v[174:175], v[174:175] op_sel_hi:[0,1]
	v_mov_b32_e32 v174, v136
	v_mov_b32_e32 v175, v132
	v_pk_mul_f32 v[176:177], v[176:177], v[176:177]
	v_mov_b32_e32 v180, v139
	v_mov_b32_e32 v181, v135
	v_pk_fma_f32 v[174:175], v[174:175], v[174:175], v[176:177]
	v_mov_b32_e32 v176, v138
	v_mov_b32_e32 v177, v134
	v_pk_mul_f32 v[180:181], v[180:181], v[180:181]
	v_mov_b32_e32 v193, v185
	v_pk_fma_f32 v[176:177], v[176:177], v[176:177], v[180:181]
	s_waitcnt vmcnt(0)
	v_and_b32_e32 v180, 0xffff0000, v162
	v_pk_add_f32 v[174:175], v[174:175], v[176:177]
	v_lshlrev_b32_e32 v176, 16, v161
	v_pk_add_f32 v[186:187], v[174:175], v[174:175] op_sel_hi:[0,1]
	v_lshlrev_b32_e32 v174, 16, v160
	v_and_b32_e32 v175, 0xffff0000, v160
	v_mul_f32_e32 v160, v174, v174
	v_pk_fma_f32 v[188:189], v[174:175], v[174:175], v[160:161] op_sel_hi:[1,1,0]
	v_and_b32_e32 v177, 0xffff0000, v161
	v_mul_f32_e32 v160, v176, v176
	v_pk_fma_f32 v[190:191], v[176:177], v[176:177], v[160:161] op_sel_hi:[1,1,0]
	v_lshlrev_b32_e32 v160, 16, v162
	v_mov_b32_e32 v161, v183
	v_mov_b32_e32 v192, v160
	v_lshlrev_b32_e32 v162, 16, v163
	v_and_b32_e32 v163, 0xffff0000, v163
	v_pk_mul_f32 v[192:193], v[160:161], v[192:193]
	v_pk_add_f32 v[182:183], v[182:183], v[184:185]
	v_mul_f32_e32 v186, v180, v180
	v_mul_f32_e32 v188, v162, v162
	v_mul_f32_e32 v190, v163, v163
	v_mov_b32_e32 v193, v183
	v_pk_add_f32 v[182:183], v[192:193], v[186:187]
	v_pk_add_f32 v[184:185], v[188:189], v[190:191]
	v_and_b32_e32 v181, 64, v236
	v_pk_add_f32 v[182:183], v[182:183], v[184:185]
	v_add_u32_e32 v181, 64, v181
	v_add_f32_e32 v161, v182, v183
	v_mov_b32_e32 v178, v161
	s_nop 1
	v_permlane16_swap_b32 v178, v161
	s_waitcnt lgkmcnt(0)
	v_add_f32_e32 v161, v161, v178
	v_xor_b32_e32 v178, 32, v236
	v_cmp_lt_i32_e32 vcc, v178, v181
	s_nop 1
	v_cndmask_b32_e32 v178, v236, v178, vcc
	v_lshlrev_b32_e32 v178, 2, v178
	v_mov_b32_e32 v178, v161
	s_nop 1
	v_permlane32_swap_b32 v178, v161
	s_waitcnt lgkmcnt(0)
	v_add_f32_e32 v161, v161, v178
	v_fmamk_f32 v161, v161, 0x3c2aaaab, v231
	v_mul_f32_e32 v178, 0x4b800000, v161
	v_cmp_gt_f32_e32 vcc, s11, v161
	s_nop 1
	v_cndmask_b32_e32 v161, v161, v178, vcc
	v_rsq_f32_e32 v161, v161
	s_nop 0
	v_mul_f32_e32 v178, 0x45800000, v161
	v_cndmask_b32_e32 v178, v161, v178, vcc
	s_and_saveexec_b64 s[18:19], s[16:17]
	s_cbranch_execz .LBB0_1022
	v_mad_u64_u32 v[182:183], s[36:37], v172, 48, s[26:27]
	v_mov_b32_e32 v184, v183
	v_mad_u64_u32 v[184:185], s[36:37], v173, 48, v[184:185]
	v_mov_b32_e32 v183, v184
	v_lshl_add_u64 v[182:183], s[8:9], 2, v[182:183]
	global_store_dword v[182:183], v178, off

.LBB0_1028:
	s_andn2_b64 vcc, exec, s[0:1]
	s_cbranch_vccnz .LBB0_1033
	v_pk_mul_f32 v[132:133], v[126:127], v[126:127]
	v_pk_mul_f32 v[134:135], v[124:125], v[124:125]
	s_waitcnt vmcnt(0)
	v_and_b32_e32 v142, 0xffff0000, v158
	v_pk_mov_b32 v[136:137], v[134:135], v[132:133] op_sel:[1,0]
	v_mov_b32_e32 v135, v133
	v_pk_add_f32 v[132:133], v[136:137], v[134:135]
	v_pk_mul_f32 v[134:135], v[120:121], v[120:121]
	v_pk_add_f32 v[144:145], v[132:133], v[132:133] op_sel_hi:[0,1]
	v_pk_mul_f32 v[132:133], v[122:123], v[122:123]
	v_lshlrev_b32_e32 v138, 16, v159
	v_pk_mov_b32 v[136:137], v[134:135], v[132:133] op_sel:[1,0]
	v_mov_b32_e32 v135, v133
	v_pk_add_f32 v[132:133], v[136:137], v[134:135]
	v_mov_b32_e32 v134, v117
	v_mov_b32_e32 v135, v113
	v_pk_add_f32 v[146:147], v[132:133], v[132:133] op_sel_hi:[0,1]
	v_mov_b32_e32 v132, v116
	v_mov_b32_e32 v133, v112
	v_pk_mul_f32 v[134:135], v[134:135], v[134:135]
	v_mov_b32_e32 v136, v119
	v_mov_b32_e32 v137, v115
	v_pk_fma_f32 v[132:133], v[132:133], v[132:133], v[134:135]
	v_mov_b32_e32 v134, v118
	v_mov_b32_e32 v135, v114
	v_pk_mul_f32 v[136:137], v[136:137], v[136:137]
	v_and_b32_e32 v139, 0xffff0000, v159
	v_pk_fma_f32 v[134:135], v[134:135], v[134:135], v[136:137]
	v_lshlrev_b32_e32 v136, 16, v157
	v_pk_add_f32 v[132:133], v[132:133], v[134:135]
	v_and_b32_e32 v137, 0xffff0000, v157
	v_pk_add_f32 v[160:161], v[132:133], v[132:133] op_sel_hi:[0,1]
	v_lshlrev_b32_e32 v132, 16, v156
	v_and_b32_e32 v133, 0xffff0000, v156
	v_mul_f32_e32 v134, v132, v132
	v_pk_fma_f32 v[162:163], v[132:133], v[132:133], v[134:135] op_sel_hi:[1,1,0]
	v_mul_f32_e32 v134, v136, v136
	v_pk_fma_f32 v[156:157], v[136:137], v[136:137], v[134:135] op_sel_hi:[1,1,0]
	v_lshlrev_b32_e32 v134, 16, v158
	v_mov_b32_e32 v135, v145
	v_mov_b32_e32 v158, v134
	v_mov_b32_e32 v159, v147
	v_pk_mul_f32 v[158:159], v[134:135], v[158:159]
	v_pk_add_f32 v[144:145], v[144:145], v[146:147]
	v_mul_f32_e32 v160, v142, v142
	v_mul_f32_e32 v162, v138, v138
	v_mul_f32_e32 v156, v139, v139
	v_mov_b32_e32 v159, v145
	v_pk_add_f32 v[144:145], v[158:159], v[160:161]
	v_pk_add_f32 v[146:147], v[162:163], v[156:157]
	v_and_b32_e32 v143, 64, v236
	v_pk_add_f32 v[144:145], v[144:145], v[146:147]
	v_add_u32_e32 v143, 64, v143
	v_add_f32_e32 v135, v144, v145
	v_mov_b32_e32 v140, v135
	s_nop 1
	v_permlane16_swap_b32 v140, v135
	s_waitcnt lgkmcnt(0)
	v_add_f32_e32 v135, v135, v140
	v_xor_b32_e32 v140, 32, v236
	v_cmp_lt_i32_e32 vcc, v140, v143
	s_nop 1
	v_cndmask_b32_e32 v140, v236, v140, vcc
	v_lshlrev_b32_e32 v140, 2, v140
	v_mov_b32_e32 v140, v135
	s_nop 1
	v_permlane32_swap_b32 v140, v135
	s_waitcnt lgkmcnt(0)
	v_add_f32_e32 v135, v135, v140
	v_fmamk_f32 v135, v135, 0x3c2aaaab, v231
	v_mul_f32_e32 v140, 0x4b800000, v135
	v_cmp_gt_f32_e32 vcc, s11, v135
	s_nop 1
	v_cndmask_b32_e32 v135, v135, v140, vcc
	v_rsq_f32_e32 v135, v135
	s_nop 0
	v_mul_f32_e32 v140, 0x45800000, v135
	v_cndmask_b32_e32 v140, v135, v140, vcc
	s_and_saveexec_b64 s[0:1], s[16:17]
	s_cbranch_execz .LBB0_1031
	v_mad_u64_u32 v[144:145], s[36:37], v141, 48, s[26:27]
	v_mov_b32_e32 v146, v145
	v_mad_u64_u32 v[146:147], s[36:37], v173, 48, v[146:147]
	v_mov_b32_e32 v145, v146
	v_lshl_add_u64 v[144:145], s[8:9], 2, v[144:145]
	global_store_dword v[144:145], v140, off

.LBB0_1037:
	s_andn2_b64 vcc, exec, s[0:1]
	s_cbranch_vccnz .LBB0_1042
	v_pk_mul_f32 v[112:113], v[106:107], v[106:107]
	v_pk_mul_f32 v[114:115], v[104:105], v[104:105]
	s_waitcnt vmcnt(0)
	v_and_b32_e32 v122, 0xffff0000, v154
	v_pk_mov_b32 v[116:117], v[114:115], v[112:113] op_sel:[1,0]
	v_mov_b32_e32 v115, v113
	v_pk_add_f32 v[112:113], v[116:117], v[114:115]
	v_pk_mul_f32 v[114:115], v[100:101], v[100:101]
	v_pk_add_f32 v[124:125], v[112:113], v[112:113] op_sel_hi:[0,1]
	v_pk_mul_f32 v[112:113], v[102:103], v[102:103]
	v_lshlrev_b32_e32 v118, 16, v155
	v_pk_mov_b32 v[116:117], v[114:115], v[112:113] op_sel:[1,0]
	v_mov_b32_e32 v115, v113
	v_pk_add_f32 v[112:113], v[116:117], v[114:115]
	v_mov_b32_e32 v114, v97
	v_mov_b32_e32 v115, v93
	v_pk_add_f32 v[126:127], v[112:113], v[112:113] op_sel_hi:[0,1]
	v_mov_b32_e32 v112, v96
	v_mov_b32_e32 v113, v92
	v_pk_mul_f32 v[114:115], v[114:115], v[114:115]
	v_mov_b32_e32 v116, v99
	v_mov_b32_e32 v117, v95
	v_pk_fma_f32 v[112:113], v[112:113], v[112:113], v[114:115]
	v_mov_b32_e32 v114, v98
	v_mov_b32_e32 v115, v94
	v_pk_mul_f32 v[116:117], v[116:117], v[116:117]
	v_mov_b32_e32 v139, v127
	v_pk_fma_f32 v[114:115], v[114:115], v[114:115], v[116:117]
	v_lshlrev_b32_e32 v116, 16, v153
	v_pk_add_f32 v[112:113], v[112:113], v[114:115]
	v_and_b32_e32 v117, 0xffff0000, v153
	v_pk_add_f32 v[132:133], v[112:113], v[112:113] op_sel_hi:[0,1]
	v_lshlrev_b32_e32 v112, 16, v152
	v_and_b32_e32 v113, 0xffff0000, v152
	v_mul_f32_e32 v114, v112, v112
	v_pk_fma_f32 v[134:135], v[112:113], v[112:113], v[114:115] op_sel_hi:[1,1,0]
	v_mul_f32_e32 v114, v116, v116
	v_pk_fma_f32 v[136:137], v[116:117], v[116:117], v[114:115] op_sel_hi:[1,1,0]
	v_lshlrev_b32_e32 v114, 16, v154
	v_mov_b32_e32 v115, v125
	v_mov_b32_e32 v138, v114
	v_and_b32_e32 v119, 0xffff0000, v155
	v_pk_mul_f32 v[138:139], v[114:115], v[138:139]
	v_pk_add_f32 v[124:125], v[124:125], v[126:127]
	v_mul_f32_e32 v132, v122, v122
	v_mul_f32_e32 v134, v118, v118
	v_mul_f32_e32 v136, v119, v119
	v_mov_b32_e32 v139, v125
	v_pk_add_f32 v[124:125], v[138:139], v[132:133]
	v_pk_add_f32 v[126:127], v[134:135], v[136:137]
	v_and_b32_e32 v123, 64, v236
	v_pk_add_f32 v[124:125], v[124:125], v[126:127]
	v_add_u32_e32 v123, 64, v123
	v_add_f32_e32 v115, v124, v125
	v_mov_b32_e32 v120, v115
	s_nop 1
	v_permlane16_swap_b32 v120, v115
	s_waitcnt lgkmcnt(0)
	v_add_f32_e32 v115, v115, v120
	v_xor_b32_e32 v120, 32, v236
	v_cmp_lt_i32_e32 vcc, v120, v123
	s_nop 1
	v_cndmask_b32_e32 v120, v236, v120, vcc
	v_lshlrev_b32_e32 v120, 2, v120
	v_mov_b32_e32 v120, v115
	s_nop 1
	v_permlane32_swap_b32 v120, v115
	s_waitcnt lgkmcnt(0)
	v_add_f32_e32 v115, v115, v120
	v_fmamk_f32 v115, v115, 0x3c2aaaab, v231
	v_mul_f32_e32 v120, 0x4b800000, v115
	v_cmp_gt_f32_e32 vcc, s11, v115
	s_nop 1
	v_cndmask_b32_e32 v115, v115, v120, vcc
	v_rsq_f32_e32 v115, v115
	s_nop 0
	v_mul_f32_e32 v120, 0x45800000, v115
	v_cndmask_b32_e32 v120, v115, v120, vcc
	s_and_saveexec_b64 s[0:1], s[16:17]
	s_cbranch_execz .LBB0_1040
	v_mad_u64_u32 v[124:125], s[36:37], v121, 48, s[26:27]
	v_mov_b32_e32 v126, v125
	v_mad_u64_u32 v[126:127], s[36:37], v173, 48, v[126:127]
	v_mov_b32_e32 v125, v126
	v_lshl_add_u64 v[124:125], s[8:9], 2, v[124:125]
	global_store_dword v[124:125], v120, off

.LBB0_1046:
	s_andn2_b64 vcc, exec, s[0:1]
	s_cbranch_vccnz .LBB0_1051
	v_pk_mul_f32 v[92:93], v[86:87], v[86:87]
	v_pk_mul_f32 v[94:95], v[84:85], v[84:85]
	s_waitcnt vmcnt(0)
	v_and_b32_e32 v102, 0xffff0000, v150
	v_pk_mov_b32 v[96:97], v[94:95], v[92:93] op_sel:[1,0]
	v_mov_b32_e32 v95, v93
	v_pk_add_f32 v[92:93], v[96:97], v[94:95]
	v_pk_mul_f32 v[94:95], v[80:81], v[80:81]
	v_pk_add_f32 v[104:105], v[92:93], v[92:93] op_sel_hi:[0,1]
	v_pk_mul_f32 v[92:93], v[82:83], v[82:83]
	v_lshlrev_b32_e32 v98, 16, v151
	v_pk_mov_b32 v[96:97], v[94:95], v[92:93] op_sel:[1,0]
	v_mov_b32_e32 v95, v93
	v_pk_add_f32 v[92:93], v[96:97], v[94:95]
	v_mov_b32_e32 v94, v77
	v_mov_b32_e32 v95, v73
	v_pk_add_f32 v[106:107], v[92:93], v[92:93] op_sel_hi:[0,1]
	v_mov_b32_e32 v92, v76
	v_mov_b32_e32 v93, v72
	v_pk_mul_f32 v[94:95], v[94:95], v[94:95]
	v_mov_b32_e32 v96, v79
	v_mov_b32_e32 v97, v75
	v_pk_fma_f32 v[92:93], v[92:93], v[92:93], v[94:95]
	v_mov_b32_e32 v94, v78
	v_mov_b32_e32 v95, v74
	v_pk_mul_f32 v[96:97], v[96:97], v[96:97]
	v_mov_b32_e32 v119, v107
	v_pk_fma_f32 v[94:95], v[94:95], v[94:95], v[96:97]
	v_lshlrev_b32_e32 v96, 16, v149
	v_pk_add_f32 v[92:93], v[92:93], v[94:95]
	v_and_b32_e32 v97, 0xffff0000, v149
	v_pk_add_f32 v[112:113], v[92:93], v[92:93] op_sel_hi:[0,1]
	v_lshlrev_b32_e32 v92, 16, v148
	v_and_b32_e32 v93, 0xffff0000, v148
	v_mul_f32_e32 v94, v92, v92
	v_pk_fma_f32 v[114:115], v[92:93], v[92:93], v[94:95] op_sel_hi:[1,1,0]
	v_mul_f32_e32 v94, v96, v96
	v_pk_fma_f32 v[116:117], v[96:97], v[96:97], v[94:95] op_sel_hi:[1,1,0]
	v_lshlrev_b32_e32 v94, 16, v150
	v_mov_b32_e32 v95, v105
	v_mov_b32_e32 v118, v94
	v_and_b32_e32 v99, 0xffff0000, v151
	v_pk_mul_f32 v[118:119], v[94:95], v[118:119]
	v_pk_add_f32 v[104:105], v[104:105], v[106:107]
	v_mul_f32_e32 v112, v102, v102
	v_mul_f32_e32 v114, v98, v98
	v_mul_f32_e32 v116, v99, v99
	v_mov_b32_e32 v119, v105
	v_pk_add_f32 v[104:105], v[118:119], v[112:113]
	v_pk_add_f32 v[106:107], v[114:115], v[116:117]
	v_and_b32_e32 v103, 64, v236
	v_pk_add_f32 v[104:105], v[104:105], v[106:107]
	v_add_u32_e32 v103, 64, v103
	v_add_f32_e32 v95, v104, v105
	v_mov_b32_e32 v100, v95
	s_nop 1
	v_permlane16_swap_b32 v100, v95
	s_waitcnt lgkmcnt(0)
	v_add_f32_e32 v95, v95, v100
	v_xor_b32_e32 v100, 32, v236
	v_cmp_lt_i32_e32 vcc, v100, v103
	s_nop 1
	v_cndmask_b32_e32 v100, v236, v100, vcc
	v_lshlrev_b32_e32 v100, 2, v100
	v_mov_b32_e32 v100, v95
	s_nop 1
	v_permlane32_swap_b32 v100, v95
	s_waitcnt lgkmcnt(0)
	v_add_f32_e32 v95, v95, v100
	v_fmamk_f32 v95, v95, 0x3c2aaaab, v231
	v_mul_f32_e32 v100, 0x4b800000, v95
	v_cmp_gt_f32_e32 vcc, s11, v95
	s_nop 1
	v_cndmask_b32_e32 v95, v95, v100, vcc
	v_rsq_f32_e32 v95, v95
	s_nop 0
	v_mul_f32_e32 v100, 0x45800000, v95
	v_cndmask_b32_e32 v100, v95, v100, vcc
	s_and_saveexec_b64 s[0:1], s[16:17]
	s_cbranch_execz .LBB0_1049
	v_mad_u64_u32 v[104:105], s[36:37], v101, 48, s[26:27]
	v_mov_b32_e32 v106, v105
	v_mad_u64_u32 v[106:107], s[36:37], v173, 48, v[106:107]
	v_mov_b32_e32 v105, v106
	v_lshl_add_u64 v[104:105], s[8:9], 2, v[104:105]
	global_store_dword v[104:105], v100, off

.LBB0_1055:
	s_andn2_b64 vcc, exec, s[0:1]
	s_cbranch_vccnz .LBB0_1061
	v_pk_mul_f32 v[74:75], v[66:67], v[66:67]
	v_pk_mul_f32 v[76:77], v[64:65], v[64:65]
	s_waitcnt vmcnt(0)
	v_and_b32_e32 v83, 0xffff0000, v130
	v_pk_mov_b32 v[78:79], v[76:77], v[74:75] op_sel:[1,0]
	v_mov_b32_e32 v77, v75
	v_pk_add_f32 v[74:75], v[78:79], v[76:77]
	v_pk_mul_f32 v[76:77], v[60:61], v[60:61]
	v_pk_add_f32 v[84:85], v[74:75], v[74:75] op_sel_hi:[0,1]
	v_pk_mul_f32 v[74:75], v[62:63], v[62:63]
	v_lshlrev_b32_e32 v80, 16, v131
	v_pk_mov_b32 v[78:79], v[76:77], v[74:75] op_sel:[1,0]
	v_mov_b32_e32 v77, v75
	v_pk_add_f32 v[74:75], v[78:79], v[76:77]
	v_mov_b32_e32 v76, v57
	v_mov_b32_e32 v77, v53
	v_pk_add_f32 v[86:87], v[74:75], v[74:75] op_sel_hi:[0,1]
	v_mov_b32_e32 v74, v56
	v_mov_b32_e32 v75, v52
	v_pk_mul_f32 v[76:77], v[76:77], v[76:77]
	v_mov_b32_e32 v78, v59
	v_mov_b32_e32 v79, v55
	v_pk_fma_f32 v[74:75], v[74:75], v[74:75], v[76:77]
	v_mov_b32_e32 v76, v58
	v_mov_b32_e32 v77, v54
	v_pk_mul_f32 v[78:79], v[78:79], v[78:79]
	v_mov_b32_e32 v99, v87
	v_pk_fma_f32 v[76:77], v[76:77], v[76:77], v[78:79]
	v_lshlrev_b32_e32 v78, 16, v129
	v_pk_add_f32 v[74:75], v[74:75], v[76:77]
	v_and_b32_e32 v79, 0xffff0000, v129
	v_pk_add_f32 v[92:93], v[74:75], v[74:75] op_sel_hi:[0,1]
	v_lshlrev_b32_e32 v74, 16, v128
	v_and_b32_e32 v75, 0xffff0000, v128
	v_mul_f32_e32 v76, v74, v74
	v_pk_fma_f32 v[94:95], v[74:75], v[74:75], v[76:77] op_sel_hi:[1,1,0]
	v_mul_f32_e32 v76, v78, v78
	v_pk_fma_f32 v[96:97], v[78:79], v[78:79], v[76:77] op_sel_hi:[1,1,0]
	v_lshlrev_b32_e32 v76, 16, v130
	v_mov_b32_e32 v77, v85
	v_mov_b32_e32 v98, v76
	v_and_b32_e32 v81, 0xffff0000, v131
	v_pk_mul_f32 v[98:99], v[76:77], v[98:99]
	v_pk_add_f32 v[84:85], v[84:85], v[86:87]
	v_mul_f32_e32 v92, v83, v83
	v_mul_f32_e32 v94, v80, v80
	v_mul_f32_e32 v96, v81, v81
	v_mov_b32_e32 v99, v85
	v_pk_add_f32 v[84:85], v[98:99], v[92:93]
	v_pk_add_f32 v[86:87], v[94:95], v[96:97]
	s_nop 0
	v_pk_add_f32 v[84:85], v[84:85], v[86:87]
	s_nop 0
	v_add_f32_e32 v77, v84, v85
	v_mov_b32_e32 v82, v77
	s_nop 1
	v_permlane16_swap_b32 v82, v77
	v_and_b32_e32 v84, 64, v236
	v_add_u32_e32 v84, 64, v84
	s_waitcnt lgkmcnt(0)
	v_add_f32_e32 v77, v77, v82
	v_xor_b32_e32 v82, 32, v236
	v_cmp_lt_i32_e32 vcc, v82, v84
	s_nop 1
	v_cndmask_b32_e32 v82, v236, v82, vcc
	v_lshlrev_b32_e32 v82, 2, v82
	v_mov_b32_e32 v82, v77
	s_nop 1
	v_permlane32_swap_b32 v82, v77
	s_waitcnt lgkmcnt(0)
	v_add_f32_e32 v77, v77, v82
	v_fmamk_f32 v77, v77, 0x3c2aaaab, v231
	v_mul_f32_e32 v82, 0x4b800000, v77
	v_cmp_gt_f32_e32 vcc, s11, v77
	s_nop 1
	v_cndmask_b32_e32 v77, v77, v82, vcc
	v_rsq_f32_e32 v77, v77
	s_nop 0
	v_mul_f32_e32 v82, 0x45800000, v77
	v_cndmask_b32_e32 v82, v77, v82, vcc
	s_and_saveexec_b64 s[0:1], s[16:17]
	s_cbranch_execz .LBB0_1058
	v_mad_u64_u32 v[84:85], s[20:21], v72, 48, s[26:27]
	v_mov_b32_e32 v86, v85
	v_mad_u64_u32 v[86:87], s[20:21], v73, 48, v[86:87]
	v_mov_b32_e32 v85, v86
	v_lshl_add_u64 v[84:85], s[8:9], 2, v[84:85]
	global_store_dword v[84:85], v82, off

.LBB0_1065:
	s_andn2_b64 vcc, exec, s[0:1]
	s_cbranch_vccnz .LBB0_1071
	v_pk_mul_f32 v[54:55], v[50:51], v[50:51]
	v_pk_mul_f32 v[56:57], v[48:49], v[48:49]
	s_waitcnt vmcnt(0)
	v_and_b32_e32 v63, 0xffff0000, v110
	v_pk_mov_b32 v[58:59], v[56:57], v[54:55] op_sel:[1,0]
	v_mov_b32_e32 v57, v55
	v_pk_add_f32 v[54:55], v[58:59], v[56:57]
	v_pk_mul_f32 v[56:57], v[44:45], v[44:45]
	v_pk_add_f32 v[64:65], v[54:55], v[54:55] op_sel_hi:[0,1]
	v_pk_mul_f32 v[54:55], v[46:47], v[46:47]
	v_lshlrev_b32_e32 v60, 16, v111
	v_pk_mov_b32 v[58:59], v[56:57], v[54:55] op_sel:[1,0]
	v_mov_b32_e32 v57, v55
	v_pk_add_f32 v[54:55], v[58:59], v[56:57]
	v_mov_b32_e32 v56, v41
	v_mov_b32_e32 v57, v37
	v_pk_add_f32 v[66:67], v[54:55], v[54:55] op_sel_hi:[0,1]
	v_mov_b32_e32 v54, v40
	v_mov_b32_e32 v55, v36
	v_pk_mul_f32 v[56:57], v[56:57], v[56:57]
	v_mov_b32_e32 v58, v43
	v_mov_b32_e32 v59, v39
	v_pk_fma_f32 v[54:55], v[54:55], v[54:55], v[56:57]
	v_mov_b32_e32 v56, v42
	v_mov_b32_e32 v57, v38
	v_pk_mul_f32 v[58:59], v[58:59], v[58:59]
	v_mov_b32_e32 v79, v67
	v_pk_fma_f32 v[56:57], v[56:57], v[56:57], v[58:59]
	v_lshlrev_b32_e32 v58, 16, v109
	v_pk_add_f32 v[54:55], v[54:55], v[56:57]
	v_and_b32_e32 v59, 0xffff0000, v109
	v_pk_add_f32 v[72:73], v[54:55], v[54:55] op_sel_hi:[0,1]
	v_lshlrev_b32_e32 v54, 16, v108
	v_and_b32_e32 v55, 0xffff0000, v108
	v_mul_f32_e32 v56, v54, v54
	v_pk_fma_f32 v[74:75], v[54:55], v[54:55], v[56:57] op_sel_hi:[1,1,0]
	v_mul_f32_e32 v56, v58, v58
	v_pk_fma_f32 v[76:77], v[58:59], v[58:59], v[56:57] op_sel_hi:[1,1,0]
	v_lshlrev_b32_e32 v56, 16, v110
	v_mov_b32_e32 v57, v65
	v_mov_b32_e32 v78, v56
	v_and_b32_e32 v61, 0xffff0000, v111
	v_pk_mul_f32 v[78:79], v[56:57], v[78:79]
	v_pk_add_f32 v[64:65], v[64:65], v[66:67]
	v_mul_f32_e32 v72, v63, v63
	v_mul_f32_e32 v74, v60, v60
	v_mul_f32_e32 v76, v61, v61
	v_mov_b32_e32 v79, v65
	v_pk_add_f32 v[64:65], v[78:79], v[72:73]
	v_pk_add_f32 v[66:67], v[74:75], v[76:77]
	s_nop 0
	v_pk_add_f32 v[64:65], v[64:65], v[66:67]
	s_nop 0
	v_add_f32_e32 v57, v64, v65
	v_mov_b32_e32 v62, v57
	s_nop 1
	v_permlane16_swap_b32 v62, v57
	v_and_b32_e32 v64, 64, v236
	v_add_u32_e32 v64, 64, v64
	s_waitcnt lgkmcnt(0)
	v_add_f32_e32 v57, v57, v62
	v_xor_b32_e32 v62, 32, v236
	v_cmp_lt_i32_e32 vcc, v62, v64
	s_nop 1
	v_cndmask_b32_e32 v62, v236, v62, vcc
	v_lshlrev_b32_e32 v62, 2, v62
	v_mov_b32_e32 v62, v57
	s_nop 1
	v_permlane32_swap_b32 v62, v57
	s_waitcnt lgkmcnt(0)
	v_add_f32_e32 v57, v57, v62
	v_fmamk_f32 v57, v57, 0x3c2aaaab, v231
	v_mul_f32_e32 v62, 0x4b800000, v57
	v_cmp_gt_f32_e32 vcc, s11, v57
	s_nop 1
	v_cndmask_b32_e32 v57, v57, v62, vcc
	v_rsq_f32_e32 v57, v57
	s_nop 0
	v_mul_f32_e32 v62, 0x45800000, v57
	v_cndmask_b32_e32 v62, v57, v62, vcc
	s_and_saveexec_b64 s[0:1], s[16:17]
	s_cbranch_execz .LBB0_1068
	v_mad_u64_u32 v[64:65], s[20:21], v52, 48, s[26:27]
	v_mov_b32_e32 v66, v65
	v_mad_u64_u32 v[66:67], s[20:21], v53, 48, v[66:67]
	v_mov_b32_e32 v65, v66
	v_lshl_add_u64 v[64:65], s[8:9], 2, v[64:65]
	global_store_dword v[64:65], v62, off

.LBB0_1075:
	s_andn2_b64 vcc, exec, s[0:1]
	s_cbranch_vccnz .LBB0_1081
	v_pk_mul_f32 v[38:39], v[34:35], v[34:35]
	v_pk_mul_f32 v[40:41], v[32:33], v[32:33]
	s_waitcnt vmcnt(0)
	v_and_b32_e32 v47, 0xffff0000, v90
	v_pk_mov_b32 v[42:43], v[40:41], v[38:39] op_sel:[1,0]
	v_mov_b32_e32 v41, v39
	v_pk_add_f32 v[38:39], v[42:43], v[40:41]
	v_pk_mul_f32 v[40:41], v[28:29], v[28:29]
	v_pk_add_f32 v[48:49], v[38:39], v[38:39] op_sel_hi:[0,1]
	v_pk_mul_f32 v[38:39], v[30:31], v[30:31]
	v_lshlrev_b32_e32 v44, 16, v91
	v_pk_mov_b32 v[42:43], v[40:41], v[38:39] op_sel:[1,0]
	v_mov_b32_e32 v41, v39
	v_pk_add_f32 v[38:39], v[42:43], v[40:41]
	v_mov_b32_e32 v40, v25
	v_mov_b32_e32 v41, v21
	v_pk_add_f32 v[50:51], v[38:39], v[38:39] op_sel_hi:[0,1]
	v_mov_b32_e32 v38, v24
	v_mov_b32_e32 v39, v20
	v_pk_mul_f32 v[40:41], v[40:41], v[40:41]
	v_mov_b32_e32 v42, v27
	v_mov_b32_e32 v43, v23
	v_pk_fma_f32 v[38:39], v[38:39], v[38:39], v[40:41]
	v_mov_b32_e32 v40, v26
	v_mov_b32_e32 v41, v22
	v_pk_mul_f32 v[42:43], v[42:43], v[42:43]
	v_mov_b32_e32 v59, v51
	v_pk_fma_f32 v[40:41], v[40:41], v[40:41], v[42:43]
	v_lshlrev_b32_e32 v42, 16, v89
	v_pk_add_f32 v[38:39], v[38:39], v[40:41]
	v_and_b32_e32 v43, 0xffff0000, v89
	v_pk_add_f32 v[52:53], v[38:39], v[38:39] op_sel_hi:[0,1]
	v_lshlrev_b32_e32 v38, 16, v88
	v_and_b32_e32 v39, 0xffff0000, v88
	v_mul_f32_e32 v40, v38, v38
	v_pk_fma_f32 v[54:55], v[38:39], v[38:39], v[40:41] op_sel_hi:[1,1,0]
	v_mul_f32_e32 v40, v42, v42
	v_pk_fma_f32 v[56:57], v[42:43], v[42:43], v[40:41] op_sel_hi:[1,1,0]
	v_lshlrev_b32_e32 v40, 16, v90
	v_mov_b32_e32 v41, v49
	v_mov_b32_e32 v58, v40
	v_and_b32_e32 v45, 0xffff0000, v91
	v_pk_mul_f32 v[58:59], v[40:41], v[58:59]
	v_pk_add_f32 v[48:49], v[48:49], v[50:51]
	v_mul_f32_e32 v52, v47, v47
	v_mul_f32_e32 v54, v44, v44
	v_mul_f32_e32 v56, v45, v45
	v_mov_b32_e32 v59, v49
	v_pk_add_f32 v[48:49], v[58:59], v[52:53]
	v_pk_add_f32 v[50:51], v[54:55], v[56:57]
	s_nop 0
	v_pk_add_f32 v[48:49], v[48:49], v[50:51]
	s_nop 0
	v_add_f32_e32 v41, v48, v49
	v_mov_b32_e32 v46, v41
	s_nop 1
	v_permlane16_swap_b32 v46, v41
	v_and_b32_e32 v48, 64, v236
	v_add_u32_e32 v48, 64, v48
	s_waitcnt lgkmcnt(0)
	v_add_f32_e32 v41, v41, v46
	v_xor_b32_e32 v46, 32, v236
	v_cmp_lt_i32_e32 vcc, v46, v48
	s_nop 1
	v_cndmask_b32_e32 v46, v236, v46, vcc
	v_lshlrev_b32_e32 v46, 2, v46
	v_mov_b32_e32 v46, v41
	s_nop 1
	v_permlane32_swap_b32 v46, v41
	s_waitcnt lgkmcnt(0)
	v_add_f32_e32 v41, v41, v46
	v_fmamk_f32 v41, v41, 0x3c2aaaab, v231
	v_mul_f32_e32 v46, 0x4b800000, v41
	v_cmp_gt_f32_e32 vcc, s11, v41
	s_nop 1
	v_cndmask_b32_e32 v41, v41, v46, vcc
	v_rsq_f32_e32 v41, v41
	s_nop 0
	v_mul_f32_e32 v46, 0x45800000, v41
	v_cndmask_b32_e32 v46, v41, v46, vcc
	s_and_saveexec_b64 s[0:1], s[16:17]
	s_cbranch_execz .LBB0_1078
	v_mad_u64_u32 v[48:49], s[20:21], v36, 48, s[26:27]
	v_mov_b32_e32 v50, v49
	v_mad_u64_u32 v[50:51], s[20:21], v37, 48, v[50:51]
	v_mov_b32_e32 v49, v50
	v_lshl_add_u64 v[48:49], s[8:9], 2, v[48:49]
	global_store_dword v[48:49], v46, off

.LBB0_1085:
	s_andn2_b64 vcc, exec, s[0:1]
	s_cbranch_vccnz .LBB0_1002
	v_pk_mul_f32 v[22:23], v[18:19], v[18:19]
	v_pk_mul_f32 v[24:25], v[16:17], v[16:17]
	s_waitcnt vmcnt(0)
	v_and_b32_e32 v31, 0xffff0000, v70
	v_pk_mov_b32 v[26:27], v[24:25], v[22:23] op_sel:[1,0]
	v_mov_b32_e32 v25, v23
	v_pk_add_f32 v[22:23], v[26:27], v[24:25]
	v_pk_mul_f32 v[24:25], v[12:13], v[12:13]
	v_pk_add_f32 v[32:33], v[22:23], v[22:23] op_sel_hi:[0,1]
	v_pk_mul_f32 v[22:23], v[14:15], v[14:15]
	v_lshlrev_b32_e32 v28, 16, v71
	v_pk_mov_b32 v[26:27], v[24:25], v[22:23] op_sel:[1,0]
	v_mov_b32_e32 v25, v23
	v_pk_add_f32 v[22:23], v[26:27], v[24:25]
	v_mov_b32_e32 v24, v9
	v_mov_b32_e32 v25, v5
	v_pk_add_f32 v[34:35], v[22:23], v[22:23] op_sel_hi:[0,1]
	v_mov_b32_e32 v22, v8
	v_mov_b32_e32 v23, v4
	v_pk_mul_f32 v[24:25], v[24:25], v[24:25]
	v_mov_b32_e32 v26, v11
	v_mov_b32_e32 v27, v7
	v_pk_fma_f32 v[22:23], v[22:23], v[22:23], v[24:25]
	v_mov_b32_e32 v24, v10
	v_mov_b32_e32 v25, v6
	v_pk_mul_f32 v[26:27], v[26:27], v[26:27]
	v_mov_b32_e32 v43, v35
	v_pk_fma_f32 v[24:25], v[24:25], v[24:25], v[26:27]
	v_lshlrev_b32_e32 v26, 16, v69
	v_pk_add_f32 v[22:23], v[22:23], v[24:25]
	v_and_b32_e32 v27, 0xffff0000, v69
	v_pk_add_f32 v[36:37], v[22:23], v[22:23] op_sel_hi:[0,1]
	v_lshlrev_b32_e32 v22, 16, v68
	v_and_b32_e32 v23, 0xffff0000, v68
	v_mul_f32_e32 v24, v22, v22
	v_pk_fma_f32 v[38:39], v[22:23], v[22:23], v[24:25] op_sel_hi:[1,1,0]
	v_mul_f32_e32 v24, v26, v26
	v_pk_fma_f32 v[40:41], v[26:27], v[26:27], v[24:25] op_sel_hi:[1,1,0]
	v_lshlrev_b32_e32 v24, 16, v70
	v_mov_b32_e32 v25, v33
	v_mov_b32_e32 v42, v24
	v_and_b32_e32 v29, 0xffff0000, v71
	v_pk_mul_f32 v[42:43], v[24:25], v[42:43]
	v_pk_add_f32 v[32:33], v[32:33], v[34:35]
	v_mul_f32_e32 v36, v31, v31
	v_mul_f32_e32 v38, v28, v28
	v_mul_f32_e32 v40, v29, v29
	v_mov_b32_e32 v43, v33
	v_pk_add_f32 v[32:33], v[42:43], v[36:37]
	v_pk_add_f32 v[34:35], v[38:39], v[40:41]
	s_nop 0
	v_pk_add_f32 v[32:33], v[32:33], v[34:35]
	s_nop 0
	v_add_f32_e32 v25, v32, v33
	v_mov_b32_e32 v30, v25
	s_nop 1
	v_permlane16_swap_b32 v30, v25
	v_and_b32_e32 v32, 64, v236
	v_add_u32_e32 v32, 64, v32
	s_waitcnt lgkmcnt(0)
	v_add_f32_e32 v25, v25, v30
	v_xor_b32_e32 v30, 32, v236
	v_cmp_lt_i32_e32 vcc, v30, v32
	s_nop 1
	v_cndmask_b32_e32 v30, v236, v30, vcc
	v_lshlrev_b32_e32 v30, 2, v30
	v_mov_b32_e32 v30, v25
	s_nop 1
	v_permlane32_swap_b32 v30, v25
	s_waitcnt lgkmcnt(0)
	v_add_f32_e32 v25, v25, v30
	v_fmamk_f32 v25, v25, 0x3c2aaaab, v231
	v_mul_f32_e32 v30, 0x4b800000, v25
	v_cmp_gt_f32_e32 vcc, s11, v25
	s_nop 1
	v_cndmask_b32_e32 v25, v25, v30, vcc
	v_rsq_f32_e32 v25, v25
	s_nop 0
	v_mul_f32_e32 v30, 0x45800000, v25
	v_cndmask_b32_e32 v30, v25, v30, vcc
	s_and_saveexec_b64 s[0:1], s[16:17]
	s_cbranch_execz .LBB0_1088
	v_mad_u64_u32 v[32:33], s[16:17], v20, 48, s[26:27]
	v_mov_b32_e32 v34, v33
	v_mad_u64_u32 v[34:35], s[16:17], v21, 48, v[34:35]
	v_mov_b32_e32 v33, v34
	v_lshl_add_u64 v[32:33], s[8:9], 2, v[32:33]
	global_store_dword v[32:33], v30, off

.LBB0_1765:
	s_add_u32 s8, s0, 0x100
	s_addc_u32 s9, s1, 0
	s_cmp_eq_u32 s80, 12
	s_cselect_b32 s46, s65, s8
	s_cselect_b32 s47, s41, s9
	s_cselect_b32 s14, s67, s68
	s_cselect_b32 s15, s39, s79
	s_add_u32 s18, s46, 0x80
	s_addc_u32 s19, s47, 0
	s_add_i32 s81, 0, 0x10000
	v_add_u32_e32 v148, s81, v1
	ds_read_b128 v[132:135], v148
	ds_read_b128 v[140:143], v148 offset:1024
	ds_read_b128 v[144:147], v148 offset:2048
	ds_read_b128 v[148:151], v148 offset:3072
	s_add_u32 s0, s0, 0x40080
	s_addc_u32 s1, s1, 0
	ds_read_b128 v[152:155], v3
	ds_read_b128 v[156:159], v3 offset:1024
	ds_read_b128 v[160:163], v3 offset:2048
	ds_read_b128 v[164:167], v3 offset:3072
	ds_read_b128 v[168:171], v3 offset:4096
	ds_read_b128 v[172:175], v3 offset:5120
	ds_read_b128 v[176:179], v3 offset:6144
	ds_read_b128 v[180:183], v3 offset:7168
	s_add_i32 m0, s57, 0xc000
	s_nop 0
	global_load_lds_dwordx4 v138, s[0:1]
	s_add_i32 m0, s57, 0xe000
	s_nop 0
	global_load_lds_dwordx4 v136, s[0:1]
	s_waitcnt lgkmcnt(8)
	s_barrier
	s_waitcnt lgkmcnt(0)
	s_setprio 1
	s_waitcnt lgkmcnt(0)
	v_mfma_f32_16x16x32_bf16 v[128:131], v[132:135], v[152:155], v[128:131]
	v_mfma_f32_16x16x32_bf16 v[124:127], v[144:147], v[152:155], v[124:127]
	v_mfma_f32_16x16x32_bf16 v[112:115], v[132:135], v[160:163], v[112:115]
	v_mfma_f32_16x16x32_bf16 v[108:111], v[144:147], v[160:163], v[108:111]
	v_mfma_f32_16x16x32_bf16 v[96:99], v[132:135], v[168:171], v[96:99]
	v_mfma_f32_16x16x32_bf16 v[92:95], v[144:147], v[168:171], v[92:95]
	v_mfma_f32_16x16x32_bf16 v[80:83], v[132:135], v[176:179], v[80:83]
	v_mfma_f32_16x16x32_bf16 v[76:79], v[144:147], v[176:179], v[76:79]
	v_mfma_f32_16x16x32_bf16 v[128:131], v[140:143], v[156:159], v[128:131]
	v_mfma_f32_16x16x32_bf16 v[124:127], v[148:151], v[156:159], v[124:127]
	v_mfma_f32_16x16x32_bf16 v[112:115], v[140:143], v[164:167], v[112:115]
	v_mfma_f32_16x16x32_bf16 v[108:111], v[148:151], v[164:167], v[108:111]
	v_mfma_f32_16x16x32_bf16 v[96:99], v[140:143], v[172:175], v[96:99]
	v_mfma_f32_16x16x32_bf16 v[92:95], v[148:151], v[172:175], v[92:95]
	v_mfma_f32_16x16x32_bf16 v[80:83], v[140:143], v[180:183], v[80:83]
	v_mfma_f32_16x16x32_bf16 v[76:79], v[148:151], v[180:183], v[76:79]
	s_setprio 0
	s_barrier
	s_add_i32 s82, 0, 0x14000
	v_add_u32_e32 v210, s82, v1
	s_mov_b64 s[0:1], s[14:15]
	s_add_i32 s81, s81, s56
	ds_read_b128 v[184:187], v210
	ds_read_b128 v[188:191], v210 offset:1024
	ds_read_b128 v[192:195], v210 offset:2048
	ds_read_b128 v[210:213], v210 offset:3072
	s_mov_b32 m0, s81
	s_nop 0
	global_load_lds_dwordx4 v138, s[0:1]
	s_add_i32 m0, s81, 0x2000
	s_nop 0
	global_load_lds_dwordx4 v136, s[0:1]
	s_barrier
	s_waitcnt lgkmcnt(0)
	s_setprio 1
	s_waitcnt lgkmcnt(0)
	v_mfma_f32_16x16x32_bf16 v[120:123], v[184:187], v[152:155], v[120:123]
	v_mfma_f32_16x16x32_bf16 v[116:119], v[192:195], v[152:155], v[116:119]
	v_mfma_f32_16x16x32_bf16 v[104:107], v[184:187], v[160:163], v[104:107]
	v_mfma_f32_16x16x32_bf16 v[100:103], v[192:195], v[160:163], v[100:103]
	v_mfma_f32_16x16x32_bf16 v[88:91], v[184:187], v[168:171], v[88:91]
	v_mfma_f32_16x16x32_bf16 v[84:87], v[192:195], v[168:171], v[84:87]
	v_mfma_f32_16x16x32_bf16 v[72:75], v[184:187], v[176:179], v[72:75]
	v_mfma_f32_16x16x32_bf16 v[68:71], v[192:195], v[176:179], v[68:71]
	v_mfma_f32_16x16x32_bf16 v[120:123], v[188:191], v[156:159], v[120:123]
	v_mfma_f32_16x16x32_bf16 v[116:119], v[210:213], v[156:159], v[116:119]
	v_mfma_f32_16x16x32_bf16 v[104:107], v[188:191], v[164:167], v[104:107]
	v_mfma_f32_16x16x32_bf16 v[100:103], v[210:213], v[164:167], v[100:103]
	v_mfma_f32_16x16x32_bf16 v[88:91], v[188:191], v[172:175], v[88:91]
	v_mfma_f32_16x16x32_bf16 v[84:87], v[210:213], v[172:175], v[84:87]
	v_mfma_f32_16x16x32_bf16 v[72:75], v[188:191], v[180:183], v[72:75]
	v_mfma_f32_16x16x32_bf16 v[68:71], v[210:213], v[180:183], v[68:71]
	s_setprio 0
	s_mov_b64 s[0:1], s[46:47]
	s_mov_b32 m0, s57
	s_barrier
	ds_read_b128 v[152:155], v3 offset:16384
	ds_read_b128 v[156:159], v3 offset:17408
	ds_read_b128 v[160:163], v3 offset:18432
	ds_read_b128 v[164:167], v3 offset:19456
	ds_read_b128 v[168:171], v3 offset:20480
	ds_read_b128 v[172:175], v3 offset:21504
	ds_read_b128 v[176:179], v3 offset:22528
	ds_read_b128 v[180:183], v3 offset:23552
	s_nop 0
	global_load_lds_dwordx4 v138, s[0:1]
	s_mov_b32 m0, s62
	s_nop 0
	global_load_lds_dwordx4 v136, s[0:1]
	s_barrier
	s_waitcnt lgkmcnt(0)
	s_setprio 1
	s_waitcnt lgkmcnt(0)
	v_mfma_f32_16x16x32_bf16 v[64:67], v[132:135], v[152:155], v[64:67]
	v_mfma_f32_16x16x32_bf16 v[60:63], v[144:147], v[152:155], v[60:63]
	v_mfma_f32_16x16x32_bf16 v[48:51], v[132:135], v[160:163], v[48:51]
	v_mfma_f32_16x16x32_bf16 v[44:47], v[144:147], v[160:163], v[44:47]
	v_mfma_f32_16x16x32_bf16 v[32:35], v[132:135], v[168:171], v[32:35]
	v_mfma_f32_16x16x32_bf16 v[28:31], v[144:147], v[168:171], v[28:31]
	v_mfma_f32_16x16x32_bf16 v[16:19], v[132:135], v[176:179], v[16:19]
	v_mfma_f32_16x16x32_bf16 v[12:15], v[144:147], v[176:179], v[12:15]
	v_mfma_f32_16x16x32_bf16 v[64:67], v[140:143], v[156:159], v[64:67]
	v_mfma_f32_16x16x32_bf16 v[60:63], v[148:151], v[156:159], v[60:63]
	v_mfma_f32_16x16x32_bf16 v[48:51], v[140:143], v[164:167], v[48:51]
	v_mfma_f32_16x16x32_bf16 v[44:47], v[148:151], v[164:167], v[44:47]
	v_mfma_f32_16x16x32_bf16 v[32:35], v[140:143], v[172:175], v[32:35]
	v_mfma_f32_16x16x32_bf16 v[28:31], v[148:151], v[172:175], v[28:31]
	v_mfma_f32_16x16x32_bf16 v[16:19], v[140:143], v[180:183], v[16:19]
	v_mfma_f32_16x16x32_bf16 v[12:15], v[148:151], v[180:183], v[12:15]
	s_setprio 0
	s_barrier
	s_add_u32 s0, s14, 0x40000
	s_addc_u32 s1, s15, 0
	s_add_i32 s81, s82, s56
	s_mov_b32 m0, s81
	s_nop 0
	global_load_lds_dwordx4 v138, s[0:1]
	s_add_i32 m0, s81, 0x2000
	s_nop 0
	global_load_lds_dwordx4 v136, s[0:1]
	s_waitcnt vmcnt(6)
	s_barrier
	s_setprio 1
	v_mfma_f32_16x16x32_bf16 v[56:59], v[184:187], v[152:155], v[56:59]
	v_mfma_f32_16x16x32_bf16 v[52:55], v[192:195], v[152:155], v[52:55]
	v_mfma_f32_16x16x32_bf16 v[40:43], v[184:187], v[160:163], v[40:43]
	v_mfma_f32_16x16x32_bf16 v[36:39], v[192:195], v[160:163], v[36:39]
	v_mfma_f32_16x16x32_bf16 v[24:27], v[184:187], v[168:171], v[24:27]
	v_mfma_f32_16x16x32_bf16 v[20:23], v[192:195], v[168:171], v[20:23]
	v_mfma_f32_16x16x32_bf16 v[8:11], v[184:187], v[176:179], v[8:11]
	v_mfma_f32_16x16x32_bf16 v[4:7], v[192:195], v[176:179], v[4:7]
	v_mfma_f32_16x16x32_bf16 v[56:59], v[188:191], v[156:159], v[56:59]
	v_mfma_f32_16x16x32_bf16 v[52:55], v[210:213], v[156:159], v[52:55]
	v_mfma_f32_16x16x32_bf16 v[40:43], v[188:191], v[164:167], v[40:43]
	v_mfma_f32_16x16x32_bf16 v[36:39], v[210:213], v[164:167], v[36:39]
	v_mfma_f32_16x16x32_bf16 v[24:27], v[188:191], v[172:175], v[24:27]
	v_mfma_f32_16x16x32_bf16 v[20:23], v[210:213], v[172:175], v[20:23]
	v_mfma_f32_16x16x32_bf16 v[8:11], v[188:191], v[180:183], v[8:11]
	v_mfma_f32_16x16x32_bf16 v[4:7], v[210:213], v[180:183], v[4:7]
	s_setprio 0
	s_add_i32 s81, 0, 0x18000
	v_add_u32_e32 v148, s81, v1
	s_barrier
	ds_read_b128 v[132:135], v148
	ds_read_b128 v[140:143], v148 offset:1024
	ds_read_b128 v[144:147], v148 offset:2048
	ds_read_b128 v[148:151], v148 offset:3072
	s_add_u32 s0, s46, 0x40000
	s_addc_u32 s1, s47, 0
	s_mov_b32 m0, s63
	ds_read_b128 v[152:155], v3 offset:32768
	ds_read_b128 v[156:159], v3 offset:33792
	ds_read_b128 v[160:163], v3 offset:34816
	ds_read_b128 v[164:167], v3 offset:35840
	ds_read_b128 v[168:171], v3 offset:36864
	ds_read_b128 v[172:175], v3 offset:37888
	ds_read_b128 v[176:179], v3 offset:38912
	ds_read_b128 v[180:183], v3 offset:39936
	s_nop 0
	global_load_lds_dwordx4 v138, s[0:1]
	s_mov_b32 m0, s72
	s_nop 0
	global_load_lds_dwordx4 v136, s[0:1]
	s_waitcnt lgkmcnt(8)
	s_barrier
	s_waitcnt lgkmcnt(0)
	s_setprio 1
	s_waitcnt lgkmcnt(0)
	v_mfma_f32_16x16x32_bf16 v[128:131], v[132:135], v[152:155], v[128:131]
	v_mfma_f32_16x16x32_bf16 v[124:127], v[144:147], v[152:155], v[124:127]
	v_mfma_f32_16x16x32_bf16 v[112:115], v[132:135], v[160:163], v[112:115]
	v_mfma_f32_16x16x32_bf16 v[108:111], v[144:147], v[160:163], v[108:111]
	v_mfma_f32_16x16x32_bf16 v[96:99], v[132:135], v[168:171], v[96:99]
	v_mfma_f32_16x16x32_bf16 v[92:95], v[144:147], v[168:171], v[92:95]
	v_mfma_f32_16x16x32_bf16 v[80:83], v[132:135], v[176:179], v[80:83]
	v_mfma_f32_16x16x32_bf16 v[76:79], v[144:147], v[176:179], v[76:79]
	v_mfma_f32_16x16x32_bf16 v[128:131], v[140:143], v[156:159], v[128:131]
	v_mfma_f32_16x16x32_bf16 v[124:127], v[148:151], v[156:159], v[124:127]
	v_mfma_f32_16x16x32_bf16 v[112:115], v[140:143], v[164:167], v[112:115]
	v_mfma_f32_16x16x32_bf16 v[108:111], v[148:151], v[164:167], v[108:111]
	v_mfma_f32_16x16x32_bf16 v[96:99], v[140:143], v[172:175], v[96:99]
	v_mfma_f32_16x16x32_bf16 v[92:95], v[148:151], v[172:175], v[92:95]
	v_mfma_f32_16x16x32_bf16 v[80:83], v[140:143], v[180:183], v[80:83]
	v_mfma_f32_16x16x32_bf16 v[76:79], v[148:151], v[180:183], v[76:79]
	s_setprio 0
	s_barrier
	s_add_i32 s46, 0, 0x1c000
	s_add_u32 s0, s14, 0x80
	v_add_u32_e32 v210, s46, v1
	s_addc_u32 s1, s15, 0
	s_add_i32 s47, s81, s56
	ds_read_b128 v[184:187], v210
	ds_read_b128 v[188:191], v210 offset:1024
	ds_read_b128 v[192:195], v210 offset:2048
	ds_read_b128 v[210:213], v210 offset:3072
	s_mov_b32 m0, s47
	s_nop 0
	global_load_lds_dwordx4 v138, s[0:1]
	s_add_i32 m0, s47, 0x2000
	s_nop 0
	global_load_lds_dwordx4 v136, s[0:1]
	s_barrier
	s_waitcnt lgkmcnt(0)
	s_setprio 1
	s_waitcnt lgkmcnt(0)
	v_mfma_f32_16x16x32_bf16 v[120:123], v[184:187], v[152:155], v[120:123]
	v_mfma_f32_16x16x32_bf16 v[116:119], v[192:195], v[152:155], v[116:119]
	v_mfma_f32_16x16x32_bf16 v[104:107], v[184:187], v[160:163], v[104:107]
	v_mfma_f32_16x16x32_bf16 v[100:103], v[192:195], v[160:163], v[100:103]
	v_mfma_f32_16x16x32_bf16 v[88:91], v[184:187], v[168:171], v[88:91]
	v_mfma_f32_16x16x32_bf16 v[84:87], v[192:195], v[168:171], v[84:87]
	v_mfma_f32_16x16x32_bf16 v[72:75], v[184:187], v[176:179], v[72:75]
	v_mfma_f32_16x16x32_bf16 v[68:71], v[192:195], v[176:179], v[68:71]
	v_mfma_f32_16x16x32_bf16 v[120:123], v[188:191], v[156:159], v[120:123]
	v_mfma_f32_16x16x32_bf16 v[116:119], v[210:213], v[156:159], v[116:119]
	v_mfma_f32_16x16x32_bf16 v[104:107], v[188:191], v[164:167], v[104:107]
	v_mfma_f32_16x16x32_bf16 v[100:103], v[210:213], v[164:167], v[100:103]
	v_mfma_f32_16x16x32_bf16 v[88:91], v[188:191], v[172:175], v[88:91]
	v_mfma_f32_16x16x32_bf16 v[84:87], v[210:213], v[172:175], v[84:87]
	v_mfma_f32_16x16x32_bf16 v[72:75], v[188:191], v[180:183], v[72:75]
	v_mfma_f32_16x16x32_bf16 v[68:71], v[210:213], v[180:183], v[68:71]
	s_setprio 0
	s_mov_b32 m0, s73
	s_barrier
	ds_read_b128 v[152:155], v3 offset:49152
	ds_read_b128 v[156:159], v3 offset:50176
	ds_read_b128 v[160:163], v3 offset:51200
	ds_read_b128 v[164:167], v3 offset:52224
	ds_read_b128 v[168:171], v3 offset:53248
	ds_read_b128 v[172:175], v3 offset:54272
	ds_read_b128 v[176:179], v3 offset:55296
	ds_read_b128 v[180:183], v3 offset:56320
	s_nop 0
	global_load_lds_dwordx4 v138, s[18:19]
	s_mov_b32 m0, s74
	s_nop 0
	global_load_lds_dwordx4 v136, s[18:19]
	s_barrier
	s_waitcnt lgkmcnt(0)
	s_setprio 1
	s_waitcnt lgkmcnt(0)
	v_mfma_f32_16x16x32_bf16 v[64:67], v[132:135], v[152:155], v[64:67]
	v_mfma_f32_16x16x32_bf16 v[60:63], v[144:147], v[152:155], v[60:63]
	v_mfma_f32_16x16x32_bf16 v[48:51], v[132:135], v[160:163], v[48:51]
	v_mfma_f32_16x16x32_bf16 v[44:47], v[144:147], v[160:163], v[44:47]
	v_mfma_f32_16x16x32_bf16 v[32:35], v[132:135], v[168:171], v[32:35]
	v_mfma_f32_16x16x32_bf16 v[28:31], v[144:147], v[168:171], v[28:31]
	v_mfma_f32_16x16x32_bf16 v[16:19], v[132:135], v[176:179], v[16:19]
	v_mfma_f32_16x16x32_bf16 v[12:15], v[144:147], v[176:179], v[12:15]
	v_mfma_f32_16x16x32_bf16 v[64:67], v[140:143], v[156:159], v[64:67]
	v_mfma_f32_16x16x32_bf16 v[60:63], v[148:151], v[156:159], v[60:63]
	v_mfma_f32_16x16x32_bf16 v[48:51], v[140:143], v[164:167], v[48:51]
	v_mfma_f32_16x16x32_bf16 v[44:47], v[148:151], v[164:167], v[44:47]
	v_mfma_f32_16x16x32_bf16 v[32:35], v[140:143], v[172:175], v[32:35]
	v_mfma_f32_16x16x32_bf16 v[28:31], v[148:151], v[172:175], v[28:31]
	v_mfma_f32_16x16x32_bf16 v[16:19], v[140:143], v[180:183], v[16:19]
	v_mfma_f32_16x16x32_bf16 v[12:15], v[148:151], v[180:183], v[12:15]
	s_setprio 0
	s_barrier
	s_add_u32 s0, s14, 0x40080
	s_addc_u32 s1, s15, 0
	s_add_i32 s14, s46, s56
	s_mov_b32 m0, s14
	s_nop 0
	global_load_lds_dwordx4 v138, s[0:1]
	s_add_i32 m0, s14, 0x2000
	s_nop 0
	global_load_lds_dwordx4 v136, s[0:1]
	s_waitcnt vmcnt(6)
	s_barrier
	s_setprio 1
	v_mfma_f32_16x16x32_bf16 v[56:59], v[184:187], v[152:155], v[56:59]
	v_mfma_f32_16x16x32_bf16 v[52:55], v[192:195], v[152:155], v[52:55]
	v_mfma_f32_16x16x32_bf16 v[40:43], v[184:187], v[160:163], v[40:43]
	v_mfma_f32_16x16x32_bf16 v[36:39], v[192:195], v[160:163], v[36:39]
	v_mfma_f32_16x16x32_bf16 v[24:27], v[184:187], v[168:171], v[24:27]
	v_mfma_f32_16x16x32_bf16 v[20:23], v[192:195], v[168:171], v[20:23]
	v_mfma_f32_16x16x32_bf16 v[8:11], v[184:187], v[176:179], v[8:11]
	v_mfma_f32_16x16x32_bf16 v[4:7], v[192:195], v[176:179], v[4:7]
	v_mfma_f32_16x16x32_bf16 v[56:59], v[188:191], v[156:159], v[56:59]
	v_mfma_f32_16x16x32_bf16 v[52:55], v[210:213], v[156:159], v[52:55]
	v_mfma_f32_16x16x32_bf16 v[40:43], v[188:191], v[164:167], v[40:43]
	v_mfma_f32_16x16x32_bf16 v[36:39], v[210:213], v[164:167], v[36:39]
	v_mfma_f32_16x16x32_bf16 v[24:27], v[188:191], v[172:175], v[24:27]
	v_mfma_f32_16x16x32_bf16 v[20:23], v[210:213], v[172:175], v[20:23]
	v_mfma_f32_16x16x32_bf16 v[8:11], v[188:191], v[180:183], v[8:11]
	v_mfma_f32_16x16x32_bf16 v[4:7], v[210:213], v[180:183], v[4:7]
	s_setprio 0
	s_add_i32 s80, s80, 2
	s_add_u32 s68, s68, 0x100
	s_addc_u32 s79, s79, 0
	s_cmp_gt_u32 s80, 13
	s_mov_b64 s[0:1], s[8:9]
	s_barrier
	s_cbranch_scc0 .LBB0_1765
	v_mov_b32_e32 v145, v0
	s_lshl_b32 s1, s64, 8
	v_readfirstlane_b32 s0, v145
	s_and_b32 s14, s0, 0xc0
	s_ashr_i32 s0, s0, 2
	v_and_b32_e32 v170, 15, v145
	s_and_b32 s15, s0, 0xffffffc0
	v_or_b32_e32 v132, s15, v170
	v_add_u32_e32 v132, s1, v132
	v_ashrrev_i32_e32 v133, 31, v132
	v_lshl_add_u64 v[132:133], v[132:133], 2, s[20:21]
	global_load_dword v134, v[132:133], off
	global_load_dword v174, v[132:133], off offset:64
	global_load_dword v173, v[132:133], off offset:128
	global_load_dword v172, v[132:133], off offset:192
	global_load_dword v171, v[132:133], off offset:512
	global_load_dword v169, v[132:133], off offset:576
	global_load_dword v168, v[132:133], off offset:640
	global_load_dword v167, v[132:133], off offset:704
	s_add_i32 s15, s15, s1
	s_cmp_gt_i32 s78, 2
	s_cselect_b64 s[0:1], -1, 0
	v_or_b32_e32 v142, s15, v170
	s_mov_b64 s[8:9], -1
	s_waitcnt vmcnt(0)
	v_fmamk_f32 v132, v134, 0x3a800000, v231
	v_cmp_gt_f32_e32 vcc, s11, v132
	v_mul_f32_e32 v133, 0x4b800000, v132
	s_nop 0
	v_cndmask_b32_e32 v132, v132, v133, vcc
	v_rsq_f32_e32 v132, v132
	s_nop 0
	v_mul_f32_e32 v133, 0x45800000, v132
	v_cndmask_b32_e32 v144, v132, v133, vcc
	v_lshrrev_b32_e32 v132, 1, v145
	v_and_b32_e32 v155, 24, v132
	s_and_b64 vcc, exec, s[0:1]
	v_lshlrev_b32_e32 v166, 2, v155
	v_lshlrev_b32_e32 v140, 1, v155
	s_cbranch_vccz .LBB0_1768
	v_ashrrev_i32_e32 v143, 31, v142
	v_lshlrev_b64 v[132:133], 9, v[142:143]
	v_lshl_add_u64 v[132:133], s[24:25], 0, v[132:133]
	s_lshl_b32 s68, s14, 1
	v_pk_mul_f32 v[160:161], v[130:131], v[144:145] op_sel_hi:[1,0]
	v_pk_mul_f32 v[162:163], v[128:129], v[144:145] op_sel_hi:[1,0]
	v_lshl_add_u64 v[164:165], v[132:133], 0, s[68:69]
	v_pk_mul_f32 v[132:133], v[160:161], v[160:161]
	v_pk_mul_f32 v[134:135], v[162:163], v[162:163]
	v_pk_mul_f32 v[156:157], v[126:127], v[144:145] op_sel_hi:[1,0]
	v_pk_mov_b32 v[146:147], v[134:135], v[132:133] op_sel:[1,0]
	v_mov_b32_e32 v135, v133
	v_pk_add_f32 v[132:133], v[146:147], v[134:135]
	v_pk_mul_f32 v[158:159], v[124:125], v[144:145] op_sel_hi:[1,0]
	v_pk_add_f32 v[132:133], v[132:133], v[132:133] op_sel_hi:[0,1]
	v_pk_mul_f32 v[134:135], v[156:157], v[156:157]
	v_pk_mul_f32 v[146:147], v[158:159], v[158:159]
	v_pk_mul_f32 v[152:153], v[120:121], v[144:145] op_sel_hi:[1,0]
	v_pk_mov_b32 v[148:149], v[146:147], v[134:135] op_sel:[1,0]
	v_mov_b32_e32 v147, v135
	v_pk_mul_f32 v[150:151], v[122:123], v[144:145] op_sel_hi:[1,0]
	v_mul_f32_e32 v132, v152, v152
	v_pk_add_f32 v[134:135], v[148:149], v[146:147]
	v_pk_fma_f32 v[176:177], v[152:153], v[152:153], v[132:133] op_sel_hi:[1,1,0]
	v_mul_f32_e32 v132, v150, v150
	v_pk_add_f32 v[134:135], v[134:135], v[134:135] op_sel_hi:[0,1]
	v_pk_fma_f32 v[178:179], v[150:151], v[150:151], v[132:133] op_sel_hi:[1,1,0]
	v_pk_mul_f32 v[146:147], v[118:119], v[144:145] op_sel_hi:[1,0]
	v_pk_mul_f32 v[148:149], v[116:117], v[144:145] op_sel_hi:[1,0]
	v_mul_f32_e32 v132, v146, v146
	v_mul_f32_e32 v176, v148, v148
	v_mul_f32_e32 v178, v149, v149
	v_mul_f32_e32 v134, v147, v147
	v_pk_add_f32 v[176:177], v[176:177], v[178:179]
	v_pk_add_f32 v[132:133], v[132:133], v[134:135]
	v_and_b32_e32 v134, 64, v236
	v_pk_add_f32 v[132:133], v[176:177], v[132:133]
	v_add_u32_e32 v134, 64, v134
	v_add_f32_e32 v132, v132, v133
	v_mov_b32_e32 v133, v132
	s_nop 1
	v_permlane16_swap_b32 v133, v132
	v_mov_b32_e32 v141, v2
	v_lshl_add_u64 v[164:165], v[164:165], 0, v[140:141]
	s_mov_b64 s[8:9], 0
	s_waitcnt lgkmcnt(0)
	v_add_f32_e32 v132, v132, v133
	v_xor_b32_e32 v133, 32, v236
	v_cmp_lt_i32_e32 vcc, v133, v134
	s_nop 1
	v_cndmask_b32_e32 v133, v236, v133, vcc
	v_lshlrev_b32_e32 v133, 2, v133
	v_mov_b32_e32 v133, v132
	s_nop 1
	v_permlane32_swap_b32 v133, v132
	s_waitcnt lgkmcnt(0)
	v_add_f32_e32 v132, v132, v133
	v_fmamk_f32 v132, v132, 0x3c800000, v231
	v_cmp_gt_f32_e32 vcc, s11, v132
	v_mul_f32_e32 v133, 0x4b800000, v132
	s_nop 0
	v_cndmask_b32_e32 v132, v132, v133, vcc
	v_rsq_f32_e32 v132, v132
	s_nop 0
	v_mul_f32_e32 v133, 0x45800000, v132
	v_cndmask_b32_e32 v132, v132, v133, vcc
	v_mul_f32_e32 v154, 0x3e38aa3b, v132
	global_load_dwordx4 v[132:135], v166, s[26:27] offset:16
	global_load_dwordx4 v[176:179], v166, s[26:27]
	v_pk_mul_f32 v[162:163], v[162:163], v[154:155] op_sel_hi:[1,0]
	v_pk_mul_f32 v[160:161], v[160:161], v[154:155] op_sel_hi:[1,0]
	v_pk_mul_f32 v[158:159], v[158:159], v[154:155] op_sel_hi:[1,0]
	v_pk_mul_f32 v[156:157], v[156:157], v[154:155] op_sel_hi:[1,0]
	v_pk_mul_f32 v[152:153], v[152:153], v[154:155] op_sel_hi:[1,0]
	v_pk_mul_f32 v[150:151], v[150:151], v[154:155] op_sel_hi:[1,0]
	v_pk_mul_f32 v[148:149], v[148:149], v[154:155] op_sel_hi:[1,0]
	v_pk_mul_f32 v[146:147], v[146:147], v[154:155] op_sel_hi:[1,0]
	s_waitcnt vmcnt(1)
	v_pk_mul_f32 v[156:157], v[134:135], v[156:157]
	s_waitcnt vmcnt(0)
	v_pk_mul_f32 v[160:161], v[178:179], v[160:161]
	v_pk_mul_f32 v[162:163], v[176:177], v[162:163]
	v_pk_mul_f32 v[134:135], v[132:133], v[158:159]
	v_cvt_pk_bf16_f32 v132, v162, v163
	v_cvt_pk_bf16_f32 v133, v160, v161
	v_cvt_pk_bf16_f32 v134, v134, v135
	v_cvt_pk_bf16_f32 v135, v156, v157
	global_store_dwordx4 v[164:165], v[132:135], off
	global_load_dwordx4 v[132:135], v166, s[26:27] offset:144
	s_nop 0
	global_load_dwordx4 v[156:159], v166, s[26:27] offset:128
	s_waitcnt vmcnt(1)
	v_pk_mul_f32 v[146:147], v[134:135], v[146:147]
	s_waitcnt vmcnt(0)
	v_pk_mul_f32 v[150:151], v[158:159], v[150:151]
	v_pk_mul_f32 v[152:153], v[156:157], v[152:153]
	v_pk_mul_f32 v[134:135], v[132:133], v[148:149]
	v_cvt_pk_bf16_f32 v132, v152, v153
	v_cvt_pk_bf16_f32 v133, v150, v151
	v_cvt_pk_bf16_f32 v134, v134, v135
	v_cvt_pk_bf16_f32 v135, v146, v147
	global_store_dwordx4 v[164:165], v[132:135], off offset:64

.LBB0_1776:
	s_nop 0
	v_fmamk_f32 v116, v174, 0x3a800000, v231
	v_cmp_gt_f32_e32 vcc, s11, v116
	v_mul_f32_e32 v117, 0x4b800000, v116
	v_or_b32_e32 v122, 16, v142
	v_cndmask_b32_e32 v116, v116, v117, vcc
	v_rsq_f32_e32 v116, v116
	s_mov_b64 s[8:9], -1
	v_mul_f32_e32 v117, 0x45800000, v116
	v_cndmask_b32_e32 v120, v116, v117, vcc
	v_cndmask_b32_e64 v116, 0, 1, s[0:1]
	v_cmp_ne_u32_e64 s[18:19], 1, v116
	s_andn2_b64 vcc, exec, s[0:1]
	s_cbranch_vccnz .LBB0_1778
	v_ashrrev_i32_e32 v123, 31, v122
	v_lshlrev_b64 v[116:117], 9, v[122:123]
	v_lshl_add_u64 v[116:117], s[24:25], 0, v[116:117]
	s_lshl_b32 s68, s14, 1
	v_pk_mul_f32 v[148:149], v[114:115], v[120:121] op_sel_hi:[1,0]
	v_pk_mul_f32 v[150:151], v[112:113], v[120:121] op_sel_hi:[1,0]
	v_lshl_add_u64 v[152:153], v[116:117], 0, s[68:69]
	v_pk_mul_f32 v[116:117], v[148:149], v[148:149]
	v_pk_mul_f32 v[118:119], v[150:151], v[150:151]
	v_pk_mul_f32 v[144:145], v[110:111], v[120:121] op_sel_hi:[1,0]
	v_pk_mov_b32 v[124:125], v[118:119], v[116:117] op_sel:[1,0]
	v_mov_b32_e32 v119, v117
	v_pk_add_f32 v[116:117], v[124:125], v[118:119]
	v_pk_mul_f32 v[146:147], v[108:109], v[120:121] op_sel_hi:[1,0]
	v_pk_add_f32 v[116:117], v[116:117], v[116:117] op_sel_hi:[0,1]
	v_pk_mul_f32 v[118:119], v[144:145], v[144:145]
	v_pk_mul_f32 v[124:125], v[146:147], v[146:147]
	v_pk_mul_f32 v[130:131], v[104:105], v[120:121] op_sel_hi:[1,0]
	v_pk_mov_b32 v[126:127], v[124:125], v[118:119] op_sel:[1,0]
	v_mov_b32_e32 v125, v119
	v_pk_mul_f32 v[128:129], v[106:107], v[120:121] op_sel_hi:[1,0]
	v_mul_f32_e32 v116, v130, v130
	v_pk_add_f32 v[118:119], v[126:127], v[124:125]
	v_pk_fma_f32 v[134:135], v[130:131], v[130:131], v[116:117] op_sel_hi:[1,1,0]
	v_mul_f32_e32 v116, v128, v128
	v_pk_add_f32 v[118:119], v[118:119], v[118:119] op_sel_hi:[0,1]
	v_pk_fma_f32 v[156:157], v[128:129], v[128:129], v[116:117] op_sel_hi:[1,1,0]
	v_pk_mul_f32 v[124:125], v[102:103], v[120:121] op_sel_hi:[1,0]
	v_pk_mul_f32 v[126:127], v[100:101], v[120:121] op_sel_hi:[1,0]
	v_mul_f32_e32 v116, v124, v124
	v_mul_f32_e32 v134, v126, v126
	v_mul_f32_e32 v156, v127, v127
	v_mul_f32_e32 v118, v125, v125
	v_pk_add_f32 v[134:135], v[134:135], v[156:157]
	v_pk_add_f32 v[116:117], v[116:117], v[118:119]
	v_and_b32_e32 v118, 64, v236
	v_pk_add_f32 v[116:117], v[134:135], v[116:117]
	v_add_u32_e32 v118, 64, v118
	v_add_f32_e32 v116, v116, v117
	v_mov_b32_e32 v117, v116
	s_nop 1
	v_permlane16_swap_b32 v117, v116
	v_mov_b32_e32 v141, v2
	v_lshl_add_u64 v[152:153], v[152:153], 0, v[140:141]
	s_mov_b64 s[8:9], 0
	s_waitcnt lgkmcnt(0)
	v_add_f32_e32 v116, v116, v117
	v_xor_b32_e32 v117, 32, v236
	v_cmp_lt_i32_e32 vcc, v117, v118
	s_nop 1
	v_cndmask_b32_e32 v117, v236, v117, vcc
	v_lshlrev_b32_e32 v117, 2, v117
	v_mov_b32_e32 v117, v116
	s_nop 1
	v_permlane32_swap_b32 v117, v116
	s_waitcnt lgkmcnt(0)
	v_add_f32_e32 v116, v116, v117
	v_fmamk_f32 v116, v116, 0x3c800000, v231
	v_cmp_gt_f32_e32 vcc, s11, v116
	v_mul_f32_e32 v117, 0x4b800000, v116
	s_nop 0
	v_cndmask_b32_e32 v116, v116, v117, vcc
	v_rsq_f32_e32 v116, v116
	s_nop 0
	v_mul_f32_e32 v117, 0x45800000, v116
	v_cndmask_b32_e32 v116, v116, v117, vcc
	v_mul_f32_e32 v134, 0x3e38aa3b, v116
	global_load_dwordx4 v[116:119], v166, s[26:27] offset:16
	global_load_dwordx4 v[156:159], v166, s[26:27]
	v_pk_mul_f32 v[150:151], v[150:151], v[134:135] op_sel_hi:[1,0]
	v_pk_mul_f32 v[148:149], v[148:149], v[134:135] op_sel_hi:[1,0]
	v_pk_mul_f32 v[146:147], v[146:147], v[134:135] op_sel_hi:[1,0]
	v_pk_mul_f32 v[144:145], v[144:145], v[134:135] op_sel_hi:[1,0]
	v_pk_mul_f32 v[130:131], v[130:131], v[134:135] op_sel_hi:[1,0]
	v_pk_mul_f32 v[128:129], v[128:129], v[134:135] op_sel_hi:[1,0]
	v_pk_mul_f32 v[126:127], v[126:127], v[134:135] op_sel_hi:[1,0]
	v_pk_mul_f32 v[124:125], v[124:125], v[134:135] op_sel_hi:[1,0]
	s_waitcnt vmcnt(1)
	v_pk_mul_f32 v[144:145], v[118:119], v[144:145]
	s_waitcnt vmcnt(0)
	v_pk_mul_f32 v[148:149], v[158:159], v[148:149]
	v_pk_mul_f32 v[150:151], v[156:157], v[150:151]
	v_pk_mul_f32 v[118:119], v[116:117], v[146:147]
	v_cvt_pk_bf16_f32 v116, v150, v151
	v_cvt_pk_bf16_f32 v117, v148, v149
	v_cvt_pk_bf16_f32 v118, v118, v119
	v_cvt_pk_bf16_f32 v119, v144, v145
	global_store_dwordx4 v[152:153], v[116:119], off
	global_load_dwordx4 v[116:119], v166, s[26:27] offset:144
	s_nop 0
	global_load_dwordx4 v[144:147], v166, s[26:27] offset:128
	s_waitcnt vmcnt(1)
	v_pk_mul_f32 v[124:125], v[118:119], v[124:125]
	s_waitcnt vmcnt(0)
	v_pk_mul_f32 v[128:129], v[146:147], v[128:129]
	v_pk_mul_f32 v[130:131], v[144:145], v[130:131]
	v_pk_mul_f32 v[118:119], v[116:117], v[126:127]
	v_cvt_pk_bf16_f32 v116, v130, v131
	v_cvt_pk_bf16_f32 v117, v128, v129
	v_cvt_pk_bf16_f32 v118, v118, v119
	v_cvt_pk_bf16_f32 v119, v124, v125
	global_store_dwordx4 v[152:153], v[116:119], off offset:64

.LBB0_1786:
	s_nop 0
	v_fmamk_f32 v100, v173, 0x3a800000, v231
	v_cmp_gt_f32_e32 vcc, s11, v100
	v_mul_f32_e32 v101, 0x4b800000, v100
	v_or_b32_e32 v106, 32, v142
	v_cndmask_b32_e32 v100, v100, v101, vcc
	v_rsq_f32_e32 v100, v100
	s_mov_b64 s[0:1], -1
	v_mul_f32_e32 v101, 0x45800000, v100
	v_cndmask_b32_e32 v104, v100, v101, vcc
	s_and_b64 vcc, exec, s[18:19]
	s_cbranch_vccnz .LBB0_1788
	v_ashrrev_i32_e32 v107, 31, v106
	v_lshlrev_b64 v[100:101], 9, v[106:107]
	v_lshl_add_u64 v[100:101], s[24:25], 0, v[100:101]
	s_lshl_b32 s68, s14, 1
	v_pk_mul_f32 v[122:123], v[98:99], v[104:105] op_sel_hi:[1,0]
	v_pk_mul_f32 v[124:125], v[96:97], v[104:105] op_sel_hi:[1,0]
	v_lshl_add_u64 v[126:127], v[100:101], 0, s[68:69]
	v_pk_mul_f32 v[100:101], v[122:123], v[122:123]
	v_pk_mul_f32 v[102:103], v[124:125], v[124:125]
	v_pk_mul_f32 v[118:119], v[94:95], v[104:105] op_sel_hi:[1,0]
	v_pk_mov_b32 v[108:109], v[102:103], v[100:101] op_sel:[1,0]
	v_mov_b32_e32 v103, v101
	v_pk_add_f32 v[100:101], v[108:109], v[102:103]
	v_pk_mul_f32 v[120:121], v[92:93], v[104:105] op_sel_hi:[1,0]
	v_pk_add_f32 v[100:101], v[100:101], v[100:101] op_sel_hi:[0,1]
	v_pk_mul_f32 v[102:103], v[118:119], v[118:119]
	v_pk_mul_f32 v[108:109], v[120:121], v[120:121]
	v_pk_mul_f32 v[114:115], v[88:89], v[104:105] op_sel_hi:[1,0]
	v_pk_mov_b32 v[110:111], v[108:109], v[102:103] op_sel:[1,0]
	v_mov_b32_e32 v109, v103
	v_pk_mul_f32 v[112:113], v[90:91], v[104:105] op_sel_hi:[1,0]
	v_mul_f32_e32 v100, v114, v114
	v_pk_add_f32 v[102:103], v[110:111], v[108:109]
	v_pk_fma_f32 v[116:117], v[114:115], v[114:115], v[100:101] op_sel_hi:[1,1,0]
	v_mul_f32_e32 v100, v112, v112
	v_pk_add_f32 v[102:103], v[102:103], v[102:103] op_sel_hi:[0,1]
	v_pk_fma_f32 v[128:129], v[112:113], v[112:113], v[100:101] op_sel_hi:[1,1,0]
	v_pk_mul_f32 v[108:109], v[86:87], v[104:105] op_sel_hi:[1,0]
	v_pk_mul_f32 v[110:111], v[84:85], v[104:105] op_sel_hi:[1,0]
	v_mul_f32_e32 v100, v108, v108
	v_mul_f32_e32 v116, v110, v110
	v_mul_f32_e32 v128, v111, v111
	v_mul_f32_e32 v102, v109, v109
	v_pk_add_f32 v[116:117], v[116:117], v[128:129]
	v_pk_add_f32 v[100:101], v[100:101], v[102:103]
	v_and_b32_e32 v102, 64, v236
	v_pk_add_f32 v[100:101], v[116:117], v[100:101]
	v_add_u32_e32 v102, 64, v102
	v_add_f32_e32 v100, v100, v101
	v_mov_b32_e32 v101, v100
	s_nop 1
	v_permlane16_swap_b32 v101, v100
	v_mov_b32_e32 v141, v2
	v_lshl_add_u64 v[126:127], v[126:127], 0, v[140:141]
	s_mov_b64 s[0:1], 0
	s_waitcnt lgkmcnt(0)
	v_add_f32_e32 v100, v100, v101
	v_xor_b32_e32 v101, 32, v236
	v_cmp_lt_i32_e32 vcc, v101, v102
	s_nop 1
	v_cndmask_b32_e32 v101, v236, v101, vcc
	v_lshlrev_b32_e32 v101, 2, v101
	v_mov_b32_e32 v101, v100
	s_nop 1
	v_permlane32_swap_b32 v101, v100
	s_waitcnt lgkmcnt(0)
	v_add_f32_e32 v100, v100, v101
	v_fmamk_f32 v100, v100, 0x3c800000, v231
	v_cmp_gt_f32_e32 vcc, s11, v100
	v_mul_f32_e32 v101, 0x4b800000, v100
	s_nop 0
	v_cndmask_b32_e32 v100, v100, v101, vcc
	v_rsq_f32_e32 v100, v100
	s_nop 0
	v_mul_f32_e32 v101, 0x45800000, v100
	v_cndmask_b32_e32 v100, v100, v101, vcc
	v_mul_f32_e32 v116, 0x3e38aa3b, v100
	global_load_dwordx4 v[100:103], v166, s[26:27] offset:16
	global_load_dwordx4 v[128:131], v166, s[26:27]
	v_pk_mul_f32 v[124:125], v[124:125], v[116:117] op_sel_hi:[1,0]
	v_pk_mul_f32 v[122:123], v[122:123], v[116:117] op_sel_hi:[1,0]
	v_pk_mul_f32 v[120:121], v[120:121], v[116:117] op_sel_hi:[1,0]
	v_pk_mul_f32 v[118:119], v[118:119], v[116:117] op_sel_hi:[1,0]
	v_pk_mul_f32 v[114:115], v[114:115], v[116:117] op_sel_hi:[1,0]
	v_pk_mul_f32 v[112:113], v[112:113], v[116:117] op_sel_hi:[1,0]
	v_pk_mul_f32 v[110:111], v[110:111], v[116:117] op_sel_hi:[1,0]
	v_pk_mul_f32 v[108:109], v[108:109], v[116:117] op_sel_hi:[1,0]
	s_waitcnt vmcnt(1)
	v_pk_mul_f32 v[118:119], v[102:103], v[118:119]
	s_waitcnt vmcnt(0)
	v_pk_mul_f32 v[122:123], v[130:131], v[122:123]
	v_pk_mul_f32 v[124:125], v[128:129], v[124:125]
	v_pk_mul_f32 v[102:103], v[100:101], v[120:121]
	v_cvt_pk_bf16_f32 v100, v124, v125
	v_cvt_pk_bf16_f32 v101, v122, v123
	v_cvt_pk_bf16_f32 v102, v102, v103
	v_cvt_pk_bf16_f32 v103, v118, v119
	global_store_dwordx4 v[126:127], v[100:103], off
	global_load_dwordx4 v[100:103], v166, s[26:27] offset:144
	s_nop 0
	global_load_dwordx4 v[118:121], v166, s[26:27] offset:128
	s_waitcnt vmcnt(1)
	v_pk_mul_f32 v[108:109], v[102:103], v[108:109]
	s_waitcnt vmcnt(0)
	v_pk_mul_f32 v[112:113], v[120:121], v[112:113]
	v_pk_mul_f32 v[114:115], v[118:119], v[114:115]
	v_pk_mul_f32 v[102:103], v[100:101], v[110:111]
	v_cvt_pk_bf16_f32 v100, v114, v115
	v_cvt_pk_bf16_f32 v101, v112, v113
	v_cvt_pk_bf16_f32 v102, v102, v103
	v_cvt_pk_bf16_f32 v103, v108, v109
	global_store_dwordx4 v[126:127], v[100:103], off offset:64

.LBB0_1796:
	s_nop 0
	v_fmamk_f32 v84, v172, 0x3a800000, v231
	v_cmp_gt_f32_e32 vcc, s11, v84
	v_mul_f32_e32 v85, 0x4b800000, v84
	v_or_b32_e32 v90, 48, v142
	v_cndmask_b32_e32 v84, v84, v85, vcc
	v_rsq_f32_e32 v84, v84
	s_mov_b64 s[0:1], -1
	v_mul_f32_e32 v85, 0x45800000, v84
	v_cndmask_b32_e32 v88, v84, v85, vcc
	s_and_b64 vcc, exec, s[18:19]
	s_cbranch_vccnz .LBB0_1798
	v_ashrrev_i32_e32 v91, 31, v90
	v_lshlrev_b64 v[84:85], 9, v[90:91]
	v_lshl_add_u64 v[84:85], s[24:25], 0, v[84:85]
	s_lshl_b32 s68, s14, 1
	v_pk_mul_f32 v[106:107], v[82:83], v[88:89] op_sel_hi:[1,0]
	v_pk_mul_f32 v[108:109], v[80:81], v[88:89] op_sel_hi:[1,0]
	v_lshl_add_u64 v[110:111], v[84:85], 0, s[68:69]
	v_pk_mul_f32 v[84:85], v[106:107], v[106:107]
	v_pk_mul_f32 v[86:87], v[108:109], v[108:109]
	v_pk_mul_f32 v[102:103], v[78:79], v[88:89] op_sel_hi:[1,0]
	v_pk_mov_b32 v[92:93], v[86:87], v[84:85] op_sel:[1,0]
	v_mov_b32_e32 v87, v85
	v_pk_add_f32 v[84:85], v[92:93], v[86:87]
	v_pk_mul_f32 v[104:105], v[76:77], v[88:89] op_sel_hi:[1,0]
	v_pk_add_f32 v[84:85], v[84:85], v[84:85] op_sel_hi:[0,1]
	v_pk_mul_f32 v[86:87], v[102:103], v[102:103]
	v_pk_mul_f32 v[92:93], v[104:105], v[104:105]
	v_pk_mul_f32 v[98:99], v[72:73], v[88:89] op_sel_hi:[1,0]
	v_pk_mov_b32 v[94:95], v[92:93], v[86:87] op_sel:[1,0]
	v_mov_b32_e32 v93, v87
	v_pk_mul_f32 v[96:97], v[74:75], v[88:89] op_sel_hi:[1,0]
	v_mul_f32_e32 v84, v98, v98
	v_pk_add_f32 v[86:87], v[94:95], v[92:93]
	v_pk_fma_f32 v[100:101], v[98:99], v[98:99], v[84:85] op_sel_hi:[1,1,0]
	v_mul_f32_e32 v84, v96, v96
	v_pk_add_f32 v[86:87], v[86:87], v[86:87] op_sel_hi:[0,1]
	v_pk_fma_f32 v[112:113], v[96:97], v[96:97], v[84:85] op_sel_hi:[1,1,0]
	v_pk_mul_f32 v[92:93], v[70:71], v[88:89] op_sel_hi:[1,0]
	v_pk_mul_f32 v[94:95], v[68:69], v[88:89] op_sel_hi:[1,0]
	v_mul_f32_e32 v84, v92, v92
	v_mul_f32_e32 v100, v94, v94
	v_mul_f32_e32 v112, v95, v95
	v_mul_f32_e32 v86, v93, v93
	v_pk_add_f32 v[100:101], v[100:101], v[112:113]
	v_pk_add_f32 v[84:85], v[84:85], v[86:87]
	v_and_b32_e32 v86, 64, v236
	v_pk_add_f32 v[84:85], v[100:101], v[84:85]
	v_add_u32_e32 v86, 64, v86
	v_add_f32_e32 v84, v84, v85
	v_mov_b32_e32 v85, v84
	s_nop 1
	v_permlane16_swap_b32 v85, v84
	v_mov_b32_e32 v141, v2
	v_lshl_add_u64 v[110:111], v[110:111], 0, v[140:141]
	s_mov_b64 s[0:1], 0
	s_waitcnt lgkmcnt(0)
	v_add_f32_e32 v84, v84, v85
	v_xor_b32_e32 v85, 32, v236
	v_cmp_lt_i32_e32 vcc, v85, v86
	s_nop 1
	v_cndmask_b32_e32 v85, v236, v85, vcc
	v_lshlrev_b32_e32 v85, 2, v85
	v_mov_b32_e32 v85, v84
	s_nop 1
	v_permlane32_swap_b32 v85, v84
	s_waitcnt lgkmcnt(0)
	v_add_f32_e32 v84, v84, v85
	v_fmamk_f32 v84, v84, 0x3c800000, v231
	v_cmp_gt_f32_e32 vcc, s11, v84
	v_mul_f32_e32 v85, 0x4b800000, v84
	s_nop 0
	v_cndmask_b32_e32 v84, v84, v85, vcc
	v_rsq_f32_e32 v84, v84
	s_nop 0
	v_mul_f32_e32 v85, 0x45800000, v84
	v_cndmask_b32_e32 v84, v84, v85, vcc
	v_mul_f32_e32 v100, 0x3e38aa3b, v84
	global_load_dwordx4 v[84:87], v166, s[26:27] offset:16
	global_load_dwordx4 v[112:115], v166, s[26:27]
	v_pk_mul_f32 v[108:109], v[108:109], v[100:101] op_sel_hi:[1,0]
	v_pk_mul_f32 v[106:107], v[106:107], v[100:101] op_sel_hi:[1,0]
	v_pk_mul_f32 v[104:105], v[104:105], v[100:101] op_sel_hi:[1,0]
	v_pk_mul_f32 v[102:103], v[102:103], v[100:101] op_sel_hi:[1,0]
	v_pk_mul_f32 v[98:99], v[98:99], v[100:101] op_sel_hi:[1,0]
	v_pk_mul_f32 v[96:97], v[96:97], v[100:101] op_sel_hi:[1,0]
	v_pk_mul_f32 v[94:95], v[94:95], v[100:101] op_sel_hi:[1,0]
	v_pk_mul_f32 v[92:93], v[92:93], v[100:101] op_sel_hi:[1,0]
	s_waitcnt vmcnt(1)
	v_pk_mul_f32 v[102:103], v[86:87], v[102:103]
	s_waitcnt vmcnt(0)
	v_pk_mul_f32 v[106:107], v[114:115], v[106:107]
	v_pk_mul_f32 v[108:109], v[112:113], v[108:109]
	v_pk_mul_f32 v[86:87], v[84:85], v[104:105]
	v_cvt_pk_bf16_f32 v84, v108, v109
	v_cvt_pk_bf16_f32 v85, v106, v107
	v_cvt_pk_bf16_f32 v86, v86, v87
	v_cvt_pk_bf16_f32 v87, v102, v103
	global_store_dwordx4 v[110:111], v[84:87], off
	global_load_dwordx4 v[84:87], v166, s[26:27] offset:144
	s_nop 0
	global_load_dwordx4 v[102:105], v166, s[26:27] offset:128
	s_waitcnt vmcnt(1)
	v_pk_mul_f32 v[92:93], v[86:87], v[92:93]
	s_waitcnt vmcnt(0)
	v_pk_mul_f32 v[96:97], v[104:105], v[96:97]
	v_pk_mul_f32 v[98:99], v[102:103], v[98:99]
	v_pk_mul_f32 v[86:87], v[84:85], v[94:95]
	v_cvt_pk_bf16_f32 v84, v98, v99
	v_cvt_pk_bf16_f32 v85, v96, v97
	v_cvt_pk_bf16_f32 v86, v86, v87
	v_cvt_pk_bf16_f32 v87, v92, v93
	global_store_dwordx4 v[110:111], v[84:87], off offset:64

.LBB0_1810:
	s_nop 0
	v_fmamk_f32 v68, v171, 0x3a800000, v231
	v_cmp_gt_f32_e32 vcc, s11, v68
	v_mul_f32_e32 v69, 0x4b800000, v68
	s_addk_i32 s15, 0x80
	v_cndmask_b32_e32 v68, v68, v69, vcc
	v_rsq_f32_e32 v68, v68
	v_or_b32_e32 v72, s15, v170
	s_mov_b64 s[0:1], -1
	v_mul_f32_e32 v69, 0x45800000, v68
	v_cndmask_b32_e32 v74, v68, v69, vcc
	s_and_b64 vcc, exec, s[18:19]
	s_cbranch_vccnz .LBB0_1812
	v_ashrrev_i32_e32 v73, 31, v72
	v_lshlrev_b64 v[68:69], 9, v[72:73]
	v_lshl_add_u64 v[68:69], s[24:25], 0, v[68:69]
	s_lshl_b32 s68, s14, 1
	v_pk_mul_f32 v[90:91], v[66:67], v[74:75] op_sel_hi:[1,0]
	v_pk_mul_f32 v[92:93], v[64:65], v[74:75] op_sel_hi:[1,0]
	v_lshl_add_u64 v[94:95], v[68:69], 0, s[68:69]
	v_pk_mul_f32 v[68:69], v[90:91], v[90:91]
	v_pk_mul_f32 v[70:71], v[92:93], v[92:93]
	v_pk_mul_f32 v[86:87], v[62:63], v[74:75] op_sel_hi:[1,0]
	v_pk_mov_b32 v[76:77], v[70:71], v[68:69] op_sel:[1,0]
	v_mov_b32_e32 v71, v69
	v_pk_add_f32 v[68:69], v[76:77], v[70:71]
	v_pk_mul_f32 v[88:89], v[60:61], v[74:75] op_sel_hi:[1,0]
	v_pk_add_f32 v[68:69], v[68:69], v[68:69] op_sel_hi:[0,1]
	v_pk_mul_f32 v[70:71], v[86:87], v[86:87]
	v_pk_mul_f32 v[76:77], v[88:89], v[88:89]
	v_pk_mul_f32 v[82:83], v[56:57], v[74:75] op_sel_hi:[1,0]
	v_pk_mov_b32 v[78:79], v[76:77], v[70:71] op_sel:[1,0]
	v_mov_b32_e32 v77, v71
	v_pk_mul_f32 v[80:81], v[58:59], v[74:75] op_sel_hi:[1,0]
	v_mul_f32_e32 v68, v82, v82
	v_pk_add_f32 v[70:71], v[78:79], v[76:77]
	v_pk_fma_f32 v[84:85], v[82:83], v[82:83], v[68:69] op_sel_hi:[1,1,0]
	v_mul_f32_e32 v68, v80, v80
	v_pk_add_f32 v[70:71], v[70:71], v[70:71] op_sel_hi:[0,1]
	v_pk_fma_f32 v[96:97], v[80:81], v[80:81], v[68:69] op_sel_hi:[1,1,0]
	v_pk_mul_f32 v[76:77], v[54:55], v[74:75] op_sel_hi:[1,0]
	v_pk_mul_f32 v[78:79], v[52:53], v[74:75] op_sel_hi:[1,0]
	v_mul_f32_e32 v68, v76, v76
	v_mul_f32_e32 v84, v78, v78
	v_mul_f32_e32 v96, v79, v79
	v_mul_f32_e32 v70, v77, v77
	v_pk_add_f32 v[84:85], v[84:85], v[96:97]
	v_pk_add_f32 v[68:69], v[68:69], v[70:71]
	v_and_b32_e32 v70, 64, v236
	v_pk_add_f32 v[68:69], v[84:85], v[68:69]
	v_add_u32_e32 v70, 64, v70
	v_add_f32_e32 v68, v68, v69
	v_mov_b32_e32 v69, v68
	s_nop 1
	v_permlane16_swap_b32 v69, v68
	v_mov_b32_e32 v141, v2
	v_lshl_add_u64 v[94:95], v[94:95], 0, v[140:141]
	s_mov_b64 s[0:1], 0
	s_waitcnt lgkmcnt(0)
	v_add_f32_e32 v68, v68, v69
	v_xor_b32_e32 v69, 32, v236
	v_cmp_lt_i32_e32 vcc, v69, v70
	s_nop 1
	v_cndmask_b32_e32 v69, v236, v69, vcc
	v_lshlrev_b32_e32 v69, 2, v69
	v_mov_b32_e32 v69, v68
	s_nop 1
	v_permlane32_swap_b32 v69, v68
	s_waitcnt lgkmcnt(0)
	v_add_f32_e32 v68, v68, v69
	v_fmamk_f32 v68, v68, 0x3c800000, v231
	v_cmp_gt_f32_e32 vcc, s11, v68
	v_mul_f32_e32 v69, 0x4b800000, v68
	s_nop 0
	v_cndmask_b32_e32 v68, v68, v69, vcc
	v_rsq_f32_e32 v68, v68
	s_nop 0
	v_mul_f32_e32 v69, 0x45800000, v68
	v_cndmask_b32_e32 v68, v68, v69, vcc
	v_mul_f32_e32 v84, 0x3e38aa3b, v68
	global_load_dwordx4 v[68:71], v166, s[26:27] offset:16
	global_load_dwordx4 v[96:99], v166, s[26:27]
	v_pk_mul_f32 v[92:93], v[92:93], v[84:85] op_sel_hi:[1,0]
	v_pk_mul_f32 v[90:91], v[90:91], v[84:85] op_sel_hi:[1,0]
	v_pk_mul_f32 v[88:89], v[88:89], v[84:85] op_sel_hi:[1,0]
	v_pk_mul_f32 v[86:87], v[86:87], v[84:85] op_sel_hi:[1,0]
	v_pk_mul_f32 v[82:83], v[82:83], v[84:85] op_sel_hi:[1,0]
	v_pk_mul_f32 v[80:81], v[80:81], v[84:85] op_sel_hi:[1,0]
	v_pk_mul_f32 v[78:79], v[78:79], v[84:85] op_sel_hi:[1,0]
	v_pk_mul_f32 v[76:77], v[76:77], v[84:85] op_sel_hi:[1,0]
	s_waitcnt vmcnt(1)
	v_pk_mul_f32 v[86:87], v[70:71], v[86:87]
	s_waitcnt vmcnt(0)
	v_pk_mul_f32 v[90:91], v[98:99], v[90:91]
	v_pk_mul_f32 v[92:93], v[96:97], v[92:93]
	v_pk_mul_f32 v[70:71], v[68:69], v[88:89]
	v_cvt_pk_bf16_f32 v68, v92, v93
	v_cvt_pk_bf16_f32 v69, v90, v91
	v_cvt_pk_bf16_f32 v70, v70, v71
	v_cvt_pk_bf16_f32 v71, v86, v87
	global_store_dwordx4 v[94:95], v[68:71], off
	global_load_dwordx4 v[68:71], v166, s[26:27] offset:144
	s_nop 0
	global_load_dwordx4 v[86:89], v166, s[26:27] offset:128
	s_waitcnt vmcnt(1)
	v_pk_mul_f32 v[76:77], v[70:71], v[76:77]
	s_waitcnt vmcnt(0)
	v_pk_mul_f32 v[80:81], v[88:89], v[80:81]
	v_pk_mul_f32 v[82:83], v[86:87], v[82:83]
	v_pk_mul_f32 v[70:71], v[68:69], v[78:79]
	v_cvt_pk_bf16_f32 v68, v82, v83
	v_cvt_pk_bf16_f32 v69, v80, v81
	v_cvt_pk_bf16_f32 v70, v70, v71
	v_cvt_pk_bf16_f32 v71, v76, v77
	global_store_dwordx4 v[94:95], v[68:71], off offset:64

.LBB0_1820:
	s_nop 0
	v_fmamk_f32 v52, v169, 0x3a800000, v231
	v_cmp_gt_f32_e32 vcc, s11, v52
	v_mul_f32_e32 v53, 0x4b800000, v52
	v_or_b32_e32 v58, 16, v72
	v_cndmask_b32_e32 v52, v52, v53, vcc
	v_rsq_f32_e32 v52, v52
	s_mov_b64 s[0:1], -1
	v_mul_f32_e32 v53, 0x45800000, v52
	v_cndmask_b32_e32 v56, v52, v53, vcc
	s_and_b64 vcc, exec, s[18:19]
	s_cbranch_vccnz .LBB0_1822
	v_ashrrev_i32_e32 v59, 31, v58
	v_lshlrev_b64 v[52:53], 9, v[58:59]
	v_lshl_add_u64 v[52:53], s[24:25], 0, v[52:53]
	s_lshl_b32 s68, s14, 1
	v_pk_mul_f32 v[76:77], v[50:51], v[56:57] op_sel_hi:[1,0]
	v_pk_mul_f32 v[78:79], v[48:49], v[56:57] op_sel_hi:[1,0]
	v_lshl_add_u64 v[80:81], v[52:53], 0, s[68:69]
	v_pk_mul_f32 v[52:53], v[76:77], v[76:77]
	v_pk_mul_f32 v[54:55], v[78:79], v[78:79]
	v_pk_mul_f32 v[70:71], v[46:47], v[56:57] op_sel_hi:[1,0]
	v_pk_mov_b32 v[60:61], v[54:55], v[52:53] op_sel:[1,0]
	v_mov_b32_e32 v55, v53
	v_pk_add_f32 v[52:53], v[60:61], v[54:55]
	v_pk_mul_f32 v[74:75], v[44:45], v[56:57] op_sel_hi:[1,0]
	v_pk_add_f32 v[52:53], v[52:53], v[52:53] op_sel_hi:[0,1]
	v_pk_mul_f32 v[54:55], v[70:71], v[70:71]
	v_pk_mul_f32 v[60:61], v[74:75], v[74:75]
	v_pk_mul_f32 v[66:67], v[40:41], v[56:57] op_sel_hi:[1,0]
	v_pk_mov_b32 v[62:63], v[60:61], v[54:55] op_sel:[1,0]
	v_mov_b32_e32 v61, v55
	v_pk_mul_f32 v[64:65], v[42:43], v[56:57] op_sel_hi:[1,0]
	v_mul_f32_e32 v52, v66, v66
	v_pk_add_f32 v[54:55], v[62:63], v[60:61]
	v_pk_fma_f32 v[68:69], v[66:67], v[66:67], v[52:53] op_sel_hi:[1,1,0]
	v_mul_f32_e32 v52, v64, v64
	v_pk_add_f32 v[54:55], v[54:55], v[54:55] op_sel_hi:[0,1]
	v_pk_fma_f32 v[82:83], v[64:65], v[64:65], v[52:53] op_sel_hi:[1,1,0]
	v_pk_mul_f32 v[60:61], v[38:39], v[56:57] op_sel_hi:[1,0]
	v_pk_mul_f32 v[62:63], v[36:37], v[56:57] op_sel_hi:[1,0]
	v_mul_f32_e32 v52, v60, v60
	v_mul_f32_e32 v68, v62, v62
	v_mul_f32_e32 v82, v63, v63
	v_mul_f32_e32 v54, v61, v61
	v_pk_add_f32 v[68:69], v[68:69], v[82:83]
	v_pk_add_f32 v[52:53], v[52:53], v[54:55]
	v_and_b32_e32 v54, 64, v236
	v_pk_add_f32 v[52:53], v[68:69], v[52:53]
	v_add_u32_e32 v54, 64, v54
	v_add_f32_e32 v52, v52, v53
	v_mov_b32_e32 v53, v52
	s_nop 1
	v_permlane16_swap_b32 v53, v52
	v_mov_b32_e32 v141, v2
	v_lshl_add_u64 v[80:81], v[80:81], 0, v[140:141]
	s_mov_b64 s[0:1], 0
	s_waitcnt lgkmcnt(0)
	v_add_f32_e32 v52, v52, v53
	v_xor_b32_e32 v53, 32, v236
	v_cmp_lt_i32_e32 vcc, v53, v54
	s_nop 1
	v_cndmask_b32_e32 v53, v236, v53, vcc
	v_lshlrev_b32_e32 v53, 2, v53
	v_mov_b32_e32 v53, v52
	s_nop 1
	v_permlane32_swap_b32 v53, v52
	s_waitcnt lgkmcnt(0)
	v_add_f32_e32 v52, v52, v53
	v_fmamk_f32 v52, v52, 0x3c800000, v231
	v_cmp_gt_f32_e32 vcc, s11, v52
	v_mul_f32_e32 v53, 0x4b800000, v52
	s_nop 0
	v_cndmask_b32_e32 v52, v52, v53, vcc
	v_rsq_f32_e32 v52, v52
	s_nop 0
	v_mul_f32_e32 v53, 0x45800000, v52
	v_cndmask_b32_e32 v52, v52, v53, vcc
	v_mul_f32_e32 v68, 0x3e38aa3b, v52
	global_load_dwordx4 v[52:55], v166, s[26:27] offset:16
	global_load_dwordx4 v[82:85], v166, s[26:27]
	v_pk_mul_f32 v[78:79], v[78:79], v[68:69] op_sel_hi:[1,0]
	v_pk_mul_f32 v[76:77], v[76:77], v[68:69] op_sel_hi:[1,0]
	v_pk_mul_f32 v[74:75], v[74:75], v[68:69] op_sel_hi:[1,0]
	v_pk_mul_f32 v[70:71], v[70:71], v[68:69] op_sel_hi:[1,0]
	v_pk_mul_f32 v[66:67], v[66:67], v[68:69] op_sel_hi:[1,0]
	v_pk_mul_f32 v[64:65], v[64:65], v[68:69] op_sel_hi:[1,0]
	v_pk_mul_f32 v[62:63], v[62:63], v[68:69] op_sel_hi:[1,0]
	v_pk_mul_f32 v[60:61], v[60:61], v[68:69] op_sel_hi:[1,0]
	s_waitcnt vmcnt(1)
	v_pk_mul_f32 v[70:71], v[54:55], v[70:71]
	s_waitcnt vmcnt(0)
	v_pk_mul_f32 v[76:77], v[84:85], v[76:77]
	v_pk_mul_f32 v[78:79], v[82:83], v[78:79]
	v_pk_mul_f32 v[54:55], v[52:53], v[74:75]
	v_cvt_pk_bf16_f32 v52, v78, v79
	v_cvt_pk_bf16_f32 v53, v76, v77
	v_cvt_pk_bf16_f32 v54, v54, v55
	v_cvt_pk_bf16_f32 v55, v70, v71
	global_store_dwordx4 v[80:81], v[52:55], off
	global_load_dwordx4 v[52:55], v166, s[26:27] offset:144
	s_nop 0
	global_load_dwordx4 v[74:77], v166, s[26:27] offset:128
	s_waitcnt vmcnt(1)
	v_pk_mul_f32 v[60:61], v[54:55], v[60:61]
	s_waitcnt vmcnt(0)
	v_pk_mul_f32 v[64:65], v[76:77], v[64:65]
	v_pk_mul_f32 v[66:67], v[74:75], v[66:67]
	v_pk_mul_f32 v[54:55], v[52:53], v[62:63]
	v_cvt_pk_bf16_f32 v52, v66, v67
	v_cvt_pk_bf16_f32 v53, v64, v65
	v_cvt_pk_bf16_f32 v54, v54, v55
	v_cvt_pk_bf16_f32 v55, v60, v61
	global_store_dwordx4 v[80:81], v[52:55], off offset:64

.LBB0_1830:
	s_nop 0
	v_fmamk_f32 v36, v168, 0x3a800000, v231
	v_cmp_gt_f32_e32 vcc, s11, v36
	v_mul_f32_e32 v37, 0x4b800000, v36
	v_or_b32_e32 v42, 32, v72
	v_cndmask_b32_e32 v36, v36, v37, vcc
	v_rsq_f32_e32 v36, v36
	s_mov_b64 s[0:1], -1
	v_mul_f32_e32 v37, 0x45800000, v36
	v_cndmask_b32_e32 v40, v36, v37, vcc
	s_and_b64 vcc, exec, s[18:19]
	s_cbranch_vccnz .LBB0_1832
	v_ashrrev_i32_e32 v43, 31, v42
	v_lshlrev_b64 v[36:37], 9, v[42:43]
	v_lshl_add_u64 v[36:37], s[24:25], 0, v[36:37]
	s_lshl_b32 s68, s14, 1
	v_pk_mul_f32 v[58:59], v[34:35], v[40:41] op_sel_hi:[1,0]
	v_pk_mul_f32 v[60:61], v[32:33], v[40:41] op_sel_hi:[1,0]
	v_lshl_add_u64 v[62:63], v[36:37], 0, s[68:69]
	v_pk_mul_f32 v[36:37], v[58:59], v[58:59]
	v_pk_mul_f32 v[38:39], v[60:61], v[60:61]
	v_pk_mul_f32 v[54:55], v[30:31], v[40:41] op_sel_hi:[1,0]
	v_pk_mov_b32 v[44:45], v[38:39], v[36:37] op_sel:[1,0]
	v_mov_b32_e32 v39, v37
	v_pk_add_f32 v[36:37], v[44:45], v[38:39]
	v_pk_mul_f32 v[56:57], v[28:29], v[40:41] op_sel_hi:[1,0]
	v_pk_add_f32 v[36:37], v[36:37], v[36:37] op_sel_hi:[0,1]
	v_pk_mul_f32 v[38:39], v[54:55], v[54:55]
	v_pk_mul_f32 v[44:45], v[56:57], v[56:57]
	v_pk_mul_f32 v[50:51], v[24:25], v[40:41] op_sel_hi:[1,0]
	v_pk_mov_b32 v[46:47], v[44:45], v[38:39] op_sel:[1,0]
	v_mov_b32_e32 v45, v39
	v_pk_mul_f32 v[48:49], v[26:27], v[40:41] op_sel_hi:[1,0]
	v_mul_f32_e32 v36, v50, v50
	v_pk_add_f32 v[38:39], v[46:47], v[44:45]
	v_pk_fma_f32 v[52:53], v[50:51], v[50:51], v[36:37] op_sel_hi:[1,1,0]
	v_mul_f32_e32 v36, v48, v48
	v_pk_add_f32 v[38:39], v[38:39], v[38:39] op_sel_hi:[0,1]
	v_pk_fma_f32 v[64:65], v[48:49], v[48:49], v[36:37] op_sel_hi:[1,1,0]
	v_pk_mul_f32 v[44:45], v[22:23], v[40:41] op_sel_hi:[1,0]
	v_pk_mul_f32 v[46:47], v[20:21], v[40:41] op_sel_hi:[1,0]
	v_mul_f32_e32 v36, v44, v44
	v_mul_f32_e32 v52, v46, v46
	v_mul_f32_e32 v64, v47, v47
	v_mul_f32_e32 v38, v45, v45
	v_pk_add_f32 v[52:53], v[52:53], v[64:65]
	v_pk_add_f32 v[36:37], v[36:37], v[38:39]
	v_and_b32_e32 v38, 64, v236
	v_pk_add_f32 v[36:37], v[52:53], v[36:37]
	v_add_u32_e32 v38, 64, v38
	v_add_f32_e32 v36, v36, v37
	v_mov_b32_e32 v37, v36
	s_nop 1
	v_permlane16_swap_b32 v37, v36
	v_mov_b32_e32 v141, v2
	v_lshl_add_u64 v[62:63], v[62:63], 0, v[140:141]
	s_mov_b64 s[0:1], 0
	s_waitcnt lgkmcnt(0)
	v_add_f32_e32 v36, v36, v37
	v_xor_b32_e32 v37, 32, v236
	v_cmp_lt_i32_e32 vcc, v37, v38
	s_nop 1
	v_cndmask_b32_e32 v37, v236, v37, vcc
	v_lshlrev_b32_e32 v37, 2, v37
	v_mov_b32_e32 v37, v36
	s_nop 1
	v_permlane32_swap_b32 v37, v36
	s_waitcnt lgkmcnt(0)
	v_add_f32_e32 v36, v36, v37
	v_fmamk_f32 v36, v36, 0x3c800000, v231
	v_cmp_gt_f32_e32 vcc, s11, v36
	v_mul_f32_e32 v37, 0x4b800000, v36
	s_nop 0
	v_cndmask_b32_e32 v36, v36, v37, vcc
	v_rsq_f32_e32 v36, v36
	s_nop 0
	v_mul_f32_e32 v37, 0x45800000, v36
	v_cndmask_b32_e32 v36, v36, v37, vcc
	v_mul_f32_e32 v52, 0x3e38aa3b, v36
	global_load_dwordx4 v[36:39], v166, s[26:27] offset:16
	global_load_dwordx4 v[64:67], v166, s[26:27]
	v_pk_mul_f32 v[60:61], v[60:61], v[52:53] op_sel_hi:[1,0]
	v_pk_mul_f32 v[58:59], v[58:59], v[52:53] op_sel_hi:[1,0]
	v_pk_mul_f32 v[56:57], v[56:57], v[52:53] op_sel_hi:[1,0]
	v_pk_mul_f32 v[54:55], v[54:55], v[52:53] op_sel_hi:[1,0]
	v_pk_mul_f32 v[50:51], v[50:51], v[52:53] op_sel_hi:[1,0]
	v_pk_mul_f32 v[48:49], v[48:49], v[52:53] op_sel_hi:[1,0]
	v_pk_mul_f32 v[46:47], v[46:47], v[52:53] op_sel_hi:[1,0]
	v_pk_mul_f32 v[44:45], v[44:45], v[52:53] op_sel_hi:[1,0]
	s_waitcnt vmcnt(1)
	v_pk_mul_f32 v[54:55], v[38:39], v[54:55]
	s_waitcnt vmcnt(0)
	v_pk_mul_f32 v[58:59], v[66:67], v[58:59]
	v_pk_mul_f32 v[60:61], v[64:65], v[60:61]
	v_pk_mul_f32 v[38:39], v[36:37], v[56:57]
	v_cvt_pk_bf16_f32 v36, v60, v61
	v_cvt_pk_bf16_f32 v37, v58, v59
	v_cvt_pk_bf16_f32 v38, v38, v39
	v_cvt_pk_bf16_f32 v39, v54, v55
	global_store_dwordx4 v[62:63], v[36:39], off
	global_load_dwordx4 v[36:39], v166, s[26:27] offset:144
	s_nop 0
	global_load_dwordx4 v[54:57], v166, s[26:27] offset:128
	s_waitcnt vmcnt(1)
	v_pk_mul_f32 v[44:45], v[38:39], v[44:45]
	s_waitcnt vmcnt(0)
	v_pk_mul_f32 v[48:49], v[56:57], v[48:49]
	v_pk_mul_f32 v[50:51], v[54:55], v[50:51]
	v_pk_mul_f32 v[38:39], v[36:37], v[46:47]
	v_cvt_pk_bf16_f32 v36, v50, v51
	v_cvt_pk_bf16_f32 v37, v48, v49
	v_cvt_pk_bf16_f32 v38, v38, v39
	v_cvt_pk_bf16_f32 v39, v44, v45
	global_store_dwordx4 v[62:63], v[36:39], off offset:64

.LBB0_1840:
	s_nop 0
	v_fmamk_f32 v20, v167, 0x3a800000, v231
	v_cmp_gt_f32_e32 vcc, s11, v20
	v_mul_f32_e32 v21, 0x4b800000, v20
	v_or_b32_e32 v26, 48, v72
	v_cndmask_b32_e32 v20, v20, v21, vcc
	v_rsq_f32_e32 v20, v20
	s_mov_b64 s[0:1], -1
	v_mul_f32_e32 v21, 0x45800000, v20
	v_cndmask_b32_e32 v24, v20, v21, vcc
	s_and_b64 vcc, exec, s[18:19]
	s_cbranch_vccnz .LBB0_1842
	v_ashrrev_i32_e32 v27, 31, v26
	v_lshlrev_b64 v[20:21], 9, v[26:27]
	v_lshl_add_u64 v[20:21], s[24:25], 0, v[20:21]
	s_lshl_b32 s68, s14, 1
	v_pk_mul_f32 v[42:43], v[18:19], v[24:25] op_sel_hi:[1,0]
	v_pk_mul_f32 v[44:45], v[16:17], v[24:25] op_sel_hi:[1,0]
	v_lshl_add_u64 v[46:47], v[20:21], 0, s[68:69]
	v_pk_mul_f32 v[20:21], v[42:43], v[42:43]
	v_pk_mul_f32 v[22:23], v[44:45], v[44:45]
	v_pk_mul_f32 v[38:39], v[14:15], v[24:25] op_sel_hi:[1,0]
	v_pk_mov_b32 v[28:29], v[22:23], v[20:21] op_sel:[1,0]
	v_mov_b32_e32 v23, v21
	v_pk_add_f32 v[20:21], v[28:29], v[22:23]
	v_pk_mul_f32 v[40:41], v[12:13], v[24:25] op_sel_hi:[1,0]
	v_pk_add_f32 v[20:21], v[20:21], v[20:21] op_sel_hi:[0,1]
	v_pk_mul_f32 v[22:23], v[38:39], v[38:39]
	v_pk_mul_f32 v[28:29], v[40:41], v[40:41]
	v_pk_mul_f32 v[34:35], v[8:9], v[24:25] op_sel_hi:[1,0]
	v_pk_mov_b32 v[30:31], v[28:29], v[22:23] op_sel:[1,0]
	v_mov_b32_e32 v29, v23
	v_pk_mul_f32 v[32:33], v[10:11], v[24:25] op_sel_hi:[1,0]
	v_mul_f32_e32 v20, v34, v34
	v_pk_add_f32 v[22:23], v[30:31], v[28:29]
	v_pk_fma_f32 v[36:37], v[34:35], v[34:35], v[20:21] op_sel_hi:[1,1,0]
	v_mul_f32_e32 v20, v32, v32
	v_pk_add_f32 v[22:23], v[22:23], v[22:23] op_sel_hi:[0,1]
	v_pk_fma_f32 v[48:49], v[32:33], v[32:33], v[20:21] op_sel_hi:[1,1,0]
	v_pk_mul_f32 v[28:29], v[6:7], v[24:25] op_sel_hi:[1,0]
	v_pk_mul_f32 v[30:31], v[4:5], v[24:25] op_sel_hi:[1,0]
	v_mul_f32_e32 v20, v28, v28
	v_mul_f32_e32 v36, v30, v30
	v_mul_f32_e32 v48, v31, v31
	v_mul_f32_e32 v22, v29, v29
	v_pk_add_f32 v[36:37], v[36:37], v[48:49]
	v_pk_add_f32 v[20:21], v[20:21], v[22:23]
	v_and_b32_e32 v22, 64, v236
	v_pk_add_f32 v[20:21], v[36:37], v[20:21]
	v_add_u32_e32 v22, 64, v22
	v_add_f32_e32 v20, v20, v21
	v_mov_b32_e32 v21, v20
	s_nop 1
	v_permlane16_swap_b32 v21, v20
	v_mov_b32_e32 v141, v2
	v_lshl_add_u64 v[46:47], v[46:47], 0, v[140:141]
	s_mov_b64 s[0:1], 0
	s_waitcnt lgkmcnt(0)
	v_add_f32_e32 v20, v20, v21
	v_xor_b32_e32 v21, 32, v236
	v_cmp_lt_i32_e32 vcc, v21, v22
	s_nop 1
	v_cndmask_b32_e32 v21, v236, v21, vcc
	v_lshlrev_b32_e32 v21, 2, v21
	v_mov_b32_e32 v21, v20
	s_nop 1
	v_permlane32_swap_b32 v21, v20
	s_waitcnt lgkmcnt(0)
	v_add_f32_e32 v20, v20, v21
	v_fmamk_f32 v20, v20, 0x3c800000, v231
	v_cmp_gt_f32_e32 vcc, s11, v20
	v_mul_f32_e32 v21, 0x4b800000, v20
	s_nop 0
	v_cndmask_b32_e32 v20, v20, v21, vcc
	v_rsq_f32_e32 v20, v20
	s_nop 0
	v_mul_f32_e32 v21, 0x45800000, v20
	v_cndmask_b32_e32 v20, v20, v21, vcc
	v_mul_f32_e32 v36, 0x3e38aa3b, v20
	global_load_dwordx4 v[20:23], v166, s[26:27] offset:16
	global_load_dwordx4 v[48:51], v166, s[26:27]
	v_pk_mul_f32 v[44:45], v[44:45], v[36:37] op_sel_hi:[1,0]
	v_pk_mul_f32 v[42:43], v[42:43], v[36:37] op_sel_hi:[1,0]
	v_pk_mul_f32 v[40:41], v[40:41], v[36:37] op_sel_hi:[1,0]
	v_pk_mul_f32 v[38:39], v[38:39], v[36:37] op_sel_hi:[1,0]
	v_pk_mul_f32 v[34:35], v[34:35], v[36:37] op_sel_hi:[1,0]
	v_pk_mul_f32 v[32:33], v[32:33], v[36:37] op_sel_hi:[1,0]
	v_pk_mul_f32 v[30:31], v[30:31], v[36:37] op_sel_hi:[1,0]
	v_pk_mul_f32 v[28:29], v[28:29], v[36:37] op_sel_hi:[1,0]
	s_waitcnt vmcnt(1)
	v_pk_mul_f32 v[38:39], v[22:23], v[38:39]
	s_waitcnt vmcnt(0)
	v_pk_mul_f32 v[42:43], v[50:51], v[42:43]
	v_pk_mul_f32 v[44:45], v[48:49], v[44:45]
	v_pk_mul_f32 v[22:23], v[20:21], v[40:41]
	v_cvt_pk_bf16_f32 v20, v44, v45
	v_cvt_pk_bf16_f32 v21, v42, v43
	v_cvt_pk_bf16_f32 v22, v22, v23
	v_cvt_pk_bf16_f32 v23, v38, v39
	global_store_dwordx4 v[46:47], v[20:23], off
	global_load_dwordx4 v[20:23], v166, s[26:27] offset:144
	s_nop 0
	global_load_dwordx4 v[38:41], v166, s[26:27] offset:128
	s_waitcnt vmcnt(1)
	v_pk_mul_f32 v[28:29], v[22:23], v[28:29]
	s_waitcnt vmcnt(0)
	v_pk_mul_f32 v[32:33], v[40:41], v[32:33]
	v_pk_mul_f32 v[34:35], v[38:39], v[34:35]
	v_pk_mul_f32 v[22:23], v[20:21], v[30:31]
	v_cvt_pk_bf16_f32 v20, v34, v35
	v_cvt_pk_bf16_f32 v21, v32, v33
	v_cvt_pk_bf16_f32 v22, v22, v23
	v_cvt_pk_bf16_f32 v23, v28, v29
	global_store_dwordx4 v[46:47], v[20:23], off offset:64

.LBB0_1912:
	s_add_u32 s18, s16, s56
	s_addc_u32 s19, s17, s57
	s_add_u32 s26, s16, 0x7bfdd00
	s_addc_u32 s27, s17, 0
	s_cmp_eq_u32 s51, 12
	s_cselect_b32 s18, s14, s18
	s_cselect_b32 s19, s15, s19
	s_cselect_b32 s38, s8, s26
	s_cselect_b32 s39, s9, s27
	s_add_u32 s28, s18, 0x80
	s_addc_u32 s29, s19, 0
	s_add_u32 s26, s38, 0x80
	s_addc_u32 s27, s39, 0
	s_add_i32 s54, 0, 0x10000
	v_add_u32_e32 v148, s54, v1
	ds_read_b128 v[136:139], v148
	ds_read_b128 v[140:143], v148 offset:1024
	ds_read_b128 v[144:147], v148 offset:2048
	ds_read_b128 v[148:151], v148 offset:3072
	s_add_u32 s52, s16, 0x7c3dc80
	s_addc_u32 s53, s17, 0
	ds_read_b128 v[152:155], v3
	ds_read_b128 v[156:159], v3 offset:1024
	ds_read_b128 v[160:163], v3 offset:2048
	ds_read_b128 v[164:167], v3 offset:3072
	ds_read_b128 v[168:171], v3 offset:4096
	ds_read_b128 v[172:175], v3 offset:5120
	ds_read_b128 v[176:179], v3 offset:6144
	ds_read_b128 v[180:183], v3 offset:7168
	s_add_i32 m0, s42, 0xc000
	s_nop 0
	global_load_lds_dwordx4 v132, s[52:53]
	s_add_i32 m0, s42, 0xe000
	s_nop 0
	global_load_lds_dwordx4 v134, s[52:53]
	s_waitcnt lgkmcnt(8)
	s_barrier
	s_waitcnt lgkmcnt(0)
	s_setprio 1
	s_waitcnt lgkmcnt(0)
	v_mfma_f32_16x16x32_bf16 v[128:131], v[136:139], v[152:155], v[128:131]
	v_mfma_f32_16x16x32_bf16 v[124:127], v[144:147], v[152:155], v[124:127]
	v_mfma_f32_16x16x32_bf16 v[112:115], v[136:139], v[160:163], v[112:115]
	v_mfma_f32_16x16x32_bf16 v[108:111], v[144:147], v[160:163], v[108:111]
	v_mfma_f32_16x16x32_bf16 v[96:99], v[136:139], v[168:171], v[96:99]
	v_mfma_f32_16x16x32_bf16 v[92:95], v[144:147], v[168:171], v[92:95]
	v_mfma_f32_16x16x32_bf16 v[80:83], v[136:139], v[176:179], v[80:83]
	v_mfma_f32_16x16x32_bf16 v[76:79], v[144:147], v[176:179], v[76:79]
	v_mfma_f32_16x16x32_bf16 v[128:131], v[140:143], v[156:159], v[128:131]
	v_mfma_f32_16x16x32_bf16 v[124:127], v[148:151], v[156:159], v[124:127]
	v_mfma_f32_16x16x32_bf16 v[112:115], v[140:143], v[164:167], v[112:115]
	v_mfma_f32_16x16x32_bf16 v[108:111], v[148:151], v[164:167], v[108:111]
	v_mfma_f32_16x16x32_bf16 v[96:99], v[140:143], v[172:175], v[96:99]
	v_mfma_f32_16x16x32_bf16 v[92:95], v[148:151], v[172:175], v[92:95]
	v_mfma_f32_16x16x32_bf16 v[80:83], v[140:143], v[180:183], v[80:83]
	v_mfma_f32_16x16x32_bf16 v[76:79], v[148:151], v[180:183], v[76:79]
	s_setprio 0
	s_barrier
	s_add_i32 s55, 0, 0x14000
	v_add_u32_e32 v210, s55, v1
	s_mov_b64 s[52:53], s[18:19]
	s_add_i32 s54, s54, s41
	ds_read_b128 v[184:187], v210
	ds_read_b128 v[188:191], v210 offset:1024
	ds_read_b128 v[192:195], v210 offset:2048
	ds_read_b128 v[210:213], v210 offset:3072
	s_mov_b32 m0, s54
	s_nop 0
	global_load_lds_dwordx4 v132, s[52:53]
	s_add_i32 m0, s54, 0x2000
	s_nop 0
	global_load_lds_dwordx4 v134, s[52:53]
	s_barrier
	s_waitcnt lgkmcnt(0)
	s_setprio 1
	s_waitcnt lgkmcnt(0)
	v_mfma_f32_16x16x32_bf16 v[120:123], v[184:187], v[152:155], v[120:123]
	v_mfma_f32_16x16x32_bf16 v[116:119], v[192:195], v[152:155], v[116:119]
	v_mfma_f32_16x16x32_bf16 v[104:107], v[184:187], v[160:163], v[104:107]
	v_mfma_f32_16x16x32_bf16 v[100:103], v[192:195], v[160:163], v[100:103]
	v_mfma_f32_16x16x32_bf16 v[88:91], v[184:187], v[168:171], v[88:91]
	v_mfma_f32_16x16x32_bf16 v[84:87], v[192:195], v[168:171], v[84:87]
	v_mfma_f32_16x16x32_bf16 v[72:75], v[184:187], v[176:179], v[72:75]
	v_mfma_f32_16x16x32_bf16 v[68:71], v[192:195], v[176:179], v[68:71]
	v_mfma_f32_16x16x32_bf16 v[120:123], v[188:191], v[156:159], v[120:123]
	v_mfma_f32_16x16x32_bf16 v[116:119], v[210:213], v[156:159], v[116:119]
	v_mfma_f32_16x16x32_bf16 v[104:107], v[188:191], v[164:167], v[104:107]
	v_mfma_f32_16x16x32_bf16 v[100:103], v[210:213], v[164:167], v[100:103]
	v_mfma_f32_16x16x32_bf16 v[88:91], v[188:191], v[172:175], v[88:91]
	v_mfma_f32_16x16x32_bf16 v[84:87], v[210:213], v[172:175], v[84:87]
	v_mfma_f32_16x16x32_bf16 v[72:75], v[188:191], v[180:183], v[72:75]
	v_mfma_f32_16x16x32_bf16 v[68:71], v[210:213], v[180:183], v[68:71]
	s_setprio 0
	s_mov_b64 s[52:53], s[38:39]
	s_mov_b32 m0, s42
	s_barrier
	ds_read_b128 v[152:155], v3 offset:16384
	ds_read_b128 v[156:159], v3 offset:17408
	ds_read_b128 v[160:163], v3 offset:18432
	ds_read_b128 v[164:167], v3 offset:19456
	ds_read_b128 v[168:171], v3 offset:20480
	ds_read_b128 v[172:175], v3 offset:21504
	ds_read_b128 v[176:179], v3 offset:22528
	ds_read_b128 v[180:183], v3 offset:23552
	s_nop 0
	global_load_lds_dwordx4 v132, s[52:53]
	s_mov_b32 m0, s43
	s_nop 0
	global_load_lds_dwordx4 v134, s[52:53]
	s_barrier
	s_waitcnt lgkmcnt(0)
	s_setprio 1
	s_waitcnt lgkmcnt(0)
	v_mfma_f32_16x16x32_bf16 v[64:67], v[136:139], v[152:155], v[64:67]
	v_mfma_f32_16x16x32_bf16 v[60:63], v[144:147], v[152:155], v[60:63]
	v_mfma_f32_16x16x32_bf16 v[48:51], v[136:139], v[160:163], v[48:51]
	v_mfma_f32_16x16x32_bf16 v[44:47], v[144:147], v[160:163], v[44:47]
	v_mfma_f32_16x16x32_bf16 v[32:35], v[136:139], v[168:171], v[32:35]
	v_mfma_f32_16x16x32_bf16 v[28:31], v[144:147], v[168:171], v[28:31]
	v_mfma_f32_16x16x32_bf16 v[16:19], v[136:139], v[176:179], v[16:19]
	v_mfma_f32_16x16x32_bf16 v[12:15], v[144:147], v[176:179], v[12:15]
	v_mfma_f32_16x16x32_bf16 v[64:67], v[140:143], v[156:159], v[64:67]
	v_mfma_f32_16x16x32_bf16 v[60:63], v[148:151], v[156:159], v[60:63]
	v_mfma_f32_16x16x32_bf16 v[48:51], v[140:143], v[164:167], v[48:51]
	v_mfma_f32_16x16x32_bf16 v[44:47], v[148:151], v[164:167], v[44:47]
	v_mfma_f32_16x16x32_bf16 v[32:35], v[140:143], v[172:175], v[32:35]
	v_mfma_f32_16x16x32_bf16 v[28:31], v[148:151], v[172:175], v[28:31]
	v_mfma_f32_16x16x32_bf16 v[16:19], v[140:143], v[180:183], v[16:19]
	v_mfma_f32_16x16x32_bf16 v[12:15], v[148:151], v[180:183], v[12:15]
	s_setprio 0
	s_barrier
	s_add_u32 s52, s18, 0x40000
	s_addc_u32 s53, s19, 0
	s_add_i32 s54, s55, s41
	s_mov_b32 m0, s54
	s_nop 0
	global_load_lds_dwordx4 v132, s[52:53]
	s_add_i32 m0, s54, 0x2000
	s_nop 0
	global_load_lds_dwordx4 v134, s[52:53]
	s_waitcnt vmcnt(6)
	s_barrier
	s_setprio 1
	v_mfma_f32_16x16x32_bf16 v[56:59], v[184:187], v[152:155], v[56:59]
	v_mfma_f32_16x16x32_bf16 v[52:55], v[192:195], v[152:155], v[52:55]
	v_mfma_f32_16x16x32_bf16 v[40:43], v[184:187], v[160:163], v[40:43]
	v_mfma_f32_16x16x32_bf16 v[36:39], v[192:195], v[160:163], v[36:39]
	v_mfma_f32_16x16x32_bf16 v[24:27], v[184:187], v[168:171], v[24:27]
	v_mfma_f32_16x16x32_bf16 v[20:23], v[192:195], v[168:171], v[20:23]
	v_mfma_f32_16x16x32_bf16 v[8:11], v[184:187], v[176:179], v[8:11]
	v_mfma_f32_16x16x32_bf16 v[4:7], v[192:195], v[176:179], v[4:7]
	v_mfma_f32_16x16x32_bf16 v[56:59], v[188:191], v[156:159], v[56:59]
	v_mfma_f32_16x16x32_bf16 v[52:55], v[210:213], v[156:159], v[52:55]
	v_mfma_f32_16x16x32_bf16 v[40:43], v[188:191], v[164:167], v[40:43]
	v_mfma_f32_16x16x32_bf16 v[36:39], v[210:213], v[164:167], v[36:39]
	v_mfma_f32_16x16x32_bf16 v[24:27], v[188:191], v[172:175], v[24:27]
	v_mfma_f32_16x16x32_bf16 v[20:23], v[210:213], v[172:175], v[20:23]
	v_mfma_f32_16x16x32_bf16 v[8:11], v[188:191], v[180:183], v[8:11]
	v_mfma_f32_16x16x32_bf16 v[4:7], v[210:213], v[180:183], v[4:7]
	s_setprio 0
	s_add_i32 s52, 0, 0x18000
	v_add_u32_e32 v148, s52, v1
	s_barrier
	ds_read_b128 v[136:139], v148
	ds_read_b128 v[140:143], v148 offset:1024
	ds_read_b128 v[144:147], v148 offset:2048
	ds_read_b128 v[148:151], v148 offset:3072
	s_add_u32 s38, s38, 0x40000
	s_addc_u32 s39, s39, 0
	s_mov_b32 m0, s44
	ds_read_b128 v[152:155], v3 offset:32768
	ds_read_b128 v[156:159], v3 offset:33792
	ds_read_b128 v[160:163], v3 offset:34816
	ds_read_b128 v[164:167], v3 offset:35840
	ds_read_b128 v[168:171], v3 offset:36864
	ds_read_b128 v[172:175], v3 offset:37888
	ds_read_b128 v[176:179], v3 offset:38912
	ds_read_b128 v[180:183], v3 offset:39936
	s_nop 0
	global_load_lds_dwordx4 v132, s[38:39]
	s_mov_b32 m0, s45
	s_nop 0
	global_load_lds_dwordx4 v134, s[38:39]
	s_waitcnt lgkmcnt(8)
	s_barrier
	s_waitcnt lgkmcnt(0)
	s_setprio 1
	s_waitcnt lgkmcnt(0)
	v_mfma_f32_16x16x32_bf16 v[128:131], v[136:139], v[152:155], v[128:131]
	v_mfma_f32_16x16x32_bf16 v[124:127], v[144:147], v[152:155], v[124:127]
	v_mfma_f32_16x16x32_bf16 v[112:115], v[136:139], v[160:163], v[112:115]
	v_mfma_f32_16x16x32_bf16 v[108:111], v[144:147], v[160:163], v[108:111]
	v_mfma_f32_16x16x32_bf16 v[96:99], v[136:139], v[168:171], v[96:99]
	v_mfma_f32_16x16x32_bf16 v[92:95], v[144:147], v[168:171], v[92:95]
	v_mfma_f32_16x16x32_bf16 v[80:83], v[136:139], v[176:179], v[80:83]
	v_mfma_f32_16x16x32_bf16 v[76:79], v[144:147], v[176:179], v[76:79]
	v_mfma_f32_16x16x32_bf16 v[128:131], v[140:143], v[156:159], v[128:131]
	v_mfma_f32_16x16x32_bf16 v[124:127], v[148:151], v[156:159], v[124:127]
	v_mfma_f32_16x16x32_bf16 v[112:115], v[140:143], v[164:167], v[112:115]
	v_mfma_f32_16x16x32_bf16 v[108:111], v[148:151], v[164:167], v[108:111]
	v_mfma_f32_16x16x32_bf16 v[96:99], v[140:143], v[172:175], v[96:99]
	v_mfma_f32_16x16x32_bf16 v[92:95], v[148:151], v[172:175], v[92:95]
	v_mfma_f32_16x16x32_bf16 v[80:83], v[140:143], v[180:183], v[80:83]
	v_mfma_f32_16x16x32_bf16 v[76:79], v[148:151], v[180:183], v[76:79]
	s_setprio 0
	s_barrier
	s_add_i32 s38, 0, 0x1c000
	v_add_u32_e32 v210, s38, v1
	s_add_i32 s39, s52, s41
	ds_read_b128 v[184:187], v210
	ds_read_b128 v[188:191], v210 offset:1024
	ds_read_b128 v[192:195], v210 offset:2048
	ds_read_b128 v[210:213], v210 offset:3072
	s_mov_b32 m0, s39
	s_nop 0
	global_load_lds_dwordx4 v132, s[28:29]
	s_add_i32 m0, s39, 0x2000
	s_nop 0
	global_load_lds_dwordx4 v134, s[28:29]
	s_barrier
	s_waitcnt lgkmcnt(0)
	s_setprio 1
	s_waitcnt lgkmcnt(0)
	v_mfma_f32_16x16x32_bf16 v[120:123], v[184:187], v[152:155], v[120:123]
	v_mfma_f32_16x16x32_bf16 v[116:119], v[192:195], v[152:155], v[116:119]
	v_mfma_f32_16x16x32_bf16 v[104:107], v[184:187], v[160:163], v[104:107]
	v_mfma_f32_16x16x32_bf16 v[100:103], v[192:195], v[160:163], v[100:103]
	v_mfma_f32_16x16x32_bf16 v[88:91], v[184:187], v[168:171], v[88:91]
	v_mfma_f32_16x16x32_bf16 v[84:87], v[192:195], v[168:171], v[84:87]
	v_mfma_f32_16x16x32_bf16 v[72:75], v[184:187], v[176:179], v[72:75]
	v_mfma_f32_16x16x32_bf16 v[68:71], v[192:195], v[176:179], v[68:71]
	v_mfma_f32_16x16x32_bf16 v[120:123], v[188:191], v[156:159], v[120:123]
	v_mfma_f32_16x16x32_bf16 v[116:119], v[210:213], v[156:159], v[116:119]
	v_mfma_f32_16x16x32_bf16 v[104:107], v[188:191], v[164:167], v[104:107]
	v_mfma_f32_16x16x32_bf16 v[100:103], v[210:213], v[164:167], v[100:103]
	v_mfma_f32_16x16x32_bf16 v[88:91], v[188:191], v[172:175], v[88:91]
	v_mfma_f32_16x16x32_bf16 v[84:87], v[210:213], v[172:175], v[84:87]
	v_mfma_f32_16x16x32_bf16 v[72:75], v[188:191], v[180:183], v[72:75]
	v_mfma_f32_16x16x32_bf16 v[68:71], v[210:213], v[180:183], v[68:71]
	s_setprio 0
	s_mov_b32 m0, s46
	s_barrier
	ds_read_b128 v[152:155], v3 offset:49152
	ds_read_b128 v[156:159], v3 offset:50176
	ds_read_b128 v[160:163], v3 offset:51200
	ds_read_b128 v[164:167], v3 offset:52224
	ds_read_b128 v[168:171], v3 offset:53248
	ds_read_b128 v[172:175], v3 offset:54272
	ds_read_b128 v[176:179], v3 offset:55296
	ds_read_b128 v[180:183], v3 offset:56320
	s_nop 0
	global_load_lds_dwordx4 v132, s[26:27]
	s_mov_b32 m0, s47
	s_nop 0
	global_load_lds_dwordx4 v134, s[26:27]
	s_barrier
	s_waitcnt lgkmcnt(0)
	s_setprio 1
	s_waitcnt lgkmcnt(0)
	v_mfma_f32_16x16x32_bf16 v[64:67], v[136:139], v[152:155], v[64:67]
	v_mfma_f32_16x16x32_bf16 v[60:63], v[144:147], v[152:155], v[60:63]
	v_mfma_f32_16x16x32_bf16 v[48:51], v[136:139], v[160:163], v[48:51]
	v_mfma_f32_16x16x32_bf16 v[44:47], v[144:147], v[160:163], v[44:47]
	v_mfma_f32_16x16x32_bf16 v[32:35], v[136:139], v[168:171], v[32:35]
	v_mfma_f32_16x16x32_bf16 v[28:31], v[144:147], v[168:171], v[28:31]
	v_mfma_f32_16x16x32_bf16 v[16:19], v[136:139], v[176:179], v[16:19]
	v_mfma_f32_16x16x32_bf16 v[12:15], v[144:147], v[176:179], v[12:15]
	v_mfma_f32_16x16x32_bf16 v[64:67], v[140:143], v[156:159], v[64:67]
	v_mfma_f32_16x16x32_bf16 v[60:63], v[148:151], v[156:159], v[60:63]
	v_mfma_f32_16x16x32_bf16 v[48:51], v[140:143], v[164:167], v[48:51]
	v_mfma_f32_16x16x32_bf16 v[44:47], v[148:151], v[164:167], v[44:47]
	v_mfma_f32_16x16x32_bf16 v[32:35], v[140:143], v[172:175], v[32:35]
	v_mfma_f32_16x16x32_bf16 v[28:31], v[148:151], v[172:175], v[28:31]
	v_mfma_f32_16x16x32_bf16 v[16:19], v[140:143], v[180:183], v[16:19]
	v_mfma_f32_16x16x32_bf16 v[12:15], v[148:151], v[180:183], v[12:15]
	s_setprio 0
	s_barrier
	s_add_u32 s18, s18, 0x40080
	s_addc_u32 s19, s19, 0
	s_add_i32 s26, s38, s41
	s_mov_b32 m0, s26
	s_nop 0
	global_load_lds_dwordx4 v132, s[18:19]
	s_add_i32 m0, s26, 0x2000
	s_nop 0
	global_load_lds_dwordx4 v134, s[18:19]
	s_waitcnt vmcnt(6)
	s_barrier
	s_setprio 1
	v_mfma_f32_16x16x32_bf16 v[56:59], v[184:187], v[152:155], v[56:59]
	v_mfma_f32_16x16x32_bf16 v[52:55], v[192:195], v[152:155], v[52:55]
	v_mfma_f32_16x16x32_bf16 v[40:43], v[184:187], v[160:163], v[40:43]
	v_mfma_f32_16x16x32_bf16 v[36:39], v[192:195], v[160:163], v[36:39]
	v_mfma_f32_16x16x32_bf16 v[24:27], v[184:187], v[168:171], v[24:27]
	v_mfma_f32_16x16x32_bf16 v[20:23], v[192:195], v[168:171], v[20:23]
	v_mfma_f32_16x16x32_bf16 v[8:11], v[184:187], v[176:179], v[8:11]
	v_mfma_f32_16x16x32_bf16 v[4:7], v[192:195], v[176:179], v[4:7]
	v_mfma_f32_16x16x32_bf16 v[56:59], v[188:191], v[156:159], v[56:59]
	v_mfma_f32_16x16x32_bf16 v[52:55], v[210:213], v[156:159], v[52:55]
	v_mfma_f32_16x16x32_bf16 v[40:43], v[188:191], v[164:167], v[40:43]
	v_mfma_f32_16x16x32_bf16 v[36:39], v[210:213], v[164:167], v[36:39]
	v_mfma_f32_16x16x32_bf16 v[24:27], v[188:191], v[172:175], v[24:27]
	v_mfma_f32_16x16x32_bf16 v[20:23], v[210:213], v[172:175], v[20:23]
	v_mfma_f32_16x16x32_bf16 v[8:11], v[188:191], v[180:183], v[8:11]
	v_mfma_f32_16x16x32_bf16 v[4:7], v[210:213], v[180:183], v[4:7]
	s_setprio 0
	s_add_i32 s51, s51, 2
	s_add_u32 s16, s16, 0x100
	s_addc_u32 s17, s17, 0
	s_cmp_gt_u32 s51, 13
	s_barrier
	s_cbranch_scc0 .LBB0_1912
	s_add_u32 s8, s24, s50
	s_addc_u32 s9, s25, 0
	s_add_u32 s18, s24, 0x7c7dc00
	s_addc_u32 s19, s25, 0
	s_add_u32 s28, s24, 0x94ddc00
	s_addc_u32 s29, s25, 0
	s_lshl_b64 s[6:7], s[6:7], 2
	s_add_u32 s26, s0, s6
	s_addc_u32 s27, s1, s7
	s_add_u32 s0, s30, s49
	s_addc_u32 s1, s31, s48
	v_mov_b32_e32 v141, v0
	s_add_u32 s6, s0, 0x53fc000
	s_addc_u32 s7, s1, 0
	v_readfirstlane_b32 s0, v141
	s_ashr_i32 s15, s0, 2
	v_and_b32_e32 v164, 15, v141
	s_andn2_b32 s15, s15, 63
	v_or_b32_e32 v132, s15, v164
	v_ashrrev_i32_e32 v133, 31, v132
	s_and_b32 s14, s0, 0xc0
	v_lshl_add_u64 v[132:133], v[132:133], 2, s[8:9]
	s_mov_b32 s0, 0x15000
	v_add_co_u32_e32 v132, vcc, s0, v132
	v_readlane_b32 s8, v253, 54
	s_nop 0
	v_addc_co_u32_e32 v133, vcc, 0, v133, vcc
	global_load_dword v1, v[132:133], off
	global_load_dword v168, v[132:133], off offset:64
	global_load_dword v167, v[132:133], off offset:128
	global_load_dword v166, v[132:133], off offset:192
	global_load_dword v165, v[132:133], off offset:512
	global_load_dword v163, v[132:133], off offset:576
	global_load_dword v162, v[132:133], off offset:640
	global_load_dword v151, v[132:133], off offset:704
	s_add_i32 s38, s15, 0x4000
	v_readlane_b32 s9, v253, 55
	v_or_b32_e32 v138, s38, v164
	s_mov_b64 s[0:1], -1
	s_waitcnt vmcnt(0)
	v_fmamk_f32 v1, v1, 0x3a800000, v231
	v_cmp_gt_f32_e32 vcc, s11, v1
	v_mul_f32_e32 v3, 0x4b800000, v1
	s_nop 0
	v_cndmask_b32_e32 v1, v1, v3, vcc
	v_rsq_f32_e32 v1, v1
	s_nop 0
	v_mul_f32_e32 v3, 0x45800000, v1
	v_cndmask_b32_e32 v140, v1, v3, vcc
	v_lshrrev_b32_e32 v1, 1, v141
	v_and_b32_e32 v1, 24, v1
	s_and_b64 vcc, exec, s[8:9]
	v_lshlrev_b32_e32 v3, 2, v1
	v_lshlrev_b32_e32 v136, 1, v1
	s_cbranch_vccz .LBB0_1915
	v_ashrrev_i32_e32 v139, 31, v138
	v_lshlrev_b64 v[132:133], 9, v[138:139]
	v_lshl_add_u64 v[132:133], s[28:29], 0, v[132:133]
	s_lshl_b32 s68, s14, 1
	v_pk_mul_f32 v[156:157], v[130:131], v[140:141] op_sel_hi:[1,0]
	v_pk_mul_f32 v[158:159], v[128:129], v[140:141] op_sel_hi:[1,0]
	v_lshl_add_u64 v[160:161], v[132:133], 0, s[68:69]
	v_pk_mul_f32 v[132:133], v[156:157], v[156:157]
	v_pk_mul_f32 v[134:135], v[158:159], v[158:159]
	v_pk_mul_f32 v[152:153], v[126:127], v[140:141] op_sel_hi:[1,0]
	v_pk_mov_b32 v[142:143], v[134:135], v[132:133] op_sel:[1,0]
	v_mov_b32_e32 v135, v133
	v_pk_add_f32 v[132:133], v[142:143], v[134:135]
	v_pk_mul_f32 v[154:155], v[124:125], v[140:141] op_sel_hi:[1,0]
	v_pk_add_f32 v[132:133], v[132:133], v[132:133] op_sel_hi:[0,1]
	v_pk_mul_f32 v[134:135], v[152:153], v[152:153]
	v_pk_mul_f32 v[142:143], v[154:155], v[154:155]
	v_pk_mul_f32 v[148:149], v[120:121], v[140:141] op_sel_hi:[1,0]
	v_pk_mov_b32 v[144:145], v[142:143], v[134:135] op_sel:[1,0]
	v_mov_b32_e32 v143, v135
	v_pk_mul_f32 v[146:147], v[122:123], v[140:141] op_sel_hi:[1,0]
	v_mul_f32_e32 v132, v148, v148
	v_pk_add_f32 v[134:135], v[144:145], v[142:143]
	v_pk_fma_f32 v[170:171], v[148:149], v[148:149], v[132:133] op_sel_hi:[1,1,0]
	v_mul_f32_e32 v132, v146, v146
	v_pk_add_f32 v[134:135], v[134:135], v[134:135] op_sel_hi:[0,1]
	v_pk_fma_f32 v[172:173], v[146:147], v[146:147], v[132:133] op_sel_hi:[1,1,0]
	v_pk_mul_f32 v[142:143], v[118:119], v[140:141] op_sel_hi:[1,0]
	v_pk_mul_f32 v[144:145], v[116:117], v[140:141] op_sel_hi:[1,0]
	v_mul_f32_e32 v132, v142, v142
	v_mul_f32_e32 v170, v144, v144
	v_mul_f32_e32 v172, v145, v145
	v_mul_f32_e32 v134, v143, v143
	v_pk_add_f32 v[170:171], v[170:171], v[172:173]
	v_pk_add_f32 v[132:133], v[132:133], v[134:135]
	v_and_b32_e32 v134, 64, v236
	v_pk_add_f32 v[132:133], v[170:171], v[132:133]
	v_add_u32_e32 v134, 64, v134
	v_add_f32_e32 v132, v132, v133
	v_mov_b32_e32 v133, v132
	s_nop 1
	v_permlane16_swap_b32 v133, v132
	v_mov_b32_e32 v137, v2
	v_lshl_add_u64 v[160:161], v[160:161], 0, v[136:137]
	s_mov_b64 s[0:1], 0
	s_waitcnt lgkmcnt(0)
	v_add_f32_e32 v132, v132, v133
	v_xor_b32_e32 v133, 32, v236
	v_cmp_lt_i32_e32 vcc, v133, v134
	s_nop 1
	v_cndmask_b32_e32 v133, v236, v133, vcc
	v_lshlrev_b32_e32 v133, 2, v133
	v_mov_b32_e32 v133, v132
	s_nop 1
	v_permlane32_swap_b32 v133, v132
	s_waitcnt lgkmcnt(0)
	v_add_f32_e32 v132, v132, v133
	v_fmamk_f32 v132, v132, 0x3c800000, v231
	v_cmp_gt_f32_e32 vcc, s11, v132
	v_mul_f32_e32 v133, 0x4b800000, v132
	s_nop 0
	v_cndmask_b32_e32 v132, v132, v133, vcc
	v_rsq_f32_e32 v132, v132
	s_nop 0
	v_mul_f32_e32 v133, 0x45800000, v132
	v_cndmask_b32_e32 v132, v132, v133, vcc
	v_mul_f32_e32 v150, 0x3e38aa3b, v132
	global_load_dwordx4 v[132:135], v3, s[26:27] offset:16
	global_load_dwordx4 v[170:173], v3, s[26:27]
	v_pk_mul_f32 v[158:159], v[158:159], v[150:151] op_sel_hi:[1,0]
	v_pk_mul_f32 v[156:157], v[156:157], v[150:151] op_sel_hi:[1,0]
	v_pk_mul_f32 v[154:155], v[154:155], v[150:151] op_sel_hi:[1,0]
	v_pk_mul_f32 v[152:153], v[152:153], v[150:151] op_sel_hi:[1,0]
	v_pk_mul_f32 v[148:149], v[148:149], v[150:151] op_sel_hi:[1,0]
	v_pk_mul_f32 v[146:147], v[146:147], v[150:151] op_sel_hi:[1,0]
	v_pk_mul_f32 v[144:145], v[144:145], v[150:151] op_sel_hi:[1,0]
	v_pk_mul_f32 v[142:143], v[142:143], v[150:151] op_sel_hi:[1,0]
	s_waitcnt vmcnt(1)
	v_pk_mul_f32 v[152:153], v[134:135], v[152:153]
	s_waitcnt vmcnt(0)
	v_pk_mul_f32 v[156:157], v[172:173], v[156:157]
	v_pk_mul_f32 v[158:159], v[170:171], v[158:159]
	v_pk_mul_f32 v[134:135], v[132:133], v[154:155]
	v_cvt_pk_bf16_f32 v132, v158, v159
	v_cvt_pk_bf16_f32 v133, v156, v157
	v_cvt_pk_bf16_f32 v134, v134, v135
	v_cvt_pk_bf16_f32 v135, v152, v153
	global_store_dwordx4 v[160:161], v[132:135], off
	global_load_dwordx4 v[132:135], v3, s[26:27] offset:144
	s_nop 0
	global_load_dwordx4 v[152:155], v3, s[26:27] offset:128
	s_waitcnt vmcnt(1)
	v_pk_mul_f32 v[142:143], v[134:135], v[142:143]
	s_waitcnt vmcnt(0)
	v_pk_mul_f32 v[146:147], v[154:155], v[146:147]
	v_pk_mul_f32 v[148:149], v[152:153], v[148:149]
	v_pk_mul_f32 v[134:135], v[132:133], v[144:145]
	v_cvt_pk_bf16_f32 v132, v148, v149
	v_cvt_pk_bf16_f32 v133, v146, v147
	v_cvt_pk_bf16_f32 v134, v134, v135
	v_cvt_pk_bf16_f32 v135, v142, v143
	global_store_dwordx4 v[160:161], v[132:135], off offset:64

.LBB0_1923:
	s_nop 0
	v_fmamk_f32 v116, v168, 0x3a800000, v231
	v_cmp_gt_f32_e32 vcc, s11, v116
	v_mul_f32_e32 v117, 0x4b800000, v116
	v_readlane_b32 s8, v253, 54
	v_cndmask_b32_e32 v116, v116, v117, vcc
	v_rsq_f32_e32 v116, v116
	v_readlane_b32 s9, v253, 55
	v_or_b32_e32 v122, 16, v138
	s_mov_b64 s[0:1], -1
	v_mul_f32_e32 v117, 0x45800000, v116
	v_cndmask_b32_e32 v120, v116, v117, vcc
	v_cndmask_b32_e64 v116, 0, 1, s[8:9]
	v_cmp_ne_u32_e64 s[16:17], 1, v116
	s_andn2_b64 vcc, exec, s[8:9]
	s_cbranch_vccnz .LBB0_1925
	v_ashrrev_i32_e32 v123, 31, v122
	v_lshlrev_b64 v[116:117], 9, v[122:123]
	v_lshl_add_u64 v[116:117], s[28:29], 0, v[116:117]
	s_lshl_b32 s68, s14, 1
	v_pk_mul_f32 v[144:145], v[114:115], v[120:121] op_sel_hi:[1,0]
	v_pk_mul_f32 v[146:147], v[112:113], v[120:121] op_sel_hi:[1,0]
	v_lshl_add_u64 v[148:149], v[116:117], 0, s[68:69]
	v_pk_mul_f32 v[116:117], v[144:145], v[144:145]
	v_pk_mul_f32 v[118:119], v[146:147], v[146:147]
	v_pk_mul_f32 v[140:141], v[110:111], v[120:121] op_sel_hi:[1,0]
	v_pk_mov_b32 v[124:125], v[118:119], v[116:117] op_sel:[1,0]
	v_mov_b32_e32 v119, v117
	v_pk_add_f32 v[116:117], v[124:125], v[118:119]
	v_pk_mul_f32 v[142:143], v[108:109], v[120:121] op_sel_hi:[1,0]
	v_pk_add_f32 v[116:117], v[116:117], v[116:117] op_sel_hi:[0,1]
	v_pk_mul_f32 v[118:119], v[140:141], v[140:141]
	v_pk_mul_f32 v[124:125], v[142:143], v[142:143]
	v_pk_mul_f32 v[130:131], v[104:105], v[120:121] op_sel_hi:[1,0]
	v_pk_mov_b32 v[126:127], v[124:125], v[118:119] op_sel:[1,0]
	v_mov_b32_e32 v125, v119
	v_pk_mul_f32 v[128:129], v[106:107], v[120:121] op_sel_hi:[1,0]
	v_mul_f32_e32 v116, v130, v130
	v_pk_add_f32 v[118:119], v[126:127], v[124:125]
	v_pk_fma_f32 v[134:135], v[130:131], v[130:131], v[116:117] op_sel_hi:[1,1,0]
	v_mul_f32_e32 v116, v128, v128
	v_pk_add_f32 v[118:119], v[118:119], v[118:119] op_sel_hi:[0,1]
	v_pk_fma_f32 v[152:153], v[128:129], v[128:129], v[116:117] op_sel_hi:[1,1,0]
	v_pk_mul_f32 v[124:125], v[102:103], v[120:121] op_sel_hi:[1,0]
	v_pk_mul_f32 v[126:127], v[100:101], v[120:121] op_sel_hi:[1,0]
	v_mul_f32_e32 v116, v124, v124
	v_mul_f32_e32 v134, v126, v126
	v_mul_f32_e32 v152, v127, v127
	v_mul_f32_e32 v118, v125, v125
	v_pk_add_f32 v[134:135], v[134:135], v[152:153]
	v_pk_add_f32 v[116:117], v[116:117], v[118:119]
	v_and_b32_e32 v118, 64, v236
	v_pk_add_f32 v[116:117], v[134:135], v[116:117]
	v_add_u32_e32 v118, 64, v118
	v_add_f32_e32 v116, v116, v117
	v_mov_b32_e32 v117, v116
	s_nop 1
	v_permlane16_swap_b32 v117, v116
	v_mov_b32_e32 v137, v2
	v_lshl_add_u64 v[148:149], v[148:149], 0, v[136:137]
	s_mov_b64 s[0:1], 0
	s_waitcnt lgkmcnt(0)
	v_add_f32_e32 v116, v116, v117
	v_xor_b32_e32 v117, 32, v236
	v_cmp_lt_i32_e32 vcc, v117, v118
	s_nop 1
	v_cndmask_b32_e32 v117, v236, v117, vcc
	v_lshlrev_b32_e32 v117, 2, v117
	v_mov_b32_e32 v117, v116
	s_nop 1
	v_permlane32_swap_b32 v117, v116
	s_waitcnt lgkmcnt(0)
	v_add_f32_e32 v116, v116, v117
	v_fmamk_f32 v116, v116, 0x3c800000, v231
	v_cmp_gt_f32_e32 vcc, s11, v116
	v_mul_f32_e32 v117, 0x4b800000, v116
	s_nop 0
	v_cndmask_b32_e32 v116, v116, v117, vcc
	v_rsq_f32_e32 v116, v116
	s_nop 0
	v_mul_f32_e32 v117, 0x45800000, v116
	v_cndmask_b32_e32 v116, v116, v117, vcc
	v_mul_f32_e32 v134, 0x3e38aa3b, v116
	global_load_dwordx4 v[116:119], v3, s[26:27] offset:16
	global_load_dwordx4 v[152:155], v3, s[26:27]
	v_pk_mul_f32 v[146:147], v[146:147], v[134:135] op_sel_hi:[1,0]
	v_pk_mul_f32 v[144:145], v[144:145], v[134:135] op_sel_hi:[1,0]
	v_pk_mul_f32 v[142:143], v[142:143], v[134:135] op_sel_hi:[1,0]
	v_pk_mul_f32 v[140:141], v[140:141], v[134:135] op_sel_hi:[1,0]
	v_pk_mul_f32 v[130:131], v[130:131], v[134:135] op_sel_hi:[1,0]
	v_pk_mul_f32 v[128:129], v[128:129], v[134:135] op_sel_hi:[1,0]
	v_pk_mul_f32 v[126:127], v[126:127], v[134:135] op_sel_hi:[1,0]
	v_pk_mul_f32 v[124:125], v[124:125], v[134:135] op_sel_hi:[1,0]
	s_waitcnt vmcnt(1)
	v_pk_mul_f32 v[140:141], v[118:119], v[140:141]
	s_waitcnt vmcnt(0)
	v_pk_mul_f32 v[144:145], v[154:155], v[144:145]
	v_pk_mul_f32 v[146:147], v[152:153], v[146:147]
	v_pk_mul_f32 v[118:119], v[116:117], v[142:143]
	v_cvt_pk_bf16_f32 v116, v146, v147
	v_cvt_pk_bf16_f32 v117, v144, v145
	v_cvt_pk_bf16_f32 v118, v118, v119
	v_cvt_pk_bf16_f32 v119, v140, v141
	global_store_dwordx4 v[148:149], v[116:119], off
	global_load_dwordx4 v[116:119], v3, s[26:27] offset:144
	s_nop 0
	global_load_dwordx4 v[140:143], v3, s[26:27] offset:128
	s_waitcnt vmcnt(1)
	v_pk_mul_f32 v[124:125], v[118:119], v[124:125]
	s_waitcnt vmcnt(0)
	v_pk_mul_f32 v[128:129], v[142:143], v[128:129]
	v_pk_mul_f32 v[130:131], v[140:141], v[130:131]
	v_pk_mul_f32 v[118:119], v[116:117], v[126:127]
	v_cvt_pk_bf16_f32 v116, v130, v131
	v_cvt_pk_bf16_f32 v117, v128, v129
	v_cvt_pk_bf16_f32 v118, v118, v119
	v_cvt_pk_bf16_f32 v119, v124, v125
	global_store_dwordx4 v[148:149], v[116:119], off offset:64

.LBB0_1933:
	s_nop 0
	v_fmamk_f32 v100, v167, 0x3a800000, v231
	v_cmp_gt_f32_e32 vcc, s11, v100
	v_mul_f32_e32 v101, 0x4b800000, v100
	v_or_b32_e32 v106, 32, v138
	v_cndmask_b32_e32 v100, v100, v101, vcc
	v_rsq_f32_e32 v100, v100
	s_mov_b64 s[0:1], -1
	v_mul_f32_e32 v101, 0x45800000, v100
	v_cndmask_b32_e32 v104, v100, v101, vcc
	s_and_b64 vcc, exec, s[16:17]
	s_cbranch_vccnz .LBB0_1935
	v_ashrrev_i32_e32 v107, 31, v106
	v_lshlrev_b64 v[100:101], 9, v[106:107]
	v_lshl_add_u64 v[100:101], s[28:29], 0, v[100:101]
	s_lshl_b32 s68, s14, 1
	v_pk_mul_f32 v[122:123], v[98:99], v[104:105] op_sel_hi:[1,0]
	v_pk_mul_f32 v[124:125], v[96:97], v[104:105] op_sel_hi:[1,0]
	v_lshl_add_u64 v[126:127], v[100:101], 0, s[68:69]
	v_pk_mul_f32 v[100:101], v[122:123], v[122:123]
	v_pk_mul_f32 v[102:103], v[124:125], v[124:125]
	v_pk_mul_f32 v[118:119], v[94:95], v[104:105] op_sel_hi:[1,0]
	v_pk_mov_b32 v[108:109], v[102:103], v[100:101] op_sel:[1,0]
	v_mov_b32_e32 v103, v101
	v_pk_add_f32 v[100:101], v[108:109], v[102:103]
	v_pk_mul_f32 v[120:121], v[92:93], v[104:105] op_sel_hi:[1,0]
	v_pk_add_f32 v[100:101], v[100:101], v[100:101] op_sel_hi:[0,1]
	v_pk_mul_f32 v[102:103], v[118:119], v[118:119]
	v_pk_mul_f32 v[108:109], v[120:121], v[120:121]
	v_pk_mul_f32 v[114:115], v[88:89], v[104:105] op_sel_hi:[1,0]
	v_pk_mov_b32 v[110:111], v[108:109], v[102:103] op_sel:[1,0]
	v_mov_b32_e32 v109, v103
	v_pk_mul_f32 v[112:113], v[90:91], v[104:105] op_sel_hi:[1,0]
	v_mul_f32_e32 v100, v114, v114
	v_pk_add_f32 v[102:103], v[110:111], v[108:109]
	v_pk_fma_f32 v[116:117], v[114:115], v[114:115], v[100:101] op_sel_hi:[1,1,0]
	v_mul_f32_e32 v100, v112, v112
	v_pk_add_f32 v[102:103], v[102:103], v[102:103] op_sel_hi:[0,1]
	v_pk_fma_f32 v[128:129], v[112:113], v[112:113], v[100:101] op_sel_hi:[1,1,0]
	v_pk_mul_f32 v[108:109], v[86:87], v[104:105] op_sel_hi:[1,0]
	v_pk_mul_f32 v[110:111], v[84:85], v[104:105] op_sel_hi:[1,0]
	v_mul_f32_e32 v100, v108, v108
	v_mul_f32_e32 v116, v110, v110
	v_mul_f32_e32 v128, v111, v111
	v_mul_f32_e32 v102, v109, v109
	v_pk_add_f32 v[116:117], v[116:117], v[128:129]
	v_pk_add_f32 v[100:101], v[100:101], v[102:103]
	v_and_b32_e32 v102, 64, v236
	v_pk_add_f32 v[100:101], v[116:117], v[100:101]
	v_add_u32_e32 v102, 64, v102
	v_add_f32_e32 v100, v100, v101
	v_mov_b32_e32 v101, v100
	s_nop 1
	v_permlane16_swap_b32 v101, v100
	v_mov_b32_e32 v137, v2
	v_lshl_add_u64 v[126:127], v[126:127], 0, v[136:137]
	s_mov_b64 s[0:1], 0
	s_waitcnt lgkmcnt(0)
	v_add_f32_e32 v100, v100, v101
	v_xor_b32_e32 v101, 32, v236
	v_cmp_lt_i32_e32 vcc, v101, v102
	s_nop 1
	v_cndmask_b32_e32 v101, v236, v101, vcc
	v_lshlrev_b32_e32 v101, 2, v101
	v_mov_b32_e32 v101, v100
	s_nop 1
	v_permlane32_swap_b32 v101, v100
	s_waitcnt lgkmcnt(0)
	v_add_f32_e32 v100, v100, v101
	v_fmamk_f32 v100, v100, 0x3c800000, v231
	v_cmp_gt_f32_e32 vcc, s11, v100
	v_mul_f32_e32 v101, 0x4b800000, v100
	s_nop 0
	v_cndmask_b32_e32 v100, v100, v101, vcc
	v_rsq_f32_e32 v100, v100
	s_nop 0
	v_mul_f32_e32 v101, 0x45800000, v100
	v_cndmask_b32_e32 v100, v100, v101, vcc
	v_mul_f32_e32 v116, 0x3e38aa3b, v100
	global_load_dwordx4 v[100:103], v3, s[26:27] offset:16
	global_load_dwordx4 v[128:131], v3, s[26:27]
	v_pk_mul_f32 v[124:125], v[124:125], v[116:117] op_sel_hi:[1,0]
	v_pk_mul_f32 v[122:123], v[122:123], v[116:117] op_sel_hi:[1,0]
	v_pk_mul_f32 v[120:121], v[120:121], v[116:117] op_sel_hi:[1,0]
	v_pk_mul_f32 v[118:119], v[118:119], v[116:117] op_sel_hi:[1,0]
	v_pk_mul_f32 v[114:115], v[114:115], v[116:117] op_sel_hi:[1,0]
	v_pk_mul_f32 v[112:113], v[112:113], v[116:117] op_sel_hi:[1,0]
	v_pk_mul_f32 v[110:111], v[110:111], v[116:117] op_sel_hi:[1,0]
	v_pk_mul_f32 v[108:109], v[108:109], v[116:117] op_sel_hi:[1,0]
	s_waitcnt vmcnt(1)
	v_pk_mul_f32 v[118:119], v[102:103], v[118:119]
	s_waitcnt vmcnt(0)
	v_pk_mul_f32 v[122:123], v[130:131], v[122:123]
	v_pk_mul_f32 v[124:125], v[128:129], v[124:125]
	v_pk_mul_f32 v[102:103], v[100:101], v[120:121]
	v_cvt_pk_bf16_f32 v100, v124, v125
	v_cvt_pk_bf16_f32 v101, v122, v123
	v_cvt_pk_bf16_f32 v102, v102, v103
	v_cvt_pk_bf16_f32 v103, v118, v119
	global_store_dwordx4 v[126:127], v[100:103], off
	global_load_dwordx4 v[100:103], v3, s[26:27] offset:144
	s_nop 0
	global_load_dwordx4 v[118:121], v3, s[26:27] offset:128
	s_waitcnt vmcnt(1)
	v_pk_mul_f32 v[108:109], v[102:103], v[108:109]
	s_waitcnt vmcnt(0)
	v_pk_mul_f32 v[112:113], v[120:121], v[112:113]
	v_pk_mul_f32 v[114:115], v[118:119], v[114:115]
	v_pk_mul_f32 v[102:103], v[100:101], v[110:111]
	v_cvt_pk_bf16_f32 v100, v114, v115
	v_cvt_pk_bf16_f32 v101, v112, v113
	v_cvt_pk_bf16_f32 v102, v102, v103
	v_cvt_pk_bf16_f32 v103, v108, v109
	global_store_dwordx4 v[126:127], v[100:103], off offset:64

.LBB0_1943:
	s_nop 0
	v_fmamk_f32 v84, v166, 0x3a800000, v231
	v_cmp_gt_f32_e32 vcc, s11, v84
	v_mul_f32_e32 v85, 0x4b800000, v84
	s_add_u32 s0, s30, s36
	v_cndmask_b32_e32 v84, v84, v85, vcc
	v_rsq_f32_e32 v84, v84
	s_addc_u32 s1, s31, s37
	s_add_u32 s30, s0, 0x5348000
	s_addc_u32 s31, s1, 0
	v_mul_f32_e32 v85, 0x45800000, v84
	v_cndmask_b32_e32 v88, v84, v85, vcc
	v_or_b32_e32 v90, 48, v138
	s_mov_b64 s[0:1], -1
	s_and_b64 vcc, exec, s[16:17]
	s_cbranch_vccnz .LBB0_1945
	v_ashrrev_i32_e32 v91, 31, v90
	v_lshlrev_b64 v[84:85], 9, v[90:91]
	v_lshl_add_u64 v[84:85], s[28:29], 0, v[84:85]
	s_lshl_b32 s68, s14, 1
	v_pk_mul_f32 v[106:107], v[82:83], v[88:89] op_sel_hi:[1,0]
	v_pk_mul_f32 v[108:109], v[80:81], v[88:89] op_sel_hi:[1,0]
	v_lshl_add_u64 v[110:111], v[84:85], 0, s[68:69]
	v_pk_mul_f32 v[84:85], v[106:107], v[106:107]
	v_pk_mul_f32 v[86:87], v[108:109], v[108:109]
	v_pk_mul_f32 v[102:103], v[78:79], v[88:89] op_sel_hi:[1,0]
	v_pk_mov_b32 v[92:93], v[86:87], v[84:85] op_sel:[1,0]
	v_mov_b32_e32 v87, v85
	v_pk_add_f32 v[84:85], v[92:93], v[86:87]
	v_pk_mul_f32 v[104:105], v[76:77], v[88:89] op_sel_hi:[1,0]
	v_pk_add_f32 v[84:85], v[84:85], v[84:85] op_sel_hi:[0,1]
	v_pk_mul_f32 v[86:87], v[102:103], v[102:103]
	v_pk_mul_f32 v[92:93], v[104:105], v[104:105]
	v_pk_mul_f32 v[98:99], v[72:73], v[88:89] op_sel_hi:[1,0]
	v_pk_mov_b32 v[94:95], v[92:93], v[86:87] op_sel:[1,0]
	v_mov_b32_e32 v93, v87
	v_pk_mul_f32 v[96:97], v[74:75], v[88:89] op_sel_hi:[1,0]
	v_mul_f32_e32 v84, v98, v98
	v_pk_add_f32 v[86:87], v[94:95], v[92:93]
	v_pk_fma_f32 v[100:101], v[98:99], v[98:99], v[84:85] op_sel_hi:[1,1,0]
	v_mul_f32_e32 v84, v96, v96
	v_pk_add_f32 v[86:87], v[86:87], v[86:87] op_sel_hi:[0,1]
	v_pk_fma_f32 v[112:113], v[96:97], v[96:97], v[84:85] op_sel_hi:[1,1,0]
	v_pk_mul_f32 v[92:93], v[70:71], v[88:89] op_sel_hi:[1,0]
	v_pk_mul_f32 v[94:95], v[68:69], v[88:89] op_sel_hi:[1,0]
	v_mul_f32_e32 v84, v92, v92
	v_mul_f32_e32 v100, v94, v94
	v_mul_f32_e32 v112, v95, v95
	v_mul_f32_e32 v86, v93, v93
	v_pk_add_f32 v[100:101], v[100:101], v[112:113]
	v_pk_add_f32 v[84:85], v[84:85], v[86:87]
	v_and_b32_e32 v86, 64, v236
	v_pk_add_f32 v[84:85], v[100:101], v[84:85]
	v_add_u32_e32 v86, 64, v86
	v_add_f32_e32 v84, v84, v85
	v_mov_b32_e32 v85, v84
	s_nop 1
	v_permlane16_swap_b32 v85, v84
	v_mov_b32_e32 v137, v2
	v_lshl_add_u64 v[110:111], v[110:111], 0, v[136:137]
	s_mov_b64 s[0:1], 0
	s_waitcnt lgkmcnt(0)
	v_add_f32_e32 v84, v84, v85
	v_xor_b32_e32 v85, 32, v236
	v_cmp_lt_i32_e32 vcc, v85, v86
	s_nop 1
	v_cndmask_b32_e32 v85, v236, v85, vcc
	v_lshlrev_b32_e32 v85, 2, v85
	v_mov_b32_e32 v85, v84
	s_nop 1
	v_permlane32_swap_b32 v85, v84
	s_waitcnt lgkmcnt(0)
	v_add_f32_e32 v84, v84, v85
	v_fmamk_f32 v84, v84, 0x3c800000, v231
	v_cmp_gt_f32_e32 vcc, s11, v84
	v_mul_f32_e32 v85, 0x4b800000, v84
	s_nop 0
	v_cndmask_b32_e32 v84, v84, v85, vcc
	v_rsq_f32_e32 v84, v84
	s_nop 0
	v_mul_f32_e32 v85, 0x45800000, v84
	v_cndmask_b32_e32 v84, v84, v85, vcc
	v_mul_f32_e32 v100, 0x3e38aa3b, v84
	global_load_dwordx4 v[84:87], v3, s[26:27] offset:16
	global_load_dwordx4 v[112:115], v3, s[26:27]
	v_pk_mul_f32 v[108:109], v[108:109], v[100:101] op_sel_hi:[1,0]
	v_pk_mul_f32 v[106:107], v[106:107], v[100:101] op_sel_hi:[1,0]
	v_pk_mul_f32 v[104:105], v[104:105], v[100:101] op_sel_hi:[1,0]
	v_pk_mul_f32 v[102:103], v[102:103], v[100:101] op_sel_hi:[1,0]
	v_pk_mul_f32 v[98:99], v[98:99], v[100:101] op_sel_hi:[1,0]
	v_pk_mul_f32 v[96:97], v[96:97], v[100:101] op_sel_hi:[1,0]
	v_pk_mul_f32 v[94:95], v[94:95], v[100:101] op_sel_hi:[1,0]
	v_pk_mul_f32 v[92:93], v[92:93], v[100:101] op_sel_hi:[1,0]
	s_waitcnt vmcnt(1)
	v_pk_mul_f32 v[102:103], v[86:87], v[102:103]
	s_waitcnt vmcnt(0)
	v_pk_mul_f32 v[106:107], v[114:115], v[106:107]
	v_pk_mul_f32 v[108:109], v[112:113], v[108:109]
	v_pk_mul_f32 v[86:87], v[84:85], v[104:105]
	v_cvt_pk_bf16_f32 v84, v108, v109
	v_cvt_pk_bf16_f32 v85, v106, v107
	v_cvt_pk_bf16_f32 v86, v86, v87
	v_cvt_pk_bf16_f32 v87, v102, v103
	global_store_dwordx4 v[110:111], v[84:87], off
	global_load_dwordx4 v[84:87], v3, s[26:27] offset:144
	s_nop 0
	global_load_dwordx4 v[102:105], v3, s[26:27] offset:128
	s_waitcnt vmcnt(1)
	v_pk_mul_f32 v[92:93], v[86:87], v[92:93]
	s_waitcnt vmcnt(0)
	v_pk_mul_f32 v[96:97], v[104:105], v[96:97]
	v_pk_mul_f32 v[98:99], v[102:103], v[98:99]
	v_pk_mul_f32 v[86:87], v[84:85], v[94:95]
	v_cvt_pk_bf16_f32 v84, v98, v99
	v_cvt_pk_bf16_f32 v85, v96, v97
	v_cvt_pk_bf16_f32 v86, v86, v87
	v_cvt_pk_bf16_f32 v87, v92, v93
	global_store_dwordx4 v[110:111], v[84:87], off offset:64

.LBB0_1957:
	s_nop 0
	v_fmamk_f32 v68, v165, 0x3a800000, v231
	v_cmp_gt_f32_e32 vcc, s11, v68
	v_mul_f32_e32 v69, 0x4b800000, v68
	s_addk_i32 s15, 0x4080
	v_cndmask_b32_e32 v68, v68, v69, vcc
	v_rsq_f32_e32 v68, v68
	v_or_b32_e32 v72, s15, v164
	s_mov_b64 s[0:1], -1
	v_mul_f32_e32 v69, 0x45800000, v68
	v_cndmask_b32_e32 v74, v68, v69, vcc
	s_and_b64 vcc, exec, s[16:17]
	s_cbranch_vccnz .LBB0_1959
	v_ashrrev_i32_e32 v73, 31, v72
	v_lshlrev_b64 v[68:69], 9, v[72:73]
	v_lshl_add_u64 v[68:69], s[28:29], 0, v[68:69]
	s_lshl_b32 s68, s14, 1
	v_pk_mul_f32 v[90:91], v[66:67], v[74:75] op_sel_hi:[1,0]
	v_pk_mul_f32 v[92:93], v[64:65], v[74:75] op_sel_hi:[1,0]
	v_lshl_add_u64 v[94:95], v[68:69], 0, s[68:69]
	v_pk_mul_f32 v[68:69], v[90:91], v[90:91]
	v_pk_mul_f32 v[70:71], v[92:93], v[92:93]
	v_pk_mul_f32 v[86:87], v[62:63], v[74:75] op_sel_hi:[1,0]
	v_pk_mov_b32 v[76:77], v[70:71], v[68:69] op_sel:[1,0]
	v_mov_b32_e32 v71, v69
	v_pk_add_f32 v[68:69], v[76:77], v[70:71]
	v_pk_mul_f32 v[88:89], v[60:61], v[74:75] op_sel_hi:[1,0]
	v_pk_add_f32 v[68:69], v[68:69], v[68:69] op_sel_hi:[0,1]
	v_pk_mul_f32 v[70:71], v[86:87], v[86:87]
	v_pk_mul_f32 v[76:77], v[88:89], v[88:89]
	v_pk_mul_f32 v[82:83], v[56:57], v[74:75] op_sel_hi:[1,0]
	v_pk_mov_b32 v[78:79], v[76:77], v[70:71] op_sel:[1,0]
	v_mov_b32_e32 v77, v71
	v_pk_mul_f32 v[80:81], v[58:59], v[74:75] op_sel_hi:[1,0]
	v_mul_f32_e32 v68, v82, v82
	v_pk_add_f32 v[70:71], v[78:79], v[76:77]
	v_pk_fma_f32 v[84:85], v[82:83], v[82:83], v[68:69] op_sel_hi:[1,1,0]
	v_mul_f32_e32 v68, v80, v80
	v_pk_add_f32 v[70:71], v[70:71], v[70:71] op_sel_hi:[0,1]
	v_pk_fma_f32 v[96:97], v[80:81], v[80:81], v[68:69] op_sel_hi:[1,1,0]
	v_pk_mul_f32 v[76:77], v[54:55], v[74:75] op_sel_hi:[1,0]
	v_pk_mul_f32 v[78:79], v[52:53], v[74:75] op_sel_hi:[1,0]
	v_mul_f32_e32 v68, v76, v76
	v_mul_f32_e32 v84, v78, v78
	v_mul_f32_e32 v96, v79, v79
	v_mul_f32_e32 v70, v77, v77
	v_pk_add_f32 v[84:85], v[84:85], v[96:97]
	v_pk_add_f32 v[68:69], v[68:69], v[70:71]
	v_and_b32_e32 v70, 64, v236
	v_pk_add_f32 v[68:69], v[84:85], v[68:69]
	v_add_u32_e32 v70, 64, v70
	v_add_f32_e32 v68, v68, v69
	v_mov_b32_e32 v69, v68
	s_nop 1
	v_permlane16_swap_b32 v69, v68
	v_mov_b32_e32 v137, v2
	v_lshl_add_u64 v[94:95], v[94:95], 0, v[136:137]
	s_mov_b64 s[0:1], 0
	s_waitcnt lgkmcnt(0)
	v_add_f32_e32 v68, v68, v69
	v_xor_b32_e32 v69, 32, v236
	v_cmp_lt_i32_e32 vcc, v69, v70
	s_nop 1
	v_cndmask_b32_e32 v69, v236, v69, vcc
	v_lshlrev_b32_e32 v69, 2, v69
	v_mov_b32_e32 v69, v68
	s_nop 1
	v_permlane32_swap_b32 v69, v68
	s_waitcnt lgkmcnt(0)
	v_add_f32_e32 v68, v68, v69
	v_fmamk_f32 v68, v68, 0x3c800000, v231
	v_cmp_gt_f32_e32 vcc, s11, v68
	v_mul_f32_e32 v69, 0x4b800000, v68
	s_nop 0
	v_cndmask_b32_e32 v68, v68, v69, vcc
	v_rsq_f32_e32 v68, v68
	s_nop 0
	v_mul_f32_e32 v69, 0x45800000, v68
	v_cndmask_b32_e32 v68, v68, v69, vcc
	v_mul_f32_e32 v84, 0x3e38aa3b, v68
	global_load_dwordx4 v[68:71], v3, s[26:27] offset:16
	global_load_dwordx4 v[96:99], v3, s[26:27]
	v_pk_mul_f32 v[92:93], v[92:93], v[84:85] op_sel_hi:[1,0]
	v_pk_mul_f32 v[90:91], v[90:91], v[84:85] op_sel_hi:[1,0]
	v_pk_mul_f32 v[88:89], v[88:89], v[84:85] op_sel_hi:[1,0]
	v_pk_mul_f32 v[86:87], v[86:87], v[84:85] op_sel_hi:[1,0]
	v_pk_mul_f32 v[82:83], v[82:83], v[84:85] op_sel_hi:[1,0]
	v_pk_mul_f32 v[80:81], v[80:81], v[84:85] op_sel_hi:[1,0]
	v_pk_mul_f32 v[78:79], v[78:79], v[84:85] op_sel_hi:[1,0]
	v_pk_mul_f32 v[76:77], v[76:77], v[84:85] op_sel_hi:[1,0]
	s_waitcnt vmcnt(1)
	v_pk_mul_f32 v[86:87], v[70:71], v[86:87]
	s_waitcnt vmcnt(0)
	v_pk_mul_f32 v[90:91], v[98:99], v[90:91]
	v_pk_mul_f32 v[92:93], v[96:97], v[92:93]
	v_pk_mul_f32 v[70:71], v[68:69], v[88:89]
	v_cvt_pk_bf16_f32 v68, v92, v93
	v_cvt_pk_bf16_f32 v69, v90, v91
	v_cvt_pk_bf16_f32 v70, v70, v71
	v_cvt_pk_bf16_f32 v71, v86, v87
	global_store_dwordx4 v[94:95], v[68:71], off
	global_load_dwordx4 v[68:71], v3, s[26:27] offset:144
	s_nop 0
	global_load_dwordx4 v[86:89], v3, s[26:27] offset:128
	s_waitcnt vmcnt(1)
	v_pk_mul_f32 v[76:77], v[70:71], v[76:77]
	s_waitcnt vmcnt(0)
	v_pk_mul_f32 v[80:81], v[88:89], v[80:81]
	v_pk_mul_f32 v[82:83], v[86:87], v[82:83]
	v_pk_mul_f32 v[70:71], v[68:69], v[78:79]
	v_cvt_pk_bf16_f32 v68, v82, v83
	v_cvt_pk_bf16_f32 v69, v80, v81
	v_cvt_pk_bf16_f32 v70, v70, v71
	v_cvt_pk_bf16_f32 v71, v76, v77
	global_store_dwordx4 v[94:95], v[68:71], off offset:64

.LBB0_1967:
	s_nop 0
	v_fmamk_f32 v52, v163, 0x3a800000, v231
	v_cmp_gt_f32_e32 vcc, s11, v52
	v_mul_f32_e32 v53, 0x4b800000, v52
	v_or_b32_e32 v58, 16, v72
	v_cndmask_b32_e32 v52, v52, v53, vcc
	v_rsq_f32_e32 v52, v52
	s_mov_b64 s[0:1], -1
	v_mul_f32_e32 v53, 0x45800000, v52
	v_cndmask_b32_e32 v56, v52, v53, vcc
	s_and_b64 vcc, exec, s[16:17]
	s_cbranch_vccnz .LBB0_1969
	v_ashrrev_i32_e32 v59, 31, v58
	v_lshlrev_b64 v[52:53], 9, v[58:59]
	v_lshl_add_u64 v[52:53], s[28:29], 0, v[52:53]
	s_lshl_b32 s68, s14, 1
	v_pk_mul_f32 v[76:77], v[50:51], v[56:57] op_sel_hi:[1,0]
	v_pk_mul_f32 v[78:79], v[48:49], v[56:57] op_sel_hi:[1,0]
	v_lshl_add_u64 v[80:81], v[52:53], 0, s[68:69]
	v_pk_mul_f32 v[52:53], v[76:77], v[76:77]
	v_pk_mul_f32 v[54:55], v[78:79], v[78:79]
	v_pk_mul_f32 v[70:71], v[46:47], v[56:57] op_sel_hi:[1,0]
	v_pk_mov_b32 v[60:61], v[54:55], v[52:53] op_sel:[1,0]
	v_mov_b32_e32 v55, v53
	v_pk_add_f32 v[52:53], v[60:61], v[54:55]
	v_pk_mul_f32 v[74:75], v[44:45], v[56:57] op_sel_hi:[1,0]
	v_pk_add_f32 v[52:53], v[52:53], v[52:53] op_sel_hi:[0,1]
	v_pk_mul_f32 v[54:55], v[70:71], v[70:71]
	v_pk_mul_f32 v[60:61], v[74:75], v[74:75]
	v_pk_mul_f32 v[66:67], v[40:41], v[56:57] op_sel_hi:[1,0]
	v_pk_mov_b32 v[62:63], v[60:61], v[54:55] op_sel:[1,0]
	v_mov_b32_e32 v61, v55
	v_pk_mul_f32 v[64:65], v[42:43], v[56:57] op_sel_hi:[1,0]
	v_mul_f32_e32 v52, v66, v66
	v_pk_add_f32 v[54:55], v[62:63], v[60:61]
	v_pk_fma_f32 v[68:69], v[66:67], v[66:67], v[52:53] op_sel_hi:[1,1,0]
	v_mul_f32_e32 v52, v64, v64
	v_pk_add_f32 v[54:55], v[54:55], v[54:55] op_sel_hi:[0,1]
	v_pk_fma_f32 v[82:83], v[64:65], v[64:65], v[52:53] op_sel_hi:[1,1,0]
	v_pk_mul_f32 v[60:61], v[38:39], v[56:57] op_sel_hi:[1,0]
	v_pk_mul_f32 v[62:63], v[36:37], v[56:57] op_sel_hi:[1,0]
	v_mul_f32_e32 v52, v60, v60
	v_mul_f32_e32 v68, v62, v62
	v_mul_f32_e32 v82, v63, v63
	v_mul_f32_e32 v54, v61, v61
	v_pk_add_f32 v[68:69], v[68:69], v[82:83]
	v_pk_add_f32 v[52:53], v[52:53], v[54:55]
	v_and_b32_e32 v54, 64, v236
	v_pk_add_f32 v[52:53], v[68:69], v[52:53]
	v_add_u32_e32 v54, 64, v54
	v_add_f32_e32 v52, v52, v53
	v_mov_b32_e32 v53, v52
	s_nop 1
	v_permlane16_swap_b32 v53, v52
	v_mov_b32_e32 v137, v2
	v_lshl_add_u64 v[80:81], v[80:81], 0, v[136:137]
	s_mov_b64 s[0:1], 0
	s_waitcnt lgkmcnt(0)
	v_add_f32_e32 v52, v52, v53
	v_xor_b32_e32 v53, 32, v236
	v_cmp_lt_i32_e32 vcc, v53, v54
	s_nop 1
	v_cndmask_b32_e32 v53, v236, v53, vcc
	v_lshlrev_b32_e32 v53, 2, v53
	v_mov_b32_e32 v53, v52
	s_nop 1
	v_permlane32_swap_b32 v53, v52
	s_waitcnt lgkmcnt(0)
	v_add_f32_e32 v52, v52, v53
	v_fmamk_f32 v52, v52, 0x3c800000, v231
	v_cmp_gt_f32_e32 vcc, s11, v52
	v_mul_f32_e32 v53, 0x4b800000, v52
	s_nop 0
	v_cndmask_b32_e32 v52, v52, v53, vcc
	v_rsq_f32_e32 v52, v52
	s_nop 0
	v_mul_f32_e32 v53, 0x45800000, v52
	v_cndmask_b32_e32 v52, v52, v53, vcc
	v_mul_f32_e32 v68, 0x3e38aa3b, v52
	global_load_dwordx4 v[52:55], v3, s[26:27] offset:16
	global_load_dwordx4 v[82:85], v3, s[26:27]
	v_pk_mul_f32 v[78:79], v[78:79], v[68:69] op_sel_hi:[1,0]
	v_pk_mul_f32 v[76:77], v[76:77], v[68:69] op_sel_hi:[1,0]
	v_pk_mul_f32 v[74:75], v[74:75], v[68:69] op_sel_hi:[1,0]
	v_pk_mul_f32 v[70:71], v[70:71], v[68:69] op_sel_hi:[1,0]
	v_pk_mul_f32 v[66:67], v[66:67], v[68:69] op_sel_hi:[1,0]
	v_pk_mul_f32 v[64:65], v[64:65], v[68:69] op_sel_hi:[1,0]
	v_pk_mul_f32 v[62:63], v[62:63], v[68:69] op_sel_hi:[1,0]
	v_pk_mul_f32 v[60:61], v[60:61], v[68:69] op_sel_hi:[1,0]
	s_waitcnt vmcnt(1)
	v_pk_mul_f32 v[70:71], v[54:55], v[70:71]
	s_waitcnt vmcnt(0)
	v_pk_mul_f32 v[76:77], v[84:85], v[76:77]
	v_pk_mul_f32 v[78:79], v[82:83], v[78:79]
	v_pk_mul_f32 v[54:55], v[52:53], v[74:75]
	v_cvt_pk_bf16_f32 v52, v78, v79
	v_cvt_pk_bf16_f32 v53, v76, v77
	v_cvt_pk_bf16_f32 v54, v54, v55
	v_cvt_pk_bf16_f32 v55, v70, v71
	global_store_dwordx4 v[80:81], v[52:55], off
	global_load_dwordx4 v[52:55], v3, s[26:27] offset:144
	s_nop 0
	global_load_dwordx4 v[74:77], v3, s[26:27] offset:128
	s_waitcnt vmcnt(1)
	v_pk_mul_f32 v[60:61], v[54:55], v[60:61]
	s_waitcnt vmcnt(0)
	v_pk_mul_f32 v[64:65], v[76:77], v[64:65]
	v_pk_mul_f32 v[66:67], v[74:75], v[66:67]
	v_pk_mul_f32 v[54:55], v[52:53], v[62:63]
	v_cvt_pk_bf16_f32 v52, v66, v67
	v_cvt_pk_bf16_f32 v53, v64, v65
	v_cvt_pk_bf16_f32 v54, v54, v55
	v_cvt_pk_bf16_f32 v55, v60, v61
	global_store_dwordx4 v[80:81], v[52:55], off offset:64

.LBB0_1977:
	s_nop 0
	v_fmamk_f32 v36, v162, 0x3a800000, v231
	v_cmp_gt_f32_e32 vcc, s11, v36
	v_mul_f32_e32 v37, 0x4b800000, v36
	v_or_b32_e32 v42, 32, v72
	v_cndmask_b32_e32 v36, v36, v37, vcc
	v_rsq_f32_e32 v36, v36
	s_mov_b64 s[0:1], -1
	v_mul_f32_e32 v37, 0x45800000, v36
	v_cndmask_b32_e32 v40, v36, v37, vcc
	s_and_b64 vcc, exec, s[16:17]
	s_cbranch_vccnz .LBB0_1979
	v_ashrrev_i32_e32 v43, 31, v42
	v_lshlrev_b64 v[36:37], 9, v[42:43]
	v_lshl_add_u64 v[36:37], s[28:29], 0, v[36:37]
	s_lshl_b32 s68, s14, 1
	v_pk_mul_f32 v[58:59], v[34:35], v[40:41] op_sel_hi:[1,0]
	v_pk_mul_f32 v[60:61], v[32:33], v[40:41] op_sel_hi:[1,0]
	v_lshl_add_u64 v[62:63], v[36:37], 0, s[68:69]
	v_pk_mul_f32 v[36:37], v[58:59], v[58:59]
	v_pk_mul_f32 v[38:39], v[60:61], v[60:61]
	v_pk_mul_f32 v[54:55], v[30:31], v[40:41] op_sel_hi:[1,0]
	v_pk_mov_b32 v[44:45], v[38:39], v[36:37] op_sel:[1,0]
	v_mov_b32_e32 v39, v37
	v_pk_add_f32 v[36:37], v[44:45], v[38:39]
	v_pk_mul_f32 v[56:57], v[28:29], v[40:41] op_sel_hi:[1,0]
	v_pk_add_f32 v[36:37], v[36:37], v[36:37] op_sel_hi:[0,1]
	v_pk_mul_f32 v[38:39], v[54:55], v[54:55]
	v_pk_mul_f32 v[44:45], v[56:57], v[56:57]
	v_pk_mul_f32 v[50:51], v[24:25], v[40:41] op_sel_hi:[1,0]
	v_pk_mov_b32 v[46:47], v[44:45], v[38:39] op_sel:[1,0]
	v_mov_b32_e32 v45, v39
	v_pk_mul_f32 v[48:49], v[26:27], v[40:41] op_sel_hi:[1,0]
	v_mul_f32_e32 v36, v50, v50
	v_pk_add_f32 v[38:39], v[46:47], v[44:45]
	v_pk_fma_f32 v[52:53], v[50:51], v[50:51], v[36:37] op_sel_hi:[1,1,0]
	v_mul_f32_e32 v36, v48, v48
	v_pk_add_f32 v[38:39], v[38:39], v[38:39] op_sel_hi:[0,1]
	v_pk_fma_f32 v[64:65], v[48:49], v[48:49], v[36:37] op_sel_hi:[1,1,0]
	v_pk_mul_f32 v[44:45], v[22:23], v[40:41] op_sel_hi:[1,0]
	v_pk_mul_f32 v[46:47], v[20:21], v[40:41] op_sel_hi:[1,0]
	v_mul_f32_e32 v36, v44, v44
	v_mul_f32_e32 v52, v46, v46
	v_mul_f32_e32 v64, v47, v47
	v_mul_f32_e32 v38, v45, v45
	v_pk_add_f32 v[52:53], v[52:53], v[64:65]
	v_pk_add_f32 v[36:37], v[36:37], v[38:39]
	v_and_b32_e32 v38, 64, v236
	v_pk_add_f32 v[36:37], v[52:53], v[36:37]
	v_add_u32_e32 v38, 64, v38
	v_add_f32_e32 v36, v36, v37
	v_mov_b32_e32 v37, v36
	s_nop 1
	v_permlane16_swap_b32 v37, v36
	v_mov_b32_e32 v137, v2
	v_lshl_add_u64 v[62:63], v[62:63], 0, v[136:137]
	s_mov_b64 s[0:1], 0
	s_waitcnt lgkmcnt(0)
	v_add_f32_e32 v36, v36, v37
	v_xor_b32_e32 v37, 32, v236
	v_cmp_lt_i32_e32 vcc, v37, v38
	s_nop 1
	v_cndmask_b32_e32 v37, v236, v37, vcc
	v_lshlrev_b32_e32 v37, 2, v37
	v_mov_b32_e32 v37, v36
	s_nop 1
	v_permlane32_swap_b32 v37, v36
	s_waitcnt lgkmcnt(0)
	v_add_f32_e32 v36, v36, v37
	v_fmamk_f32 v36, v36, 0x3c800000, v231
	v_cmp_gt_f32_e32 vcc, s11, v36
	v_mul_f32_e32 v37, 0x4b800000, v36
	s_nop 0
	v_cndmask_b32_e32 v36, v36, v37, vcc
	v_rsq_f32_e32 v36, v36
	s_nop 0
	v_mul_f32_e32 v37, 0x45800000, v36
	v_cndmask_b32_e32 v36, v36, v37, vcc
	v_mul_f32_e32 v52, 0x3e38aa3b, v36
	global_load_dwordx4 v[36:39], v3, s[26:27] offset:16
	global_load_dwordx4 v[64:67], v3, s[26:27]
	v_pk_mul_f32 v[60:61], v[60:61], v[52:53] op_sel_hi:[1,0]
	v_pk_mul_f32 v[58:59], v[58:59], v[52:53] op_sel_hi:[1,0]
	v_pk_mul_f32 v[56:57], v[56:57], v[52:53] op_sel_hi:[1,0]
	v_pk_mul_f32 v[54:55], v[54:55], v[52:53] op_sel_hi:[1,0]
	v_pk_mul_f32 v[50:51], v[50:51], v[52:53] op_sel_hi:[1,0]
	v_pk_mul_f32 v[48:49], v[48:49], v[52:53] op_sel_hi:[1,0]
	v_pk_mul_f32 v[46:47], v[46:47], v[52:53] op_sel_hi:[1,0]
	v_pk_mul_f32 v[44:45], v[44:45], v[52:53] op_sel_hi:[1,0]
	s_waitcnt vmcnt(1)
	v_pk_mul_f32 v[54:55], v[38:39], v[54:55]
	s_waitcnt vmcnt(0)
	v_pk_mul_f32 v[58:59], v[66:67], v[58:59]
	v_pk_mul_f32 v[60:61], v[64:65], v[60:61]
	v_pk_mul_f32 v[38:39], v[36:37], v[56:57]
	v_cvt_pk_bf16_f32 v36, v60, v61
	v_cvt_pk_bf16_f32 v37, v58, v59
	v_cvt_pk_bf16_f32 v38, v38, v39
	v_cvt_pk_bf16_f32 v39, v54, v55
	global_store_dwordx4 v[62:63], v[36:39], off
	global_load_dwordx4 v[36:39], v3, s[26:27] offset:144
	s_nop 0
	global_load_dwordx4 v[54:57], v3, s[26:27] offset:128
	s_waitcnt vmcnt(1)
	v_pk_mul_f32 v[44:45], v[38:39], v[44:45]
	s_waitcnt vmcnt(0)
	v_pk_mul_f32 v[48:49], v[56:57], v[48:49]
	v_pk_mul_f32 v[50:51], v[54:55], v[50:51]
	v_pk_mul_f32 v[38:39], v[36:37], v[46:47]
	v_cvt_pk_bf16_f32 v36, v50, v51
	v_cvt_pk_bf16_f32 v37, v48, v49
	v_cvt_pk_bf16_f32 v38, v38, v39
	v_cvt_pk_bf16_f32 v39, v44, v45
	global_store_dwordx4 v[62:63], v[36:39], off offset:64

.LBB0_1987:
	s_nop 0
	v_fmamk_f32 v20, v151, 0x3a800000, v231
	v_cmp_gt_f32_e32 vcc, s11, v20
	v_mul_f32_e32 v21, 0x4b800000, v20
	v_or_b32_e32 v26, 48, v72
	v_cndmask_b32_e32 v20, v20, v21, vcc
	v_rsq_f32_e32 v20, v20
	s_mov_b64 s[0:1], -1
	v_mul_f32_e32 v21, 0x45800000, v20
	v_cndmask_b32_e32 v24, v20, v21, vcc
	s_and_b64 vcc, exec, s[16:17]
	s_cbranch_vccnz .LBB0_1989
	v_ashrrev_i32_e32 v27, 31, v26
	v_lshlrev_b64 v[20:21], 9, v[26:27]
	v_lshl_add_u64 v[20:21], s[28:29], 0, v[20:21]
	s_lshl_b32 s68, s14, 1
	v_pk_mul_f32 v[42:43], v[18:19], v[24:25] op_sel_hi:[1,0]
	v_pk_mul_f32 v[44:45], v[16:17], v[24:25] op_sel_hi:[1,0]
	v_lshl_add_u64 v[46:47], v[20:21], 0, s[68:69]
	v_pk_mul_f32 v[20:21], v[42:43], v[42:43]
	v_pk_mul_f32 v[22:23], v[44:45], v[44:45]
	v_pk_mul_f32 v[38:39], v[14:15], v[24:25] op_sel_hi:[1,0]
	v_pk_mov_b32 v[28:29], v[22:23], v[20:21] op_sel:[1,0]
	v_mov_b32_e32 v23, v21
	v_pk_add_f32 v[20:21], v[28:29], v[22:23]
	v_pk_mul_f32 v[40:41], v[12:13], v[24:25] op_sel_hi:[1,0]
	v_pk_add_f32 v[20:21], v[20:21], v[20:21] op_sel_hi:[0,1]
	v_pk_mul_f32 v[22:23], v[38:39], v[38:39]
	v_pk_mul_f32 v[28:29], v[40:41], v[40:41]
	v_pk_mul_f32 v[34:35], v[8:9], v[24:25] op_sel_hi:[1,0]
	v_pk_mov_b32 v[30:31], v[28:29], v[22:23] op_sel:[1,0]
	v_mov_b32_e32 v29, v23
	v_pk_mul_f32 v[32:33], v[10:11], v[24:25] op_sel_hi:[1,0]
	v_mul_f32_e32 v20, v34, v34
	v_pk_add_f32 v[22:23], v[30:31], v[28:29]
	v_pk_fma_f32 v[36:37], v[34:35], v[34:35], v[20:21] op_sel_hi:[1,1,0]
	v_mul_f32_e32 v20, v32, v32
	v_pk_add_f32 v[22:23], v[22:23], v[22:23] op_sel_hi:[0,1]
	v_pk_fma_f32 v[48:49], v[32:33], v[32:33], v[20:21] op_sel_hi:[1,1,0]
	v_pk_mul_f32 v[28:29], v[6:7], v[24:25] op_sel_hi:[1,0]
	v_pk_mul_f32 v[30:31], v[4:5], v[24:25] op_sel_hi:[1,0]
	v_mul_f32_e32 v20, v28, v28
	v_mul_f32_e32 v36, v30, v30
	v_mul_f32_e32 v48, v31, v31
	v_mul_f32_e32 v22, v29, v29
	v_pk_add_f32 v[36:37], v[36:37], v[48:49]
	v_pk_add_f32 v[20:21], v[20:21], v[22:23]
	v_and_b32_e32 v22, 64, v236
	v_pk_add_f32 v[20:21], v[36:37], v[20:21]
	v_add_u32_e32 v22, 64, v22
	v_add_f32_e32 v20, v20, v21
	v_mov_b32_e32 v21, v20
	s_nop 1
	v_permlane16_swap_b32 v21, v20
	v_mov_b32_e32 v137, v2
	v_lshl_add_u64 v[46:47], v[46:47], 0, v[136:137]
	s_mov_b64 s[0:1], 0
	s_waitcnt lgkmcnt(0)
	v_add_f32_e32 v20, v20, v21
	v_xor_b32_e32 v21, 32, v236
	v_cmp_lt_i32_e32 vcc, v21, v22
	s_nop 1
	v_cndmask_b32_e32 v21, v236, v21, vcc
	v_lshlrev_b32_e32 v21, 2, v21
	v_mov_b32_e32 v21, v20
	s_nop 1
	v_permlane32_swap_b32 v21, v20
	s_waitcnt lgkmcnt(0)
	v_add_f32_e32 v20, v20, v21
	v_fmamk_f32 v20, v20, 0x3c800000, v231
	v_cmp_gt_f32_e32 vcc, s11, v20
	v_mul_f32_e32 v21, 0x4b800000, v20
	s_nop 0
	v_cndmask_b32_e32 v20, v20, v21, vcc
	v_rsq_f32_e32 v20, v20
	s_nop 0
	v_mul_f32_e32 v21, 0x45800000, v20
	v_cndmask_b32_e32 v20, v20, v21, vcc
	v_mul_f32_e32 v36, 0x3e38aa3b, v20
	global_load_dwordx4 v[20:23], v3, s[26:27] offset:16
	global_load_dwordx4 v[48:51], v3, s[26:27]
	v_pk_mul_f32 v[44:45], v[44:45], v[36:37] op_sel_hi:[1,0]
	v_pk_mul_f32 v[42:43], v[42:43], v[36:37] op_sel_hi:[1,0]
	v_pk_mul_f32 v[40:41], v[40:41], v[36:37] op_sel_hi:[1,0]
	v_pk_mul_f32 v[38:39], v[38:39], v[36:37] op_sel_hi:[1,0]
	v_pk_mul_f32 v[34:35], v[34:35], v[36:37] op_sel_hi:[1,0]
	v_pk_mul_f32 v[32:33], v[32:33], v[36:37] op_sel_hi:[1,0]
	v_pk_mul_f32 v[30:31], v[30:31], v[36:37] op_sel_hi:[1,0]
	v_pk_mul_f32 v[28:29], v[28:29], v[36:37] op_sel_hi:[1,0]
	s_waitcnt vmcnt(1)
	v_pk_mul_f32 v[38:39], v[22:23], v[38:39]
	s_waitcnt vmcnt(0)
	v_pk_mul_f32 v[42:43], v[50:51], v[42:43]
	v_pk_mul_f32 v[44:45], v[48:49], v[44:45]
	v_pk_mul_f32 v[22:23], v[20:21], v[40:41]
	v_cvt_pk_bf16_f32 v20, v44, v45
	v_cvt_pk_bf16_f32 v21, v42, v43
	v_cvt_pk_bf16_f32 v22, v22, v23
	v_cvt_pk_bf16_f32 v23, v38, v39
	global_store_dwordx4 v[46:47], v[20:23], off
	global_load_dwordx4 v[20:23], v3, s[26:27] offset:144
	s_nop 0
	global_load_dwordx4 v[38:41], v3, s[26:27] offset:128
	s_waitcnt vmcnt(1)
	v_pk_mul_f32 v[28:29], v[22:23], v[28:29]
	s_waitcnt vmcnt(0)
	v_pk_mul_f32 v[32:33], v[40:41], v[32:33]
	v_pk_mul_f32 v[34:35], v[38:39], v[34:35]
	v_pk_mul_f32 v[22:23], v[20:21], v[30:31]
	v_cvt_pk_bf16_f32 v20, v34, v35
	v_cvt_pk_bf16_f32 v21, v32, v33
	v_cvt_pk_bf16_f32 v22, v22, v23
	v_cvt_pk_bf16_f32 v23, v28, v29
	global_store_dwordx4 v[46:47], v[20:23], off offset:64
